# conv-input loads de-serialised (one wait per chain instead of one per 2-byte load) in gdn1, lru and gdnfin items
# speedup vs baseline: 1.0360x; 1.0281x over previous
.LBB0_97:
	s_or_b64 exec, exec, s[12:13]
	s_add_u32 s3, s6, 0xcc27800
	s_addc_u32 s12, s7, 0
	s_lshl_b64 s[18:19], s[4:5], 14
	v_and_b32_e32 v34, 15, v20
	s_add_u32 s18, s3, s18
	v_ashrrev_i32_e32 v21, 31, v20
	v_and_b32_e32 v10, 0xffffffc0, v20
	v_lshlrev_b32_e32 v2, 2, v34
	s_addc_u32 s19, s12, s19
	v_lshlrev_b64 v[22:23], 4, v[20:21]
	v_or_b32_e32 v14, 0x200, v18
	v_add3_u32 v30, 0, v10, v2
	v_lshl_add_u64 v[2:3], s[18:19], 0, v[22:23]
	v_add_u32_e32 v15, 0x100, v10
	s_waitcnt lgkmcnt(0)
	s_barrier
	global_load_dwordx4 v[6:9], v[2:3], off
	v_add_u32_e32 v2, v14, v10
	v_or_b32_e32 v10, v15, v18
	v_ashrrev_i32_e32 v11, 31, v10
	v_lshlrev_b64 v[26:27], 4, v[10:11]
	v_lshl_add_u64 v[10:11], s[18:19], 0, v[26:27]
	global_load_dwordx4 v[10:13], v[10:11], off
	v_ashrrev_i32_e32 v3, 31, v2
	v_lshlrev_b64 v[24:25], 4, v[2:3]
	v_lshl_add_u64 v[2:3], s[18:19], 0, v[24:25]
	global_load_dwordx4 v[2:5], v[2:3], off
	v_add_u32_e32 v14, v15, v14
	v_ashrrev_i32_e32 v15, 31, v14
	v_lshlrev_b64 v[28:29], 4, v[14:15]
	v_lshl_add_u64 v[14:15], s[18:19], 0, v[28:29]
	global_load_dwordx4 v[14:17], v[14:15], off
	v_lshrrev_b32_e32 v33, 4, v18
	v_lshl_add_u32 v32, v33, 3, 0
	s_movk_i32 s17, 0x90
	v_mad_u32_u24 v21, v34, s17, v32
	ds_read2_b64 v[34:37], v21 offset1:4
	ds_read2_b64 v[38:41], v21 offset0:8 offset1:12
	v_and_b32_e32 v0, 48, v20
	v_add_u32_e32 v31, 0, v0
	v_add_u32_e32 v43, 0x2000, v21
	s_movk_i32 s5, 0x410
	v_lshlrev_b32_e32 v0, 2, v33
	v_mad_u32_u24 v33, v33, s5, v30
	v_add_u32_e32 v45, 0x2800, v21
	s_lshl_b64 s[10:11], s[10:11], 14
	s_add_u32 s10, s3, s10
	s_addc_u32 s11, s12, s11
	v_bitop3_b32 v42, v20, 63, 15 bitop3:0x6c
	v_xor_b32_e32 v44, 62, v0
	s_and_b32 s3, s15, 0xc0
	s_lshl_b32 s3, s3, 1
	s_movk_i32 s5, 0x5000
	s_waitcnt vmcnt(3) lgkmcnt(1)
	v_mfma_f32_16x16x32_bf16 v[34:37], v[34:37], v[6:9], 0
	s_waitcnt vmcnt(2) lgkmcnt(0)
	v_mfma_f32_16x16x32_bf16 v[34:37], v[38:41], v[10:13], v[34:37]
	ds_read_b128 v[38:41], v31 offset:44288
	s_waitcnt lgkmcnt(0)
	s_nop 5
	v_pk_mul_f32 v[36:37], v[36:37], v[40:41]
	v_pk_mul_f32 v[34:35], v[34:35], v[38:39]
	ds_read2_b64 v[38:41], v43 offset0:128 offset1:132
	s_waitcnt vmcnt(1) lgkmcnt(0)
	v_mfma_f32_16x16x32_bf16 v[34:37], v[38:41], v[2:5], v[34:37]
	ds_read2_b64 v[38:41], v43 offset0:136 offset1:140
	v_xor_b32_e32 v43, 63, v0
	s_waitcnt vmcnt(0) lgkmcnt(0)
	v_mfma_f32_16x16x32_bf16 v[34:37], v[38:41], v[14:17], v[34:37]
	v_add_u32_e32 v38, 0x6c00, v33
	s_nop 6
	ds_write2_b32 v38, v34, v35 offset1:65
	ds_write2_b32 v38, v36, v37 offset0:130 offset1:195
	v_add_u32_e32 v38, 0x800, v21
	ds_read2_b64 v[34:37], v38 offset0:32 offset1:36
	ds_read2_b64 v[38:41], v38 offset0:40 offset1:44
	s_waitcnt lgkmcnt(1)
	v_mfma_f32_16x16x32_bf16 v[34:37], v[34:37], v[6:9], 0
	s_waitcnt lgkmcnt(0)
	v_mfma_f32_16x16x32_bf16 v[34:37], v[38:41], v[10:13], v[34:37]
	ds_read_b128 v[38:41], v31 offset:44352
	s_waitcnt lgkmcnt(0)
	s_nop 5
	v_pk_mul_f32 v[36:37], v[36:37], v[40:41]
	v_pk_mul_f32 v[34:35], v[34:35], v[38:39]
	ds_read2_b64 v[38:41], v45 offset0:160 offset1:164
	s_waitcnt lgkmcnt(0)
	v_mfma_f32_16x16x32_bf16 v[34:37], v[38:41], v[2:5], v[34:37]
	ds_read2_b64 v[38:41], v45 offset0:168 offset1:172
	v_add_u32_e32 v45, 0x3000, v21
	s_waitcnt lgkmcnt(0)
	v_mfma_f32_16x16x32_bf16 v[34:37], v[38:41], v[14:17], v[34:37]
	v_add_u32_e32 v38, 0x7c00, v33
	s_nop 6
	ds_write2_b32 v38, v34, v35 offset0:16 offset1:81
	ds_write2_b32 v38, v36, v37 offset0:146 offset1:211
	v_add_u32_e32 v38, 0x1000, v21
	ds_read2_b64 v[34:37], v38 offset0:64 offset1:68
	ds_read2_b64 v[38:41], v38 offset0:72 offset1:76
	s_waitcnt lgkmcnt(1)
	v_mfma_f32_16x16x32_bf16 v[34:37], v[34:37], v[6:9], 0
	s_waitcnt lgkmcnt(0)
	v_mfma_f32_16x16x32_bf16 v[34:37], v[38:41], v[10:13], v[34:37]
	ds_read_b128 v[38:41], v31 offset:44416
	s_waitcnt lgkmcnt(0)
	s_nop 5
	v_pk_mul_f32 v[36:37], v[36:37], v[40:41]
	v_pk_mul_f32 v[34:35], v[34:35], v[38:39]
	ds_read2_b64 v[38:41], v45 offset0:192 offset1:196
	s_waitcnt lgkmcnt(0)
	v_mfma_f32_16x16x32_bf16 v[34:37], v[38:41], v[2:5], v[34:37]
	ds_read2_b64 v[38:41], v45 offset0:200 offset1:204
	s_waitcnt lgkmcnt(0)
	v_mfma_f32_16x16x32_bf16 v[34:37], v[38:41], v[14:17], v[34:37]
	v_add_u32_e32 v38, 0x8c00, v33
	s_nop 6
	ds_write2_b32 v38, v34, v35 offset0:32 offset1:97
	ds_write2_b32 v38, v36, v37 offset0:162 offset1:227
	v_add_u32_e32 v38, 0x1800, v21
	ds_read2_b64 v[34:37], v38 offset0:96 offset1:100
	s_waitcnt lgkmcnt(0)
	v_mfma_f32_16x16x32_bf16 v[6:9], v[34:37], v[6:9], 0
	ds_read2_b64 v[34:37], v38 offset0:104 offset1:108
	s_waitcnt lgkmcnt(0)
	v_mfma_f32_16x16x32_bf16 v[6:9], v[34:37], v[10:13], v[6:9]
	ds_read_b128 v[10:13], v31 offset:44480
	v_add_u32_e32 v34, 0x3800, v21
	s_waitcnt lgkmcnt(0)
	s_nop 4
	v_pk_mul_f32 v[8:9], v[8:9], v[12:13]
	v_pk_mul_f32 v[6:7], v[6:7], v[10:11]
	ds_read2_b64 v[10:13], v34 offset0:224 offset1:228
	s_waitcnt lgkmcnt(0)
	v_mfma_f32_16x16x32_bf16 v[2:5], v[10:13], v[2:5], v[6:9]
	s_nop 2
	ds_read2_b64 v[6:9], v34 offset0:232 offset1:236
	s_waitcnt lgkmcnt(0)
	v_mfma_f32_16x16x32_bf16 v[2:5], v[6:9], v[14:17], v[2:5]
	v_add_u32_e32 v6, 0x9c00, v33
	s_nop 6
	ds_write2_b32 v6, v2, v3 offset0:48 offset1:113
	ds_write2_b32 v6, v4, v5 offset0:178 offset1:243
	v_lshl_add_u64 v[2:3], s[10:11], 0, v[22:23]
	s_waitcnt lgkmcnt(0)
	s_barrier
	global_load_dwordx4 v[10:13], v[2:3], off
	v_lshl_add_u64 v[6:7], s[10:11], 0, v[26:27]
	global_load_dwordx4 v[14:17], v[6:7], off
	v_lshl_add_u64 v[2:3], s[10:11], 0, v[24:25]
	global_load_dwordx4 v[2:5], v[2:3], off
	v_lshl_add_u64 v[6:7], s[10:11], 0, v[28:29]
	global_load_dwordx4 v[6:9], v[6:7], off
	v_mad_u32_u24 v26, v42, s17, v32
	ds_read2_b64 v[22:25], v26 offset1:4
	ds_read2_b64 v[26:29], v26 offset0:8 offset1:12
	v_add_u32_e32 v33, 0x4800, v21
	s_ashr_i32 s10, s16, 2
	s_ashr_i32 s11, s10, 31
	s_waitcnt vmcnt(3) lgkmcnt(1)
	v_mfma_f32_16x16x32_bf16 v[22:25], v[22:25], v[10:13], 0
	s_waitcnt vmcnt(2) lgkmcnt(0)
	v_mfma_f32_16x16x32_bf16 v[22:25], v[26:29], v[14:17], v[22:25]
	ds_read_b128 v[26:29], v31 offset:44544
	s_waitcnt lgkmcnt(0)
	s_nop 5
	v_pk_mul_f32 v[24:25], v[24:25], v[28:29]
	v_pk_mul_f32 v[22:23], v[22:23], v[26:27]
	ds_read2_b64 v[26:29], v33 offset1:4
	s_waitcnt vmcnt(1) lgkmcnt(0)
	v_mfma_f32_16x16x32_bf16 v[22:25], v[26:29], v[2:5], v[22:25]
	ds_read2_b64 v[26:29], v33 offset0:8 offset1:12
	v_add_u32_e32 v33, 0x5000, v21
	s_waitcnt vmcnt(0) lgkmcnt(0)
	v_mfma_f32_16x16x32_bf16 v[22:25], v[26:29], v[6:9], v[22:25]
	v_mad_u32_u24 v26, v43, s97, v30
	ds_read_b32 v27, v26 offset:27648
	s_waitcnt lgkmcnt(0)
	s_nop 4
	v_add_f32_e32 v22, v22, v27
	ds_write_b32 v26, v22 offset:27648
	v_mad_u32_u24 v22, v44, s97, v30
	ds_read_b32 v26, v22 offset:27648
	s_waitcnt lgkmcnt(0)
	v_add_f32_e32 v23, v23, v26
	ds_write_b32 v22, v23 offset:27648
	v_xor_b32_e32 v22, 61, v0
	v_mad_u32_u24 v22, v22, s97, v30
	ds_read_b32 v23, v22 offset:27648
	s_waitcnt lgkmcnt(0)
	v_add_f32_e32 v23, v24, v23
	ds_write_b32 v22, v23 offset:27648
	v_xor_b32_e32 v22, 60, v0
	v_mad_u32_u24 v22, v22, s97, v30
	ds_read_b32 v23, v22 offset:27648
	s_waitcnt lgkmcnt(0)
	v_add_f32_e32 v23, v25, v23
	ds_write_b32 v22, v23 offset:27648
	v_bitop3_b32 v22, v20, 47, 15 bitop3:0x6c
	v_mad_u32_u24 v26, v22, s17, v32
	ds_read2_b64 v[22:25], v26 offset1:4
	ds_read2_b64 v[26:29], v26 offset0:8 offset1:12
	s_waitcnt lgkmcnt(1)
	v_mfma_f32_16x16x32_bf16 v[22:25], v[22:25], v[10:13], 0
	s_waitcnt lgkmcnt(0)
	v_mfma_f32_16x16x32_bf16 v[22:25], v[26:29], v[14:17], v[22:25]
	ds_read_b128 v[26:29], v31 offset:44608
	s_waitcnt lgkmcnt(0)
	s_nop 5
	v_pk_mul_f32 v[24:25], v[24:25], v[28:29]
	v_pk_mul_f32 v[22:23], v[22:23], v[26:27]
	ds_read2_b64 v[26:29], v33 offset0:32 offset1:36
	s_waitcnt lgkmcnt(0)
	v_mfma_f32_16x16x32_bf16 v[22:25], v[26:29], v[2:5], v[22:25]
	ds_read2_b64 v[26:29], v33 offset0:40 offset1:44
	v_add_u32_e32 v33, 0x5800, v21
	s_waitcnt lgkmcnt(0)
	v_mfma_f32_16x16x32_bf16 v[22:25], v[26:29], v[6:9], v[22:25]
	v_xor_b32_e32 v26, 47, v0
	v_mad_u32_u24 v26, v26, s97, v30
	ds_read_b32 v27, v26 offset:27648
	s_waitcnt lgkmcnt(0)
	s_nop 3
	v_add_f32_e32 v22, v22, v27
	ds_write_b32 v26, v22 offset:27648
	v_xor_b32_e32 v22, 46, v0
	v_mad_u32_u24 v22, v22, s97, v30
	ds_read_b32 v26, v22 offset:27648
	s_waitcnt lgkmcnt(0)
	v_add_f32_e32 v23, v23, v26
	ds_write_b32 v22, v23 offset:27648
	v_xor_b32_e32 v22, 45, v0
	v_mad_u32_u24 v22, v22, s97, v30
	ds_read_b32 v23, v22 offset:27648
	s_waitcnt lgkmcnt(0)
	v_add_f32_e32 v23, v24, v23
	ds_write_b32 v22, v23 offset:27648
	v_xor_b32_e32 v22, 44, v0
	v_mad_u32_u24 v22, v22, s97, v30
	ds_read_b32 v23, v22 offset:27648
	s_waitcnt lgkmcnt(0)
	v_add_f32_e32 v23, v25, v23
	ds_write_b32 v22, v23 offset:27648
	v_bitop3_b32 v22, v20, 31, 15 bitop3:0x6c
	v_mad_u32_u24 v26, v22, s17, v32
	ds_read2_b64 v[22:25], v26 offset1:4
	ds_read2_b64 v[26:29], v26 offset0:8 offset1:12
	s_waitcnt lgkmcnt(1)
	v_mfma_f32_16x16x32_bf16 v[22:25], v[22:25], v[10:13], 0
	v_bitop3_b32 v20, v20, 15, v20 bitop3:0xc
	v_mad_u32_u24 v20, v20, s17, v32
	s_waitcnt lgkmcnt(0)
	v_mfma_f32_16x16x32_bf16 v[22:25], v[26:29], v[14:17], v[22:25]
	ds_read_b128 v[26:29], v31 offset:44672
	s_waitcnt lgkmcnt(0)
	s_nop 5
	v_pk_mul_f32 v[24:25], v[24:25], v[28:29]
	v_pk_mul_f32 v[22:23], v[22:23], v[26:27]
	ds_read2_b64 v[26:29], v33 offset0:64 offset1:68
	s_waitcnt lgkmcnt(0)
	v_mfma_f32_16x16x32_bf16 v[22:25], v[26:29], v[2:5], v[22:25]
	ds_read2_b64 v[26:29], v33 offset0:72 offset1:76
	s_waitcnt lgkmcnt(0)
	v_mfma_f32_16x16x32_bf16 v[22:25], v[26:29], v[6:9], v[22:25]
	v_xor_b32_e32 v26, 31, v0
	v_mad_u32_u24 v26, v26, s97, v30
	ds_read_b32 v27, v26 offset:27648
	s_waitcnt lgkmcnt(0)
	s_nop 3
	v_add_f32_e32 v22, v22, v27
	ds_write_b32 v26, v22 offset:27648
	v_xor_b32_e32 v22, 30, v0
	v_mad_u32_u24 v22, v22, s97, v30
	ds_read_b32 v26, v22 offset:27648
	s_waitcnt lgkmcnt(0)
	v_add_f32_e32 v23, v23, v26
	ds_write_b32 v22, v23 offset:27648
	v_xor_b32_e32 v22, 29, v0
	v_mad_u32_u24 v22, v22, s97, v30
	ds_read_b32 v23, v22 offset:27648
	s_waitcnt lgkmcnt(0)
	v_add_f32_e32 v23, v24, v23
	ds_write_b32 v22, v23 offset:27648
	v_xor_b32_e32 v22, 28, v0
	v_mad_u32_u24 v22, v22, s97, v30
	ds_read_b32 v23, v22 offset:27648
	s_waitcnt lgkmcnt(0)
	v_add_f32_e32 v23, v25, v23
	ds_write_b32 v22, v23 offset:27648
	ds_read2_b64 v[22:25], v20 offset1:4
	s_waitcnt lgkmcnt(0)
	v_mfma_f32_16x16x32_bf16 v[10:13], v[22:25], v[10:13], 0
	ds_read2_b64 v[22:25], v20 offset0:8 offset1:12
	v_add_u32_e32 v20, 0x6000, v21
	s_waitcnt lgkmcnt(0)
	v_mfma_f32_16x16x32_bf16 v[10:13], v[22:25], v[14:17], v[10:13]
	ds_read_b128 v[14:17], v31 offset:44736
	s_waitcnt lgkmcnt(0)
	s_nop 5
	v_pk_mul_f32 v[12:13], v[12:13], v[16:17]
	v_pk_mul_f32 v[10:11], v[10:11], v[14:15]
	ds_read2_b64 v[14:17], v20 offset0:96 offset1:100
	s_waitcnt lgkmcnt(0)
	v_mfma_f32_16x16x32_bf16 v[2:5], v[14:17], v[2:5], v[10:13]
	s_nop 2
	ds_read2_b64 v[10:13], v20 offset0:104 offset1:108
	s_waitcnt lgkmcnt(0)
	v_mfma_f32_16x16x32_bf16 v[2:5], v[10:13], v[6:9], v[2:5]
	v_xor_b32_e32 v6, 15, v0
	v_mad_u32_u24 v6, v6, s97, v30
	ds_read_b32 v7, v6 offset:27648
	s_waitcnt lgkmcnt(0)
	s_nop 3
	v_add_f32_e32 v2, v2, v7
	ds_write_b32 v6, v2 offset:27648
	v_xor_b32_e32 v2, 14, v0
	v_mad_u32_u24 v2, v2, s97, v30
	ds_read_b32 v6, v2 offset:27648
	s_waitcnt lgkmcnt(0)
	v_add_f32_e32 v3, v3, v6
	ds_write_b32 v2, v3 offset:27648
	v_xor_b32_e32 v2, 13, v0
	v_mad_u32_u24 v2, v2, s97, v30
	ds_read_b32 v3, v2 offset:27648
	v_xor_b32_e32 v0, 12, v0
	v_mad_u32_u24 v0, v0, s97, v30
	v_lshlrev_b32_e32 v6, 4, v19
	v_ashrrev_i32_e32 v7, 31, v6
	s_waitcnt lgkmcnt(0)
	v_add_f32_e32 v3, v4, v3
	ds_write_b32 v2, v3 offset:27648
	ds_read_b32 v2, v0 offset:27648
	s_waitcnt lgkmcnt(0)
	v_add_f32_e32 v2, v5, v2
	ds_write_b32 v0, v2 offset:27648
	s_waitcnt lgkmcnt(0)
	s_barrier
	s_load_dwordx2 s[12:13], s[0:1], 0xe0
	v_or_b32_e32 v2, s14, v18
	v_ashrrev_i32_e32 v3, 31, v2
	v_lshlrev_b32_e32 v0, 1, v18
	s_waitcnt lgkmcnt(0)
	v_lshl_add_u64 v[2:3], v[2:3], 2, s[12:13]
	s_lshl_b64 s[12:13], s[10:11], 6
	global_load_dword v16, v[2:3], off
	v_lshl_add_u64 v[2:3], s[12:13], 0, v[6:7]
	s_add_u32 s12, s6, s3
	s_addc_u32 s13, s7, 0
	v_lshl_add_u64 v[4:5], s[12:13], 0, v[0:1]
	s_mov_b64 s[12:13], 0x4b28600
	v_lshl_add_u64 v[4:5], v[4:5], 0, s[12:13]
	v_mad_u64_u32 v[4:5], s[12:13], v2, s33, v[4:5]
	v_mad_i32_i24 v5, v3, s33, v5
	global_load_ushort v2, v[4:5], off
	s_lshl_b64 s[10:11], s[10:11], 17
	s_waitcnt vmcnt(0)
	v_lshlrev_b32_e32 v10, 16, v2
	v_add_co_u32_e32 v2, vcc, s41, v4
	s_nop 1
	v_addc_co_u32_e32 v3, vcc, 0, v5, vcc
	global_load_ushort v33, v[2:3], off offset:1088
	v_add_co_u32_e32 v2, vcc, s40, v4
	s_nop 1
	v_addc_co_u32_e32 v3, vcc, 0, v5, vcc
	global_load_ushort v32, v[2:3], off offset:2176
	v_add_co_u32_e32 v2, vcc, s44, v4
	s_nop 1
	v_addc_co_u32_e32 v3, vcc, 0, v5, vcc
	global_load_ushort v31, v[2:3], off offset:3264
	v_add_co_u32_e32 v2, vcc, s5, v4
	s_movk_i32 s5, 0x7000
	s_nop 0
	v_addc_co_u32_e32 v3, vcc, 0, v5, vcc
	global_load_ushort v30, v[2:3], off offset:256
	v_add_co_u32_e32 v2, vcc, s45, v4
	s_nop 1
	v_addc_co_u32_e32 v3, vcc, 0, v5, vcc
	global_load_ushort v29, v[2:3], off offset:1344
	v_add_co_u32_e32 v2, vcc, s5, v4
	s_mov_b32 s5, 0x8000
	s_nop 0
	v_addc_co_u32_e32 v3, vcc, 0, v5, vcc
	global_load_ushort v28, v[2:3], off offset:2432
	v_add_co_u32_e32 v2, vcc, s5, v4
	s_mov_b32 s5, 0xa000
	s_nop 0
	v_addc_co_u32_e32 v3, vcc, 0, v5, vcc
	global_load_ushort v27, v[2:3], off offset:3520
	v_add_co_u32_e32 v2, vcc, s5, v4
	s_mov_b32 s5, 0xb000
	s_nop 0
	v_addc_co_u32_e32 v3, vcc, 0, v5, vcc
	global_load_ushort v26, v[2:3], off offset:512
	v_add_co_u32_e32 v2, vcc, s5, v4
	s_mov_b32 s5, 0xc000
	s_nop 0
	v_addc_co_u32_e32 v3, vcc, 0, v5, vcc
	global_load_ushort v25, v[2:3], off offset:1600
	v_add_co_u32_e32 v2, vcc, s5, v4
	s_mov_b32 s5, 0xd000
	s_nop 0
	v_addc_co_u32_e32 v3, vcc, 0, v5, vcc
	global_load_ushort v24, v[2:3], off offset:2688
	v_add_co_u32_e32 v2, vcc, s5, v4
	s_mov_b32 s5, 0xf000
	s_nop 0
	v_addc_co_u32_e32 v3, vcc, 0, v5, vcc
	global_load_ushort v23, v[2:3], off offset:3776
	v_add_co_u32_e32 v2, vcc, s5, v4
	s_mov_b32 s5, 0x10000
	s_nop 0
	v_addc_co_u32_e32 v3, vcc, 0, v5, vcc
	global_load_ushort v22, v[2:3], off offset:768
	v_add_co_u32_e32 v2, vcc, s5, v4
	s_mov_b32 s5, 0x11000
	s_nop 0
	v_addc_co_u32_e32 v3, vcc, 0, v5, vcc
	global_load_ushort v21, v[2:3], off offset:1856
	v_add_co_u32_e32 v2, vcc, s5, v4
	s_mov_b32 s5, 0x12000
	s_nop 0
	v_addc_co_u32_e32 v3, vcc, 0, v5, vcc
	global_load_ushort v20, v[2:3], off offset:2944
	s_waitcnt vmcnt(0)
	v_lshlrev_b32_e32 v33, 16, v33
	v_lshlrev_b32_e32 v32, 16, v32
	v_lshlrev_b32_e32 v31, 16, v31
	v_lshlrev_b32_e32 v30, 16, v30
	v_lshlrev_b32_e32 v29, 16, v29
	v_lshlrev_b32_e32 v28, 16, v28
	v_lshlrev_b32_e32 v27, 16, v27
	v_lshlrev_b32_e32 v26, 16, v26
	v_lshlrev_b32_e32 v25, 16, v25
	v_lshlrev_b32_e32 v24, 16, v24
	v_lshlrev_b32_e32 v23, 16, v23
	v_lshlrev_b32_e32 v22, 16, v22
	v_lshlrev_b32_e32 v21, 16, v21
	v_lshlrev_b32_e32 v20, 16, v20
	v_add_co_u32_e32 v2, vcc, s5, v4
	s_add_u32 s5, s6, s10
	s_nop 0
	v_addc_co_u32_e32 v3, vcc, 0, v5, vcc
	global_load_ushort v2, v[2:3], off offset:4032
	s_addc_u32 s7, s7, s11
	s_add_u32 s6, s5, s3
	s_addc_u32 s7, s7, 0
	v_lshl_add_u32 v4, v18, 2, 0
	s_movk_i32 s3, 0x1040
	s_mov_b32 s10, 0x3c800000
	s_add_i32 s16, s16, s42
	s_waitcnt vmcnt(0)
	v_lshlrev_b32_e32 v17, 16, v2
	v_lshl_add_u64 v[2:3], s[6:7], 0, v[0:1]
	s_mov_b64 s[6:7], 0x9c27c00
	v_lshl_add_u64 v[2:3], v[2:3], 0, s[6:7]
	v_mad_u64_u32 v[8:9], s[6:7], v19, s3, v[4:5]
	ds_read_b32 v36, v8 offset:27648
	s_waitcnt lgkmcnt(0)
	v_mul_f32_e32 v0, v36, v36
	s_nop 1
	v_mov_b32_dpp v0, v0 quad_perm:[1,0,3,2] row_mask:0xf bank_mask:0xf bound_ctrl:1
	v_fmac_f32_e32 v0, v36, v36
	s_nop 1
	v_add_f32_dpp v0, v0, v0 quad_perm:[2,3,0,1] row_mask:0xf bank_mask:0xf bound_ctrl:1
	s_nop 1
	v_add_f32_dpp v0, v0, v0 row_half_mirror row_mask:0xf bank_mask:0xf bound_ctrl:1
	s_nop 1
	v_add_f32_dpp v0, v0, v0 row_mirror row_mask:0xf bank_mask:0xf bound_ctrl:1
	s_nop 0
	v_readlane_b32 s6, v0, 0
	v_readlane_b32 s3, v0, 16
	v_readlane_b32 s7, v0, 32
	v_readlane_b32 s5, v0, 48
	v_mul_f32_e32 v0, 0xbfb8aa3b, v10
	v_exp_f32_e32 v0, v0
	v_mov_b32_e32 v8, s3
	v_mov_b32_e32 v9, s5
	v_pk_add_f32 v[18:19], s[6:7], v[8:9]
	v_add_f32_e32 v0, 1.0, v0
	v_rcp_f32_e32 v0, v0
	v_lshlrev_b64 v[8:9], 11, v[6:7]
	v_lshl_add_u64 v[12:13], v[2:3], 0, v[8:9]
	v_mov_b32_e32 v35, v18
	v_mul_f32_e32 v37, v0, v10
	v_or_b32_e32 v10, 1, v6
	v_mad_u64_u32 v[14:15], s[6:7], v10, s97, v[4:5]
	v_add_u32_e32 v0, 0x6c00, v14
	ds_read2_b32 v[8:9], v0 offset1:65
	v_ashrrev_i32_e32 v11, 31, v10
	v_lshlrev_b64 v[10:11], 11, v[10:11]
	v_lshl_add_u64 v[10:11], v[2:3], 0, v[10:11]
	s_waitcnt lgkmcnt(0)
	v_mul_f32_e32 v4, v8, v8
	s_nop 1
	v_mov_b32_dpp v4, v4 quad_perm:[1,0,3,2] row_mask:0xf bank_mask:0xf bound_ctrl:1
	v_fmac_f32_e32 v4, v8, v8
	s_nop 1
	v_add_f32_dpp v4, v4, v4 quad_perm:[2,3,0,1] row_mask:0xf bank_mask:0xf bound_ctrl:1
	s_nop 1
	v_add_f32_dpp v4, v4, v4 row_half_mirror row_mask:0xf bank_mask:0xf bound_ctrl:1
	s_nop 1
	v_add_f32_dpp v4, v4, v4 row_mirror row_mask:0xf bank_mask:0xf bound_ctrl:1
	s_nop 0
	v_readlane_b32 s3, v4, 16
	v_readlane_b32 s5, v4, 48
	v_readlane_b32 s6, v4, 0
	v_readlane_b32 s7, v4, 32
	v_mov_b32_e32 v4, s3
	v_mov_b32_e32 v5, s5
	v_pk_add_f32 v[4:5], s[6:7], v[4:5]
	s_mov_b32 s6, 0x358637bd
	v_mov_b32_e32 v34, v4
	v_mov_b32_e32 v18, v5
	v_pk_add_f32 v[18:19], v[34:35], v[18:19]
	v_mov_b64_e32 v[4:5], s[6:7]
	v_pk_fma_f32 v[18:19], v[18:19], s[10:11], v[4:5] op_sel_hi:[1,0,0]
	s_nop 0
	v_mul_f32_e32 v7, 0x4b800000, v19
	v_cmp_gt_f32_e64 s[6:7], s68, v19
	v_cmp_gt_f32_e32 vcc, s68, v18
	s_nop 0
	v_cndmask_b32_e64 v7, v19, v7, s[6:7]
	v_rsq_f32_e32 v7, v7
	s_nop 0
	v_mul_f32_e32 v15, 0x45800000, v7
	v_cndmask_b32_e64 v7, v7, v15, s[6:7]
	v_mul_f32_e32 v7, v36, v7
	v_mul_f32_e32 v7, v16, v7
	v_mul_f32_e32 v7, v37, v7
	v_cvt_pk_bf16_f32 v7, v7, s0
	global_store_short v[12:13], v7, off
	v_mul_f32_e32 v7, 0x4b800000, v18
	v_cndmask_b32_e32 v7, v18, v7, vcc
	v_rsq_f32_e32 v7, v7
	s_nop 0
	v_mul_f32_e32 v12, 0x45800000, v7
	v_cndmask_b32_e32 v7, v7, v12, vcc
	v_mul_f32_e32 v7, v8, v7
	v_mul_f32_e32 v8, 0xbfb8aa3b, v33
	v_exp_f32_e32 v8, v8
	v_mul_f32_e32 v7, v16, v7
	v_add_f32_e32 v8, 1.0, v8
	v_rcp_f32_e32 v8, v8
	s_nop 0
	v_mul_f32_e32 v8, v8, v33
	v_mul_f32_e32 v7, v8, v7
	v_cvt_pk_bf16_f32 v7, v7, s0
	global_store_short v[10:11], v7, off
	v_or_b32_e32 v10, 2, v6
	v_ashrrev_i32_e32 v11, 31, v10
	v_lshlrev_b64 v[10:11], 11, v[10:11]
	v_lshl_add_u64 v[18:19], v[2:3], 0, v[10:11]
	ds_read2_b32 v[10:11], v0 offset0:130 offset1:195
	v_mul_f32_e32 v7, v9, v9
	s_waitcnt lgkmcnt(0)
	v_mul_f32_e32 v0, v10, v10
	v_mov_b32_dpp v7, v7 quad_perm:[1,0,3,2] row_mask:0xf bank_mask:0xf bound_ctrl:1
	v_fmac_f32_e32 v7, v9, v9
	v_mov_b32_dpp v0, v0 quad_perm:[1,0,3,2] row_mask:0xf bank_mask:0xf bound_ctrl:1
	v_fmac_f32_e32 v0, v10, v10
	v_add_f32_dpp v7, v7, v7 quad_perm:[2,3,0,1] row_mask:0xf bank_mask:0xf bound_ctrl:1
	s_nop 0
	v_add_f32_dpp v0, v0, v0 quad_perm:[2,3,0,1] row_mask:0xf bank_mask:0xf bound_ctrl:1
	v_add_f32_dpp v7, v7, v7 row_half_mirror row_mask:0xf bank_mask:0xf bound_ctrl:1
	s_nop 0
	v_add_f32_dpp v0, v0, v0 row_half_mirror row_mask:0xf bank_mask:0xf bound_ctrl:1
	v_add_f32_dpp v7, v7, v7 row_mirror row_mask:0xf bank_mask:0xf bound_ctrl:1
	s_nop 0
	v_readlane_b32 s3, v7, 16
	v_readlane_b32 s5, v7, 48
	v_add_f32_dpp v0, v0, v0 row_mirror row_mask:0xf bank_mask:0xf bound_ctrl:1
	v_readlane_b32 s6, v7, 0
	v_readlane_b32 s7, v7, 32
	v_mov_b32_e32 v12, s3
	v_mov_b32_e32 v13, s5
	v_readlane_b32 s3, v0, 16
	v_readlane_b32 s5, v0, 48
	v_pk_add_f32 v[12:13], s[6:7], v[12:13]
	v_readlane_b32 s6, v0, 0
	v_readlane_b32 s7, v0, 32
	v_mov_b32_e32 v34, s3
	v_mov_b32_e32 v35, s5
	v_pk_add_f32 v[34:35], s[6:7], v[34:35]
	v_mov_b32_e32 v37, v12
	v_mov_b32_e32 v36, v34
	v_mov_b32_e32 v12, v35
	v_pk_add_f32 v[12:13], v[36:37], v[12:13]
	v_mul_f32_e32 v7, 0xbfb8aa3b, v32
	v_pk_fma_f32 v[12:13], v[12:13], s[10:11], v[4:5] op_sel_hi:[1,0,0]
	v_exp_f32_e32 v7, v7
	v_mul_f32_e32 v0, 0x4b800000, v13
	v_cmp_gt_f32_e64 s[6:7], s68, v13
	v_cmp_gt_f32_e32 vcc, s68, v12
	v_add_f32_e32 v7, 1.0, v7
	v_cndmask_b32_e64 v0, v13, v0, s[6:7]
	v_rsq_f32_e32 v0, v0
	v_rcp_f32_e32 v7, v7
	v_mul_f32_e32 v8, 0x45800000, v0
	v_cndmask_b32_e64 v0, v0, v8, s[6:7]
	v_mul_f32_e32 v0, v9, v0
	v_mul_f32_e32 v7, v7, v32
	v_mul_f32_e32 v0, v16, v0
	v_mul_f32_e32 v0, v7, v0
	v_cvt_pk_bf16_f32 v0, v0, s0
	global_store_short v[18:19], v0, off
	v_mul_f32_e32 v0, 0x4b800000, v12
	v_cndmask_b32_e32 v0, v12, v0, vcc
	v_rsq_f32_e32 v0, v0
	v_or_b32_e32 v32, 3, v6
	v_ashrrev_i32_e32 v33, 31, v32
	v_lshlrev_b64 v[8:9], 11, v[32:33]
	v_mul_f32_e32 v7, 0x45800000, v0
	v_cndmask_b32_e32 v0, v0, v7, vcc
	v_mul_f32_e32 v7, 0xbfb8aa3b, v31
	v_exp_f32_e32 v7, v7
	v_mul_f32_e32 v0, v10, v0
	v_mul_f32_e32 v0, v16, v0
	v_lshl_add_u64 v[8:9], v[2:3], 0, v[8:9]
	v_add_f32_e32 v7, 1.0, v7
	v_rcp_f32_e32 v7, v7
	v_or_b32_e32 v18, 5, v6
	v_ashrrev_i32_e32 v19, 31, v18
	v_mul_f32_e32 v7, v7, v31
	v_mul_f32_e32 v0, v7, v0
	v_cvt_pk_bf16_f32 v0, v0, s0
	global_store_short v[8:9], v0, off
	v_mul_f32_e32 v0, v11, v11
	v_add_u32_e32 v7, 0x7000, v14
	v_or_b32_e32 v8, 4, v6
	v_mov_b32_dpp v0, v0 quad_perm:[1,0,3,2] row_mask:0xf bank_mask:0xf bound_ctrl:1
	v_fmac_f32_e32 v0, v11, v11
	v_ashrrev_i32_e32 v9, 31, v8
	v_lshlrev_b64 v[8:9], 11, v[8:9]
	v_add_f32_dpp v0, v0, v0 quad_perm:[2,3,0,1] row_mask:0xf bank_mask:0xf bound_ctrl:1
	v_lshl_add_u64 v[8:9], v[2:3], 0, v[8:9]
	s_nop 0
	v_add_f32_dpp v0, v0, v0 row_half_mirror row_mask:0xf bank_mask:0xf bound_ctrl:1
	s_nop 1
	v_add_f32_dpp v0, v0, v0 row_mirror row_mask:0xf bank_mask:0xf bound_ctrl:1
	s_nop 0
	v_readlane_b32 s6, v0, 0
	v_readlane_b32 s3, v0, 16
	v_readlane_b32 s7, v0, 32
	v_readlane_b32 s5, v0, 48
	v_mul_f32_e32 v0, 0xbfb8aa3b, v30
	v_exp_f32_e32 v0, v0
	v_mov_b32_e32 v12, s3
	v_mov_b32_e32 v13, s5
	v_pk_add_f32 v[12:13], s[6:7], v[12:13]
	v_add_f32_e32 v0, 1.0, v0
	v_rcp_f32_e32 v0, v0
	v_mov_b32_e32 v35, v12
	v_mul_f32_e32 v0, v0, v30
	ds_read2_b32 v[30:31], v7 offset0:4 offset1:69
	s_waitcnt lgkmcnt(0)
	v_mul_f32_e32 v10, v30, v30
	s_nop 1
	v_mov_b32_dpp v10, v10 quad_perm:[1,0,3,2] row_mask:0xf bank_mask:0xf bound_ctrl:1
	v_fmac_f32_e32 v10, v30, v30
	s_nop 1
	v_add_f32_dpp v10, v10, v10 quad_perm:[2,3,0,1] row_mask:0xf bank_mask:0xf bound_ctrl:1
	s_nop 1
	v_add_f32_dpp v10, v10, v10 row_half_mirror row_mask:0xf bank_mask:0xf bound_ctrl:1
	s_nop 1
	v_add_f32_dpp v10, v10, v10 row_mirror row_mask:0xf bank_mask:0xf bound_ctrl:1
	s_nop 0
	v_readlane_b32 s3, v10, 16
	v_readlane_b32 s5, v10, 48
	v_readlane_b32 s6, v10, 0
	v_readlane_b32 s7, v10, 32
	v_mov_b32_e32 v32, s3
	v_mov_b32_e32 v33, s5
	v_pk_add_f32 v[32:33], s[6:7], v[32:33]
	s_nop 0
	v_mov_b32_e32 v34, v32
	v_mov_b32_e32 v12, v33
	v_pk_add_f32 v[12:13], v[34:35], v[12:13]
	s_nop 0
	v_pk_fma_f32 v[12:13], v[12:13], s[10:11], v[4:5] op_sel_hi:[1,0,0]
	s_nop 0
	v_mul_f32_e32 v10, 0x4b800000, v13
	v_cmp_gt_f32_e64 s[6:7], s68, v13
	v_cmp_gt_f32_e32 vcc, s68, v12
	s_nop 0
	v_cndmask_b32_e64 v10, v13, v10, s[6:7]
	v_rsq_f32_e32 v10, v10
	s_nop 0
	v_mul_f32_e32 v13, 0x45800000, v10
	v_cndmask_b32_e64 v10, v10, v13, s[6:7]
	v_mul_f32_e32 v10, v11, v10
	v_mul_f32_e32 v10, v16, v10
	v_mul_f32_e32 v0, v0, v10
	v_cvt_pk_bf16_f32 v0, v0, s0
	global_store_short v[8:9], v0, off
	v_mul_f32_e32 v0, 0x4b800000, v12
	v_cndmask_b32_e32 v0, v12, v0, vcc
	v_rsq_f32_e32 v0, v0
	v_or_b32_e32 v12, 7, v6
	v_ashrrev_i32_e32 v13, 31, v12
	v_mul_f32_e32 v8, 0x45800000, v0
	v_cndmask_b32_e32 v0, v0, v8, vcc
	v_mul_f32_e32 v8, 0xbfb8aa3b, v29
	v_exp_f32_e32 v8, v8
	v_mul_f32_e32 v0, v30, v0
	v_mul_f32_e32 v0, v16, v0
	v_add_f32_e32 v8, 1.0, v8
	v_rcp_f32_e32 v8, v8
	s_nop 0
	v_mul_f32_e32 v8, v8, v29
	v_mul_f32_e32 v0, v8, v0
	v_lshlrev_b64 v[8:9], 11, v[18:19]
	v_cvt_pk_bf16_f32 v0, v0, s0
	v_lshl_add_u64 v[8:9], v[2:3], 0, v[8:9]
	global_store_short v[8:9], v0, off
	v_mul_f32_e32 v0, v31, v31
	ds_read2_b32 v[18:19], v7 offset0:134 offset1:199
	v_or_b32_e32 v8, 6, v6
	v_mov_b32_dpp v0, v0 quad_perm:[1,0,3,2] row_mask:0xf bank_mask:0xf bound_ctrl:1
	v_fmac_f32_e32 v0, v31, v31
	v_ashrrev_i32_e32 v9, 31, v8
	s_waitcnt lgkmcnt(0)
	v_mul_f32_e32 v7, v18, v18
	v_add_f32_dpp v0, v0, v0 quad_perm:[2,3,0,1] row_mask:0xf bank_mask:0xf bound_ctrl:1
	v_lshlrev_b64 v[8:9], 11, v[8:9]
	v_mov_b32_dpp v7, v7 quad_perm:[1,0,3,2] row_mask:0xf bank_mask:0xf bound_ctrl:1
	v_add_f32_dpp v0, v0, v0 row_half_mirror row_mask:0xf bank_mask:0xf bound_ctrl:1
	v_fmac_f32_e32 v7, v18, v18
	v_lshl_add_u64 v[8:9], v[2:3], 0, v[8:9]
	v_add_f32_dpp v0, v0, v0 row_mirror row_mask:0xf bank_mask:0xf bound_ctrl:1
	v_add_f32_dpp v7, v7, v7 quad_perm:[2,3,0,1] row_mask:0xf bank_mask:0xf bound_ctrl:1
	v_readlane_b32 s6, v0, 0
	v_readlane_b32 s3, v0, 16
	v_readlane_b32 s7, v0, 32
	v_readlane_b32 s5, v0, 48
	v_mul_f32_e32 v0, 0xbfb8aa3b, v28
	v_exp_f32_e32 v0, v0
	v_add_f32_dpp v7, v7, v7 row_half_mirror row_mask:0xf bank_mask:0xf bound_ctrl:1
	v_mov_b32_e32 v10, s3
	v_mov_b32_e32 v11, s5
	v_add_f32_e32 v0, 1.0, v0
	v_rcp_f32_e32 v0, v0
	v_add_f32_dpp v7, v7, v7 row_mirror row_mask:0xf bank_mask:0xf bound_ctrl:1
	v_pk_add_f32 v[10:11], s[6:7], v[10:11]
	v_readlane_b32 s3, v7, 16
	v_readlane_b32 s5, v7, 48
	v_mul_f32_e32 v0, v0, v28
	v_readlane_b32 s6, v7, 0
	v_readlane_b32 s7, v7, 32
	v_mov_b32_e32 v28, s3
	v_mov_b32_e32 v29, s5
	v_pk_add_f32 v[28:29], s[6:7], v[28:29]
	v_mov_b32_e32 v33, v10
	v_mov_b32_e32 v32, v28
	v_mov_b32_e32 v10, v29
	v_pk_add_f32 v[10:11], v[32:33], v[10:11]
	s_nop 0
	v_pk_fma_f32 v[10:11], v[10:11], s[10:11], v[4:5] op_sel_hi:[1,0,0]
	s_nop 0
	v_mul_f32_e32 v7, 0x4b800000, v11
	v_cmp_gt_f32_e64 s[6:7], s68, v11
	v_cmp_gt_f32_e32 vcc, s68, v10
	s_nop 0
	v_cndmask_b32_e64 v7, v11, v7, s[6:7]
	v_rsq_f32_e32 v7, v7
	s_nop 0
	v_mul_f32_e32 v11, 0x45800000, v7
	v_cndmask_b32_e64 v7, v7, v11, s[6:7]
	v_mul_f32_e32 v7, v31, v7
	v_mul_f32_e32 v7, v16, v7
	v_mul_f32_e32 v0, v0, v7
	v_cvt_pk_bf16_f32 v0, v0, s0
	global_store_short v[8:9], v0, off
	v_mul_f32_e32 v0, 0x4b800000, v10
	v_cndmask_b32_e32 v0, v10, v0, vcc
	v_rsq_f32_e32 v0, v0
	v_lshlrev_b64 v[8:9], 11, v[12:13]
	v_lshl_add_u64 v[8:9], v[2:3], 0, v[8:9]
	v_or_b32_e32 v12, 9, v6
	v_mul_f32_e32 v7, 0x45800000, v0
	v_cndmask_b32_e32 v0, v0, v7, vcc
	v_mul_f32_e32 v7, 0xbfb8aa3b, v27
	v_exp_f32_e32 v7, v7
	v_mul_f32_e32 v0, v18, v0
	v_mul_f32_e32 v0, v16, v0
	v_ashrrev_i32_e32 v13, 31, v12
	v_add_f32_e32 v7, 1.0, v7
	v_rcp_f32_e32 v7, v7
	s_nop 0
	v_mul_f32_e32 v7, v7, v27
	v_mul_f32_e32 v0, v7, v0
	v_cvt_pk_bf16_f32 v0, v0, s0
	global_store_short v[8:9], v0, off
	v_mul_f32_e32 v0, v19, v19
	v_add_u32_e32 v7, 0x7400, v14
	v_or_b32_e32 v8, 8, v6
	v_mov_b32_dpp v0, v0 quad_perm:[1,0,3,2] row_mask:0xf bank_mask:0xf bound_ctrl:1
	v_fmac_f32_e32 v0, v19, v19
	v_ashrrev_i32_e32 v9, 31, v8
	v_lshlrev_b64 v[8:9], 11, v[8:9]
	v_add_f32_dpp v0, v0, v0 quad_perm:[2,3,0,1] row_mask:0xf bank_mask:0xf bound_ctrl:1
	v_lshl_add_u64 v[8:9], v[2:3], 0, v[8:9]
	s_nop 0
	v_add_f32_dpp v0, v0, v0 row_half_mirror row_mask:0xf bank_mask:0xf bound_ctrl:1
	s_nop 1
	v_add_f32_dpp v0, v0, v0 row_mirror row_mask:0xf bank_mask:0xf bound_ctrl:1
	s_nop 0
	v_readlane_b32 s6, v0, 0
	v_readlane_b32 s3, v0, 16
	v_readlane_b32 s7, v0, 32
	v_readlane_b32 s5, v0, 48
	v_mul_f32_e32 v0, 0xbfb8aa3b, v26
	v_exp_f32_e32 v0, v0
	v_mov_b32_e32 v10, s3
	v_mov_b32_e32 v11, s5
	v_pk_add_f32 v[10:11], s[6:7], v[10:11]
	v_add_f32_e32 v0, 1.0, v0
	v_rcp_f32_e32 v0, v0
	v_mov_b32_e32 v31, v10
	v_mul_f32_e32 v0, v0, v26
	ds_read2_b32 v[26:27], v7 offset0:8 offset1:73
	s_waitcnt lgkmcnt(0)
	v_mul_f32_e32 v15, v26, v26
	s_nop 1
	v_mov_b32_dpp v15, v15 quad_perm:[1,0,3,2] row_mask:0xf bank_mask:0xf bound_ctrl:1
	v_fmac_f32_e32 v15, v26, v26
	s_nop 1
	v_add_f32_dpp v15, v15, v15 quad_perm:[2,3,0,1] row_mask:0xf bank_mask:0xf bound_ctrl:1
	s_nop 1
	v_add_f32_dpp v15, v15, v15 row_half_mirror row_mask:0xf bank_mask:0xf bound_ctrl:1
	s_nop 1
	v_add_f32_dpp v15, v15, v15 row_mirror row_mask:0xf bank_mask:0xf bound_ctrl:1
	s_nop 0
	v_readlane_b32 s3, v15, 16
	v_readlane_b32 s5, v15, 48
	v_readlane_b32 s6, v15, 0
	v_readlane_b32 s7, v15, 32
	v_mov_b32_e32 v28, s3
	v_mov_b32_e32 v29, s5
	v_pk_add_f32 v[28:29], s[6:7], v[28:29]
	s_nop 0
	v_mov_b32_e32 v30, v28
	v_mov_b32_e32 v10, v29
	v_pk_add_f32 v[10:11], v[30:31], v[10:11]
	s_nop 0
	v_pk_fma_f32 v[10:11], v[10:11], s[10:11], v[4:5] op_sel_hi:[1,0,0]
	s_nop 0
	v_mul_f32_e32 v15, 0x4b800000, v11
	v_cmp_gt_f32_e64 s[6:7], s68, v11
	v_cmp_gt_f32_e32 vcc, s68, v10
	s_nop 0
	v_cndmask_b32_e64 v11, v11, v15, s[6:7]
	v_rsq_f32_e32 v11, v11
	s_nop 0
	v_mul_f32_e32 v15, 0x45800000, v11
	v_cndmask_b32_e64 v11, v11, v15, s[6:7]
	v_mul_f32_e32 v11, v19, v11
	v_mul_f32_e32 v11, v16, v11
	v_mul_f32_e32 v0, v0, v11
	v_cvt_pk_bf16_f32 v0, v0, s0
	global_store_short v[8:9], v0, off
	v_mul_f32_e32 v0, 0x4b800000, v10
	v_cndmask_b32_e32 v0, v10, v0, vcc
	v_rsq_f32_e32 v0, v0
	ds_read2_b32 v[18:19], v7 offset0:138 offset1:203
	v_mul_f32_e32 v8, 0x45800000, v0
	v_cndmask_b32_e32 v0, v0, v8, vcc
	v_mul_f32_e32 v8, 0xbfb8aa3b, v25
	v_exp_f32_e32 v8, v8
	v_mul_f32_e32 v0, v26, v0
	v_mul_f32_e32 v0, v16, v0
	s_waitcnt lgkmcnt(0)
	v_mul_f32_e32 v7, v18, v18
	v_add_f32_e32 v8, 1.0, v8
	v_rcp_f32_e32 v8, v8
	v_mov_b32_dpp v7, v7 quad_perm:[1,0,3,2] row_mask:0xf bank_mask:0xf bound_ctrl:1
	v_fmac_f32_e32 v7, v18, v18
	v_mul_f32_e32 v8, v8, v25
	v_mul_f32_e32 v0, v8, v0
	v_lshlrev_b64 v[8:9], 11, v[12:13]
	v_cvt_pk_bf16_f32 v0, v0, s0
	v_lshl_add_u64 v[8:9], v[2:3], 0, v[8:9]
	global_store_short v[8:9], v0, off
	v_mul_f32_e32 v0, v27, v27
	v_add_f32_dpp v7, v7, v7 quad_perm:[2,3,0,1] row_mask:0xf bank_mask:0xf bound_ctrl:1
	v_or_b32_e32 v8, 10, v6
	v_mov_b32_dpp v0, v0 quad_perm:[1,0,3,2] row_mask:0xf bank_mask:0xf bound_ctrl:1
	v_fmac_f32_e32 v0, v27, v27
	v_add_f32_dpp v7, v7, v7 row_half_mirror row_mask:0xf bank_mask:0xf bound_ctrl:1
	v_ashrrev_i32_e32 v9, 31, v8
	v_add_f32_dpp v0, v0, v0 quad_perm:[2,3,0,1] row_mask:0xf bank_mask:0xf bound_ctrl:1
	v_add_f32_dpp v7, v7, v7 row_mirror row_mask:0xf bank_mask:0xf bound_ctrl:1
	v_lshlrev_b64 v[8:9], 11, v[8:9]
	v_add_f32_dpp v0, v0, v0 row_half_mirror row_mask:0xf bank_mask:0xf bound_ctrl:1
	v_lshl_add_u64 v[8:9], v[2:3], 0, v[8:9]
	v_or_b32_e32 v12, 11, v6
	v_add_f32_dpp v0, v0, v0 row_mirror row_mask:0xf bank_mask:0xf bound_ctrl:1
	v_ashrrev_i32_e32 v13, 31, v12
	v_readlane_b32 s6, v0, 0
	v_readlane_b32 s3, v0, 16
	v_readlane_b32 s7, v0, 32
	v_readlane_b32 s5, v0, 48
	v_mul_f32_e32 v0, 0xbfb8aa3b, v24
	v_exp_f32_e32 v0, v0
	v_mov_b32_e32 v10, s3
	v_mov_b32_e32 v11, s5
	v_readlane_b32 s3, v7, 16
	v_add_f32_e32 v0, 1.0, v0
	v_rcp_f32_e32 v0, v0
	v_readlane_b32 s5, v7, 48
	v_pk_add_f32 v[10:11], s[6:7], v[10:11]
	v_readlane_b32 s6, v7, 0
	v_mul_f32_e32 v0, v0, v24
	v_readlane_b32 s7, v7, 32
	v_mov_b32_e32 v24, s3
	v_mov_b32_e32 v25, s5
	v_pk_add_f32 v[24:25], s[6:7], v[24:25]
	v_mov_b32_e32 v29, v10
	v_mov_b32_e32 v28, v24
	v_mov_b32_e32 v10, v25
	v_pk_add_f32 v[10:11], v[28:29], v[10:11]
	s_nop 0
	v_pk_fma_f32 v[10:11], v[10:11], s[10:11], v[4:5] op_sel_hi:[1,0,0]
	s_nop 0
	v_mul_f32_e32 v7, 0x4b800000, v11
	v_cmp_gt_f32_e64 s[6:7], s68, v11
	v_cmp_gt_f32_e32 vcc, s68, v10
	s_nop 0
	v_cndmask_b32_e64 v7, v11, v7, s[6:7]
	v_rsq_f32_e32 v7, v7
	s_nop 0
	v_mul_f32_e32 v11, 0x45800000, v7
	v_cndmask_b32_e64 v7, v7, v11, s[6:7]
	v_mul_f32_e32 v7, v27, v7
	v_mul_f32_e32 v7, v16, v7
	v_mul_f32_e32 v0, v0, v7
	v_cvt_pk_bf16_f32 v0, v0, s0
	global_store_short v[8:9], v0, off
	v_mul_f32_e32 v0, 0x4b800000, v10
	v_cndmask_b32_e32 v0, v10, v0, vcc
	v_rsq_f32_e32 v0, v0
	v_lshlrev_b64 v[8:9], 11, v[12:13]
	v_lshl_add_u64 v[8:9], v[2:3], 0, v[8:9]
	v_mul_f32_e32 v7, 0x45800000, v0
	v_cndmask_b32_e32 v0, v0, v7, vcc
	v_mul_f32_e32 v7, 0xbfb8aa3b, v23
	v_exp_f32_e32 v7, v7
	v_mul_f32_e32 v0, v18, v0
	v_mul_f32_e32 v0, v16, v0
	v_add_f32_e32 v7, 1.0, v7
	v_rcp_f32_e32 v7, v7
	s_nop 0
	v_mul_f32_e32 v7, v7, v23
	v_mul_f32_e32 v0, v7, v0
	v_cvt_pk_bf16_f32 v0, v0, s0
	global_store_short v[8:9], v0, off
	v_or_b32_e32 v8, 12, v6
	v_ashrrev_i32_e32 v9, 31, v8
	v_lshlrev_b64 v[8:9], 11, v[8:9]
	v_add_u32_e32 v7, 0x7800, v14
	v_lshl_add_u64 v[12:13], v[2:3], 0, v[8:9]
	ds_read2_b32 v[8:9], v7 offset0:12 offset1:77
	v_mul_f32_e32 v0, v19, v19
	s_waitcnt lgkmcnt(0)
	v_mul_f32_e32 v7, v8, v8
	v_mov_b32_dpp v0, v0 quad_perm:[1,0,3,2] row_mask:0xf bank_mask:0xf bound_ctrl:1
	v_fmac_f32_e32 v0, v19, v19
	v_mov_b32_dpp v7, v7 quad_perm:[1,0,3,2] row_mask:0xf bank_mask:0xf bound_ctrl:1
	v_fmac_f32_e32 v7, v8, v8
	v_add_f32_dpp v0, v0, v0 quad_perm:[2,3,0,1] row_mask:0xf bank_mask:0xf bound_ctrl:1
	s_nop 0
	v_add_f32_dpp v7, v7, v7 quad_perm:[2,3,0,1] row_mask:0xf bank_mask:0xf bound_ctrl:1
	v_add_f32_dpp v0, v0, v0 row_half_mirror row_mask:0xf bank_mask:0xf bound_ctrl:1
	s_nop 0
	v_add_f32_dpp v7, v7, v7 row_half_mirror row_mask:0xf bank_mask:0xf bound_ctrl:1
	v_add_f32_dpp v0, v0, v0 row_mirror row_mask:0xf bank_mask:0xf bound_ctrl:1
	s_nop 0
	v_readlane_b32 s3, v0, 16
	v_readlane_b32 s5, v0, 48
	v_add_f32_dpp v7, v7, v7 row_mirror row_mask:0xf bank_mask:0xf bound_ctrl:1
	v_readlane_b32 s6, v0, 0
	v_readlane_b32 s7, v0, 32
	v_mov_b32_e32 v10, s3
	v_mov_b32_e32 v11, s5
	v_readlane_b32 s3, v7, 16
	v_readlane_b32 s5, v7, 48
	v_pk_add_f32 v[10:11], s[6:7], v[10:11]
	v_readlane_b32 s6, v7, 0
	v_readlane_b32 s7, v7, 32
	v_mov_b32_e32 v24, s3
	v_mov_b32_e32 v25, s5
	v_pk_add_f32 v[24:25], s[6:7], v[24:25]
	v_mov_b32_e32 v27, v10
	v_mov_b32_e32 v26, v24
	v_mov_b32_e32 v10, v25
	v_pk_add_f32 v[10:11], v[26:27], v[10:11]
	v_mul_f32_e32 v0, 0xbfb8aa3b, v22
	v_pk_fma_f32 v[10:11], v[10:11], s[10:11], v[4:5] op_sel_hi:[1,0,0]
	v_exp_f32_e32 v0, v0
	v_mul_f32_e32 v7, 0x4b800000, v11
	v_cmp_gt_f32_e64 s[6:7], s68, v11
	v_cmp_gt_f32_e32 vcc, s68, v10
	v_add_f32_e32 v0, 1.0, v0
	v_cndmask_b32_e64 v7, v11, v7, s[6:7]
	v_rsq_f32_e32 v7, v7
	v_rcp_f32_e32 v0, v0
	v_mul_f32_e32 v11, 0x45800000, v7
	v_cndmask_b32_e64 v7, v7, v11, s[6:7]
	v_mul_f32_e32 v7, v19, v7
	v_mul_f32_e32 v0, v0, v22
	v_mul_f32_e32 v7, v16, v7
	v_mul_f32_e32 v0, v0, v7
	v_cvt_pk_bf16_f32 v0, v0, s0
	global_store_short v[12:13], v0, off
	v_mul_f32_e32 v0, 0x4b800000, v10
	v_cndmask_b32_e32 v0, v10, v0, vcc
	v_rsq_f32_e32 v0, v0
	v_or_b32_e32 v22, 13, v6
	v_ashrrev_i32_e32 v23, 31, v22
	v_lshlrev_b64 v[10:11], 11, v[22:23]
	v_mul_f32_e32 v7, 0x45800000, v0
	v_cndmask_b32_e32 v0, v0, v7, vcc
	v_mul_f32_e32 v7, 0xbfb8aa3b, v21
	v_exp_f32_e32 v7, v7
	v_mul_f32_e32 v0, v8, v0
	ds_read_b32 v8, v14 offset:31288
	v_mul_f32_e32 v0, v16, v0
	v_add_f32_e32 v7, 1.0, v7
	v_rcp_f32_e32 v7, v7
	v_lshl_add_u64 v[10:11], v[2:3], 0, v[10:11]
	s_waitcnt lgkmcnt(0)
	v_mul_f32_e32 v14, v8, v8
	v_mul_f32_e32 v7, v7, v21
	v_mul_f32_e32 v0, v7, v0
	v_cvt_pk_bf16_f32 v0, v0, s0
	global_store_short v[10:11], v0, off
	v_mul_f32_e32 v0, v9, v9
	v_mov_b32_dpp v14, v14 quad_perm:[1,0,3,2] row_mask:0xf bank_mask:0xf bound_ctrl:1
	v_fmac_f32_e32 v14, v8, v8
	v_mov_b32_dpp v0, v0 quad_perm:[1,0,3,2] row_mask:0xf bank_mask:0xf bound_ctrl:1
	v_fmac_f32_e32 v0, v9, v9
	v_add_f32_dpp v14, v14, v14 quad_perm:[2,3,0,1] row_mask:0xf bank_mask:0xf bound_ctrl:1
	v_or_b32_e32 v10, 14, v6
	v_add_f32_dpp v0, v0, v0 quad_perm:[2,3,0,1] row_mask:0xf bank_mask:0xf bound_ctrl:1
	v_add_f32_dpp v14, v14, v14 row_half_mirror row_mask:0xf bank_mask:0xf bound_ctrl:1
	v_ashrrev_i32_e32 v11, 31, v10
	v_add_f32_dpp v0, v0, v0 row_half_mirror row_mask:0xf bank_mask:0xf bound_ctrl:1
	v_add_f32_dpp v14, v14, v14 row_mirror row_mask:0xf bank_mask:0xf bound_ctrl:1
	v_lshlrev_b64 v[10:11], 11, v[10:11]
	v_add_f32_dpp v0, v0, v0 row_mirror row_mask:0xf bank_mask:0xf bound_ctrl:1
	v_lshl_add_u64 v[10:11], v[2:3], 0, v[10:11]
	v_readlane_b32 s3, v0, 16
	v_readlane_b32 s5, v0, 48
	v_readlane_b32 s6, v0, 0
	v_readlane_b32 s7, v0, 32
	v_mov_b32_e32 v12, s3
	v_mov_b32_e32 v13, s5
	v_readlane_b32 s3, v14, 16
	v_readlane_b32 s5, v14, 48
	v_pk_add_f32 v[12:13], s[6:7], v[12:13]
	v_readlane_b32 s6, v14, 0
	v_readlane_b32 s7, v14, 32
	v_mov_b32_e32 v14, s3
	v_mov_b32_e32 v15, s5
	v_pk_add_f32 v[14:15], s[6:7], v[14:15]
	v_mov_b32_e32 v19, v12
	v_mov_b32_e32 v18, v14
	v_mov_b32_e32 v12, v15
	v_pk_add_f32 v[12:13], v[18:19], v[12:13]
	v_mul_f32_e32 v0, 0xbfb8aa3b, v20
	v_pk_fma_f32 v[4:5], v[12:13], s[10:11], v[4:5] op_sel_hi:[1,0,0]
	v_exp_f32_e32 v0, v0
	v_mul_f32_e32 v12, 0x4b800000, v5
	v_cmp_gt_f32_e64 s[6:7], s68, v5
	v_cmp_gt_f32_e32 vcc, s68, v4
	v_add_f32_e32 v0, 1.0, v0
	v_cndmask_b32_e64 v5, v5, v12, s[6:7]
	v_rsq_f32_e32 v5, v5
	v_rcp_f32_e32 v0, v0
	v_or_b32_e32 v6, 15, v6
	v_ashrrev_i32_e32 v7, 31, v6
	v_mul_f32_e32 v12, 0x45800000, v5
	v_cndmask_b32_e64 v5, v5, v12, s[6:7]
	v_mul_f32_e32 v5, v9, v5
	v_mul_f32_e32 v0, v0, v20
	v_mul_f32_e32 v5, v16, v5
	v_mul_f32_e32 v0, v0, v5
	v_cvt_pk_bf16_f32 v0, v0, s0
	global_store_short v[10:11], v0, off
	v_mul_f32_e32 v0, 0x4b800000, v4
	v_cndmask_b32_e32 v0, v4, v0, vcc
	v_rsq_f32_e32 v0, v0
	v_readlane_b32 s6, v239, 25
	v_readlane_b32 s7, v239, 26
	s_add_u32 s8, s8, s6
	v_mul_f32_e32 v4, 0x45800000, v0
	v_cndmask_b32_e32 v0, v0, v4, vcc
	v_mul_f32_e32 v4, 0xbfb8aa3b, v17
	v_exp_f32_e32 v4, v4
	v_mul_f32_e32 v0, v8, v0
	v_mul_f32_e32 v0, v16, v0
	s_addc_u32 s9, s9, s7
	v_add_f32_e32 v4, 1.0, v4
	v_rcp_f32_e32 v4, v4
	s_add_i32 s4, s4, s38
	s_add_i32 s15, s15, s39
	s_cmpk_gt_i32 s16, 0x3ff
	v_mul_f32_e32 v4, v4, v17
	v_mul_f32_e32 v0, v4, v0
	v_lshlrev_b64 v[4:5], 11, v[6:7]
	v_cvt_pk_bf16_f32 v0, v0, s0
	v_lshl_add_u64 v[2:3], v[2:3], 0, v[4:5]
	global_store_short v[2:3], v0, off
	s_cbranch_scc1 .LBB0_100

.LBB0_145:
	v_add_co_u32_e32 v12, vcc, 0x1000, v2
	s_nop 1
	v_addc_co_u32_e32 v13, vcc, 0, v3, vcc
	global_load_ushort v10, v[12:13], off offset:2112
.LBB0_146:
	s_or_b32 s10, s7, 2
	v_mov_b32_e32 v12, 0
	s_cmp_ge_u32 s10, s6
	v_mov_b32_e32 v13, 0
	s_cbranch_scc1 .LBB0_148
	s_waitcnt vmcnt(17)
	v_add_co_u32_e32 v14, vcc, 0x2000, v2
	s_nop 1
	v_addc_co_u32_e32 v15, vcc, 0, v3, vcc
	global_load_ushort v13, v[14:15], off offset:3200
.LBB0_148:
	s_or_b32 s10, s7, 3
	s_cmp_ge_u32 s10, s6
	s_cbranch_scc1 .LBB0_150
	s_waitcnt vmcnt(17)
	v_add_co_u32_e32 v14, vcc, 0x4000, v2
	s_nop 1
	v_addc_co_u32_e32 v15, vcc, 0, v3, vcc
	global_load_ushort v12, v[14:15], off offset:192
.LBB0_150:
	s_or_b32 s10, s7, 4
	s_waitcnt vmcnt(17)
	v_mov_b32_e32 v14, 0
	s_cmp_ge_u32 s10, s6
	v_mov_b32_e32 v15, 0
	s_cbranch_scc1 .LBB0_152
	v_add_co_u32_e32 v16, vcc, 0x5000, v2
	s_nop 1
	v_addc_co_u32_e32 v17, vcc, 0, v3, vcc
	global_load_ushort v15, v[16:17], off offset:1280
.LBB0_152:
	s_or_b32 s10, s7, 5
	s_cmp_ge_u32 s10, s6
	s_cbranch_scc1 .LBB0_154
	v_add_co_u32_e32 v16, vcc, 0x6000, v2
	s_nop 1
	v_addc_co_u32_e32 v17, vcc, 0, v3, vcc
	global_load_ushort v14, v[16:17], off offset:2368
.LBB0_154:
	s_or_b32 s10, s7, 6
	v_mov_b32_e32 v16, 0
	s_cmp_ge_u32 s10, s6
	v_mov_b32_e32 v17, 0
	s_cbranch_scc1 .LBB0_156
	s_waitcnt vmcnt(16)
	v_add_co_u32_e32 v18, vcc, 0x7000, v2
	s_nop 1
	v_addc_co_u32_e32 v19, vcc, 0, v3, vcc
	global_load_ushort v17, v[18:19], off offset:3456
.LBB0_156:
	s_or_b32 s10, s7, 7
	s_cmp_ge_u32 s10, s6
	s_cbranch_scc1 .LBB0_158
	s_waitcnt vmcnt(16)
	v_add_co_u32_e32 v18, vcc, 0x9000, v2
	s_nop 1
	v_addc_co_u32_e32 v19, vcc, 0, v3, vcc
	global_load_ushort v16, v[18:19], off offset:448
.LBB0_158:
	s_or_b32 s10, s7, 8
	s_waitcnt vmcnt(16)
	v_mov_b32_e32 v18, 0
	s_cmp_ge_u32 s10, s6
	v_mov_b32_e32 v19, 0
	s_cbranch_scc1 .LBB0_160
	v_add_co_u32_e32 v20, vcc, 0xa000, v2
	s_nop 1
	v_addc_co_u32_e32 v21, vcc, 0, v3, vcc
	global_load_ushort v19, v[20:21], off offset:1536
.LBB0_160:
	s_or_b32 s10, s7, 9
	s_cmp_ge_u32 s10, s6
	s_cbranch_scc1 .LBB0_162
	v_add_co_u32_e32 v20, vcc, 0xb000, v2
	s_nop 1
	v_addc_co_u32_e32 v21, vcc, 0, v3, vcc
	global_load_ushort v18, v[20:21], off offset:2624
.LBB0_162:
	s_or_b32 s10, s7, 10
	v_mov_b32_e32 v20, 0
	s_cmp_ge_u32 s10, s6
	v_mov_b32_e32 v21, 0
	s_cbranch_scc1 .LBB0_164
	s_waitcnt vmcnt(15)
	v_add_co_u32_e32 v22, vcc, 0xc000, v2
	s_nop 1
	v_addc_co_u32_e32 v23, vcc, 0, v3, vcc
	global_load_ushort v21, v[22:23], off offset:3712
.LBB0_164:
	s_or_b32 s10, s7, 11
	s_cmp_ge_u32 s10, s6
	s_cbranch_scc1 .LBB0_166
	s_waitcnt vmcnt(15)
	v_add_co_u32_e32 v22, vcc, 0xe000, v2
	s_nop 1
	v_addc_co_u32_e32 v23, vcc, 0, v3, vcc
	global_load_ushort v20, v[22:23], off offset:704
.LBB0_166:
	s_or_b32 s10, s7, 12
	s_waitcnt vmcnt(15)
	v_mov_b32_e32 v22, 0
	s_cmp_ge_u32 s10, s6
	v_mov_b32_e32 v23, 0
	s_cbranch_scc1 .LBB0_168
	v_add_co_u32_e32 v24, vcc, 0xf000, v2
	s_nop 1
	v_addc_co_u32_e32 v25, vcc, 0, v3, vcc
	global_load_ushort v23, v[24:25], off offset:1792
.LBB0_168:
	s_or_b32 s10, s7, 13
	s_cmp_ge_u32 s10, s6
	s_cbranch_scc1 .LBB0_170
	v_add_co_u32_e32 v24, vcc, 0x10000, v2
	s_nop 1
	v_addc_co_u32_e32 v25, vcc, 0, v3, vcc
	global_load_ushort v22, v[24:25], off offset:2880
.LBB0_170:
	s_or_b32 s10, s7, 14
	v_mov_b32_e32 v24, 0
	s_cmp_ge_u32 s10, s6
	v_mov_b32_e32 v25, 0
	s_cbranch_scc1 .LBB0_172
	s_waitcnt vmcnt(14)
	v_add_co_u32_e32 v26, vcc, 0x11000, v2
	s_nop 1
	v_addc_co_u32_e32 v27, vcc, 0, v3, vcc
	global_load_ushort v25, v[26:27], off offset:3968
.LBB0_172:
	s_or_b32 s10, s7, 15
	s_cmp_ge_u32 s10, s6
	s_cbranch_scc1 .LBB0_174
	s_waitcnt vmcnt(14)
	v_add_co_u32_e32 v26, vcc, 0x13000, v2
	s_nop 1
	v_addc_co_u32_e32 v27, vcc, 0, v3, vcc
	global_load_ushort v24, v[26:27], off offset:960
.LBB0_174:
	s_or_b32 s10, s7, 16
	s_waitcnt vmcnt(14)
	v_mov_b32_e32 v26, 0
	s_cmp_ge_u32 s10, s6
	v_mov_b32_e32 v27, 0
	s_cbranch_scc1 .LBB0_176
	v_add_co_u32_e32 v28, vcc, 0x14000, v2
	s_nop 1
	v_addc_co_u32_e32 v29, vcc, 0, v3, vcc
	global_load_ushort v27, v[28:29], off offset:2048
.LBB0_176:
	s_or_b32 s10, s7, 17
	s_cmp_ge_u32 s10, s6
	s_cbranch_scc1 .LBB0_178
	v_add_co_u32_e32 v28, vcc, 0x15000, v2
	s_nop 1
	v_addc_co_u32_e32 v29, vcc, 0, v3, vcc
	global_load_ushort v26, v[28:29], off offset:3136
.LBB0_178:
	s_or_b32 s10, s7, 18
	v_mov_b32_e32 v28, 0
	s_cmp_ge_u32 s10, s6
	v_mov_b32_e32 v29, 0
	s_cbranch_scc1 .LBB0_180
	s_waitcnt vmcnt(13)
	v_add_co_u32_e32 v30, vcc, 0x17000, v2
	s_nop 1
	v_addc_co_u32_e32 v31, vcc, 0, v3, vcc
	global_load_ushort v29, v[30:31], off offset:128
.LBB0_180:
	s_or_b32 s10, s7, 19
	s_cmp_ge_u32 s10, s6
	s_cbranch_scc1 .LBB0_182
	s_waitcnt vmcnt(13)
	v_add_co_u32_e32 v30, vcc, 0x18000, v2
	s_nop 1
	v_addc_co_u32_e32 v31, vcc, 0, v3, vcc
	global_load_ushort v28, v[30:31], off offset:1216
.LBB0_182:
	s_or_b32 s10, s7, 20
	s_waitcnt vmcnt(13)
	v_mov_b32_e32 v30, 0
	s_cmp_ge_u32 s10, s6
	v_mov_b32_e32 v31, 0
	s_cbranch_scc1 .LBB0_184
	v_add_co_u32_e32 v32, vcc, 0x19000, v2
	s_nop 1
	v_addc_co_u32_e32 v33, vcc, 0, v3, vcc
	global_load_ushort v31, v[32:33], off offset:2304
.LBB0_184:
	s_or_b32 s10, s7, 21
	s_cmp_ge_u32 s10, s6
	s_cbranch_scc1 .LBB0_186
	v_add_co_u32_e32 v32, vcc, 0x1a000, v2
	s_nop 1
	v_addc_co_u32_e32 v33, vcc, 0, v3, vcc
	global_load_ushort v30, v[32:33], off offset:3392
.LBB0_186:
	s_or_b32 s10, s7, 22
	v_mov_b32_e32 v32, 0
	s_cmp_ge_u32 s10, s6
	v_mov_b32_e32 v33, 0
	s_cbranch_scc1 .LBB0_188
	v_add_co_u32_e32 v34, vcc, 0x1c000, v2
	s_nop 1
	v_addc_co_u32_e32 v35, vcc, 0, v3, vcc
	global_load_ushort v33, v[34:35], off offset:384
.LBB0_188:
	s_or_b32 s10, s7, 23
	s_cmp_ge_u32 s10, s6
	s_cbranch_scc1 .LBB0_190
	v_add_co_u32_e32 v34, vcc, 0x1d000, v2
	s_nop 1
	v_addc_co_u32_e32 v35, vcc, 0, v3, vcc
	global_load_ushort v32, v[34:35], off offset:1472
.LBB0_190:
	s_or_b32 s10, s7, 24
	v_mov_b32_e32 v34, 0
	s_cmp_ge_u32 s10, s6
	v_mov_b32_e32 v35, 0
	s_cbranch_scc1 .LBB0_192
	v_add_co_u32_e32 v36, vcc, 0x1e000, v2
	s_nop 1
	v_addc_co_u32_e32 v37, vcc, 0, v3, vcc
	global_load_ushort v35, v[36:37], off offset:2560
.LBB0_192:
	s_or_b32 s10, s7, 25
	s_cmp_ge_u32 s10, s6
	s_cbranch_scc1 .LBB0_194
	v_add_co_u32_e32 v36, vcc, 0x1f000, v2
	s_nop 1
	v_addc_co_u32_e32 v37, vcc, 0, v3, vcc
	global_load_ushort v34, v[36:37], off offset:3648
.LBB0_194:
	s_or_b32 s10, s7, 26
	v_mov_b32_e32 v36, 0
	s_cmp_ge_u32 s10, s6
	v_mov_b32_e32 v37, 0
	s_cbranch_scc1 .LBB0_196
	s_waitcnt vmcnt(12)
	v_add_co_u32_e32 v38, vcc, 0x21000, v2
	s_nop 1
	v_addc_co_u32_e32 v39, vcc, 0, v3, vcc
	global_load_ushort v37, v[38:39], off offset:640
.LBB0_196:
	s_or_b32 s10, s7, 27
	s_cmp_ge_u32 s10, s6
	s_cbranch_scc1 .LBB0_198
	s_waitcnt vmcnt(12)
	v_add_co_u32_e32 v38, vcc, 0x22000, v2
	s_nop 1
	v_addc_co_u32_e32 v39, vcc, 0, v3, vcc
	global_load_ushort v36, v[38:39], off offset:1728
.LBB0_198:
	s_or_b32 s10, s7, 28
	s_waitcnt vmcnt(12)
	v_mov_b32_e32 v38, 0
	s_cmp_ge_u32 s10, s6
	v_mov_b32_e32 v39, 0
	s_cbranch_scc1 .LBB0_200
	v_add_co_u32_e32 v40, vcc, 0x23000, v2
	s_nop 1
	v_addc_co_u32_e32 v41, vcc, 0, v3, vcc
	global_load_ushort v39, v[40:41], off offset:2816
.LBB0_200:
	s_or_b32 s10, s7, 29
	s_cmp_ge_u32 s10, s6
	s_cbranch_scc1 .LBB0_202
	v_add_co_u32_e32 v40, vcc, 0x24000, v2
	s_nop 1
	v_addc_co_u32_e32 v41, vcc, 0, v3, vcc
	global_load_ushort v38, v[40:41], off offset:3904
.LBB0_202:
	s_waitcnt vmcnt(0)
	v_lshlrev_b32_e32 v10, 16, v10
	v_lshlrev_b32_e32 v13, 16, v13
	v_lshlrev_b32_e32 v12, 16, v12
	v_lshlrev_b32_e32 v15, 16, v15
	v_lshlrev_b32_e32 v14, 16, v14
	v_lshlrev_b32_e32 v17, 16, v17
	v_lshlrev_b32_e32 v16, 16, v16
	v_lshlrev_b32_e32 v19, 16, v19
	v_lshlrev_b32_e32 v18, 16, v18
	v_lshlrev_b32_e32 v21, 16, v21
	v_lshlrev_b32_e32 v20, 16, v20
	v_lshlrev_b32_e32 v23, 16, v23
	v_lshlrev_b32_e32 v22, 16, v22
	v_lshlrev_b32_e32 v25, 16, v25
	v_lshlrev_b32_e32 v24, 16, v24
	v_lshlrev_b32_e32 v27, 16, v27
	v_lshlrev_b32_e32 v26, 16, v26
	v_lshlrev_b32_e32 v29, 16, v29
	v_lshlrev_b32_e32 v28, 16, v28
	v_lshlrev_b32_e32 v31, 16, v31
	v_lshlrev_b32_e32 v30, 16, v30
	v_lshlrev_b32_e32 v33, 16, v33
	v_lshlrev_b32_e32 v32, 16, v32
	v_lshlrev_b32_e32 v35, 16, v35
	v_lshlrev_b32_e32 v34, 16, v34
	v_lshlrev_b32_e32 v37, 16, v37
	v_lshlrev_b32_e32 v36, 16, v36
	v_lshlrev_b32_e32 v39, 16, v39
	v_lshlrev_b32_e32 v38, 16, v38
	s_or_b32 s10, s7, 30
	v_mov_b32_e32 v40, 0
	s_cmp_ge_u32 s10, s6
	v_mov_b32_e32 v41, 0
	s_cbranch_scc0 .LBB0_385
	s_or_b32 s24, s7, 31
	s_cmp_ge_u32 s24, s6
	s_cbranch_scc0 .LBB0_386

.LBB0_494:
	s_add_i32 s3, s16, 0xfffffc00
	s_lshl_b32 s10, s3, 5
	s_cmpk_gt_u32 s3, 0xff
	s_movk_i32 s4, 0x100
	s_cselect_b32 s8, 0x1000, s4
	s_movk_i32 s4, 0x1f00
	s_cselect_b32 s4, 0x3000, s4
	s_and_b32 s4, s4, s10
	s_add_i32 s11, s10, -2
	s_waitcnt vmcnt(0)
	v_mov_b32_e32 v18, v133
	s_sub_i32 s9, s11, s4
	s_load_dwordx2 s[6:7], s[0:1], 0x130
	s_waitcnt lgkmcnt(0)
	s_barrier
	s_load_dwordx4 s[20:23], s[0:1], 0x90
	s_cmp_gt_i32 s9, -1
	s_cselect_b64 s[4:5], -1, 0
	s_cmp_lt_u32 s9, s8
	s_cselect_b64 s[18:19], -1, 0
	s_and_b64 s[18:19], s[4:5], s[18:19]
	s_waitcnt lgkmcnt(0)
	s_add_u32 s20, s20, s14
	s_addc_u32 s21, s21, s15
	v_ashrrev_i32_e32 v19, 31, v18
	v_lshl_add_u64 v[8:9], v[18:19], 2, s[20:21]
	global_load_dword v2, v[8:9], off
	global_load_dword v4, v[8:9], off offset:1024
	global_load_dword v3, v[8:9], off offset:2048
	global_load_dword v0, v[8:9], off offset:3072
	v_add_u32_e32 v8, s47, v18
	v_mov_b32_e32 v6, s22
	v_mov_b32_e32 v7, s23
	v_ashrrev_i32_e32 v9, 31, v8
	v_lshl_add_u64 v[6:7], v[8:9], 2, v[6:7]
	global_load_dword v5, v[6:7], off
	v_mov_b32_e32 v6, 0
	s_andn2_b64 vcc, exec, s[18:19]
	v_mov_b32_e32 v7, 0
	s_cbranch_vccnz .LBB0_496
	s_mul_hi_u32 s17, s11, 0x1440
	s_mulk_i32 s11, 0x1440
	s_add_u32 s18, s6, s11
	s_addc_u32 s19, s7, s17
	v_lshl_add_u64 v[8:9], v[18:19], 1, s[18:19]
	v_add_co_u32_e32 v8, vcc, 0x4b27000, v8
	s_nop 1
	v_addc_co_u32_e32 v9, vcc, 0, v9, vcc
	global_load_ushort v7, v[8:9], off offset:3072
.LBB0_496:
	s_or_b32 s11, s9, 1
	s_cmp_lt_i32 s11, s8
	s_cselect_b64 s[18:19], -1, 0
	s_and_b64 s[4:5], s[4:5], s[18:19]
	s_andn2_b64 vcc, exec, s[4:5]
	s_cbranch_vccnz .LBB0_498
	s_add_i32 s4, s10, -1
	s_mul_hi_u32 s5, s4, 0x1440
	s_mulk_i32 s4, 0x1440
	s_add_u32 s4, s6, s4
	s_addc_u32 s5, s7, s5
	v_lshl_add_u64 v[8:9], v[18:19], 1, s[4:5]
	v_add_co_u32_e32 v8, vcc, 0x4b27000, v8
	s_nop 1
	v_addc_co_u32_e32 v9, vcc, 0, v9, vcc
	global_load_ushort v6, v[8:9], off offset:3072
.LBB0_498:
	s_add_i32 s4, s9, 2
	s_cmp_gt_i32 s9, -3
	s_cselect_b64 s[10:11], -1, 0
	s_cmp_lt_u32 s4, s8
	s_cselect_b64 s[18:19], -1, 0
	s_and_b64 s[10:11], s[10:11], s[18:19]
	s_mul_i32 s4, s3, 0x28800
	v_mov_b32_e32 v8, 0
	s_andn2_b64 vcc, exec, s[10:11]
	v_mov_b32_e32 v9, 0
	s_cbranch_vccnz .LBB0_500
	s_add_u32 s10, s6, s4
	s_addc_u32 s11, s7, 0
	v_lshl_add_u64 v[10:11], v[18:19], 1, s[10:11]
	v_add_co_u32_e32 v10, vcc, 0x4b27000, v10
	s_nop 1
	v_addc_co_u32_e32 v11, vcc, 0, v11, vcc
	global_load_ushort v9, v[10:11], off offset:3072
.LBB0_500:
	s_add_i32 s5, s9, 3
	s_cmp_gt_i32 s9, -4
	s_cselect_b64 s[10:11], -1, 0
	s_cmp_lt_u32 s5, s8
	s_cselect_b64 s[18:19], -1, 0
	s_and_b64 s[10:11], s[10:11], s[18:19]
	s_andn2_b64 vcc, exec, s[10:11]
	s_cbranch_vccnz .LBB0_502
	s_add_u32 s10, s6, s4
	s_addc_u32 s11, s7, 0
	v_lshl_add_u64 v[10:11], v[18:19], 1, s[10:11]
	v_add_co_u32_e32 v10, vcc, 0x4b29000, v10
	s_nop 1
	v_addc_co_u32_e32 v11, vcc, 0, v11, vcc
	global_load_ushort v8, v[10:11], off offset:64
.LBB0_502:
	s_add_i32 s5, s9, 4
	s_cmp_gt_i32 s9, -5
	s_cselect_b64 s[10:11], -1, 0
	s_cmp_lt_u32 s5, s8
	s_cselect_b64 s[18:19], -1, 0
	s_and_b64 s[10:11], s[10:11], s[18:19]
	v_mov_b32_e32 v10, 0
	s_andn2_b64 vcc, exec, s[10:11]
	v_mov_b32_e32 v11, 0
	s_cbranch_vccnz .LBB0_504
	s_add_u32 s10, s6, s4
	s_addc_u32 s11, s7, 0
	v_lshl_add_u64 v[12:13], v[18:19], 1, s[10:11]
	v_add_co_u32_e32 v12, vcc, 0x4b2a000, v12
	s_nop 1
	v_addc_co_u32_e32 v13, vcc, 0, v13, vcc
	global_load_ushort v11, v[12:13], off offset:1152
.LBB0_504:
	s_add_i32 s5, s9, 5
	s_cmp_gt_i32 s9, -6
	s_cselect_b64 s[10:11], -1, 0
	s_cmp_lt_u32 s5, s8
	s_cselect_b64 s[18:19], -1, 0
	s_and_b64 s[10:11], s[10:11], s[18:19]
	s_andn2_b64 vcc, exec, s[10:11]
	s_cbranch_vccnz .LBB0_506
	s_add_u32 s10, s6, s4
	s_addc_u32 s11, s7, 0
	v_lshl_add_u64 v[12:13], v[18:19], 1, s[10:11]
	v_add_co_u32_e32 v12, vcc, 0x4b2b000, v12
	s_nop 1
	v_addc_co_u32_e32 v13, vcc, 0, v13, vcc
	global_load_ushort v10, v[12:13], off offset:2240
.LBB0_506:
	s_add_i32 s5, s9, 6
	s_cmp_gt_i32 s9, -7
	s_cselect_b64 s[10:11], -1, 0
	s_cmp_lt_u32 s5, s8
	s_cselect_b64 s[18:19], -1, 0
	s_and_b64 s[10:11], s[10:11], s[18:19]
	v_mov_b32_e32 v12, 0
	s_andn2_b64 vcc, exec, s[10:11]
	v_mov_b32_e32 v13, 0
	s_cbranch_vccnz .LBB0_508
	s_add_u32 s10, s6, s4
	s_addc_u32 s11, s7, 0
	v_lshl_add_u64 v[14:15], v[18:19], 1, s[10:11]
	v_add_co_u32_e32 v14, vcc, 0x4b2c000, v14
	s_nop 1
	v_addc_co_u32_e32 v15, vcc, 0, v15, vcc
	global_load_ushort v13, v[14:15], off offset:3328
.LBB0_508:
	s_add_i32 s5, s9, 7
	s_cmp_gt_i32 s9, -8
	s_cselect_b64 s[10:11], -1, 0
	s_cmp_lt_u32 s5, s8
	s_cselect_b64 s[18:19], -1, 0
	s_and_b64 s[10:11], s[10:11], s[18:19]
	s_andn2_b64 vcc, exec, s[10:11]
	s_cbranch_vccnz .LBB0_510
	s_add_u32 s10, s6, s4
	s_addc_u32 s11, s7, 0
	v_lshl_add_u64 v[14:15], v[18:19], 1, s[10:11]
	v_add_co_u32_e32 v14, vcc, 0x4b2e000, v14
	s_nop 1
	v_addc_co_u32_e32 v15, vcc, 0, v15, vcc
	global_load_ushort v12, v[14:15], off offset:320
.LBB0_510:
	s_add_i32 s5, s9, 8
	s_cmp_gt_i32 s9, -9
	s_cselect_b64 s[10:11], -1, 0
	s_cmp_lt_u32 s5, s8
	s_cselect_b64 s[18:19], -1, 0
	s_and_b64 s[10:11], s[10:11], s[18:19]
	v_mov_b32_e32 v14, 0
	s_andn2_b64 vcc, exec, s[10:11]
	v_mov_b32_e32 v15, 0
	s_cbranch_vccnz .LBB0_512
	s_add_u32 s10, s6, s4
	s_addc_u32 s11, s7, 0
	v_lshl_add_u64 v[16:17], v[18:19], 1, s[10:11]
	v_add_co_u32_e32 v16, vcc, 0x4b2f000, v16
	s_nop 1
	v_addc_co_u32_e32 v17, vcc, 0, v17, vcc
	global_load_ushort v15, v[16:17], off offset:1408
.LBB0_512:
	s_add_i32 s5, s9, 9
	s_cmp_gt_i32 s9, -10
	s_cselect_b64 s[10:11], -1, 0
	s_cmp_lt_u32 s5, s8
	s_cselect_b64 s[18:19], -1, 0
	s_and_b64 s[10:11], s[10:11], s[18:19]
	s_andn2_b64 vcc, exec, s[10:11]
	s_cbranch_vccnz .LBB0_514
	s_add_u32 s10, s6, s4
	s_addc_u32 s11, s7, 0
	v_lshl_add_u64 v[16:17], v[18:19], 1, s[10:11]
	v_add_co_u32_e32 v16, vcc, 0x4b30000, v16
	s_nop 1
	v_addc_co_u32_e32 v17, vcc, 0, v17, vcc
	global_load_ushort v14, v[16:17], off offset:2496
.LBB0_514:
	s_add_i32 s5, s9, 10
	s_cmp_gt_i32 s9, -11
	s_cselect_b64 s[10:11], -1, 0
	s_cmp_lt_u32 s5, s8
	s_cselect_b64 s[18:19], -1, 0
	s_and_b64 s[10:11], s[10:11], s[18:19]
	v_mov_b32_e32 v16, 0
	s_andn2_b64 vcc, exec, s[10:11]
	v_mov_b32_e32 v17, 0
	s_cbranch_vccnz .LBB0_516
	s_add_u32 s10, s6, s4
	s_addc_u32 s11, s7, 0
	v_lshl_add_u64 v[20:21], v[18:19], 1, s[10:11]
	v_add_co_u32_e32 v20, vcc, 0x4b31000, v20
	s_nop 1
	v_addc_co_u32_e32 v21, vcc, 0, v21, vcc
	global_load_ushort v17, v[20:21], off offset:3584
.LBB0_516:
	s_add_i32 s5, s9, 11
	s_cmp_gt_i32 s9, -12
	s_cselect_b64 s[10:11], -1, 0
	s_cmp_lt_u32 s5, s8
	s_cselect_b64 s[18:19], -1, 0
	s_and_b64 s[10:11], s[10:11], s[18:19]
	s_andn2_b64 vcc, exec, s[10:11]
	s_cbranch_vccnz .LBB0_518
	s_add_u32 s10, s6, s4
	s_addc_u32 s11, s7, 0
	v_lshl_add_u64 v[20:21], v[18:19], 1, s[10:11]
	v_add_co_u32_e32 v20, vcc, 0x4b33000, v20
	s_nop 1
	v_addc_co_u32_e32 v21, vcc, 0, v21, vcc
	global_load_ushort v16, v[20:21], off offset:576
.LBB0_518:
	s_add_i32 s5, s9, 12
	s_cmp_gt_i32 s9, -13
	s_cselect_b64 s[10:11], -1, 0
	s_cmp_lt_u32 s5, s8
	s_cselect_b64 s[18:19], -1, 0
	s_and_b64 s[10:11], s[10:11], s[18:19]
	v_mov_b32_e32 v20, 0
	s_andn2_b64 vcc, exec, s[10:11]
	v_mov_b32_e32 v21, 0
	s_cbranch_vccnz .LBB0_520
	s_add_u32 s10, s6, s4
	s_addc_u32 s11, s7, 0
	v_lshl_add_u64 v[22:23], v[18:19], 1, s[10:11]
	v_add_co_u32_e32 v22, vcc, 0x4b34000, v22
	s_nop 1
	v_addc_co_u32_e32 v23, vcc, 0, v23, vcc
	global_load_ushort v21, v[22:23], off offset:1664
.LBB0_520:
	s_add_i32 s5, s9, 13
	s_cmp_gt_i32 s9, -14
	s_cselect_b64 s[10:11], -1, 0
	s_cmp_lt_u32 s5, s8
	s_cselect_b64 s[18:19], -1, 0
	s_and_b64 s[10:11], s[10:11], s[18:19]
	s_andn2_b64 vcc, exec, s[10:11]
	s_cbranch_vccnz .LBB0_522
	s_add_u32 s10, s6, s4
	s_addc_u32 s11, s7, 0
	v_lshl_add_u64 v[22:23], v[18:19], 1, s[10:11]
	v_add_co_u32_e32 v22, vcc, 0x4b35000, v22
	s_nop 1
	v_addc_co_u32_e32 v23, vcc, 0, v23, vcc
	global_load_ushort v20, v[22:23], off offset:2752
.LBB0_522:
	s_add_i32 s5, s9, 14
	s_cmp_gt_i32 s9, -15
	s_cselect_b64 s[10:11], -1, 0
	s_cmp_lt_u32 s5, s8
	s_cselect_b64 s[18:19], -1, 0
	s_and_b64 s[10:11], s[10:11], s[18:19]
	v_mov_b32_e32 v22, 0
	s_andn2_b64 vcc, exec, s[10:11]
	v_mov_b32_e32 v23, 0
	s_cbranch_vccnz .LBB0_524
	s_add_u32 s10, s6, s4
	s_addc_u32 s11, s7, 0
	v_lshl_add_u64 v[24:25], v[18:19], 1, s[10:11]
	v_add_co_u32_e32 v24, vcc, 0x4b36000, v24
	s_nop 1
	v_addc_co_u32_e32 v25, vcc, 0, v25, vcc
	global_load_ushort v23, v[24:25], off offset:3840
.LBB0_524:
	s_add_i32 s5, s9, 15
	s_cmp_gt_i32 s9, -16
	s_cselect_b64 s[10:11], -1, 0
	s_cmp_lt_u32 s5, s8
	s_cselect_b64 s[18:19], -1, 0
	s_and_b64 s[10:11], s[10:11], s[18:19]
	s_andn2_b64 vcc, exec, s[10:11]
	s_cbranch_vccnz .LBB0_526
	s_add_u32 s10, s6, s4
	s_addc_u32 s11, s7, 0
	v_lshl_add_u64 v[24:25], v[18:19], 1, s[10:11]
	v_add_co_u32_e32 v24, vcc, 0x4b38000, v24
	s_nop 1
	v_addc_co_u32_e32 v25, vcc, 0, v25, vcc
	global_load_ushort v22, v[24:25], off offset:832
.LBB0_526:
	s_add_i32 s5, s9, 16
	s_cmpk_gt_i32 s9, 0xffef
	s_cselect_b64 s[10:11], -1, 0
	s_cmp_lt_u32 s5, s8
	s_cselect_b64 s[18:19], -1, 0
	s_and_b64 s[10:11], s[10:11], s[18:19]
	v_mov_b32_e32 v24, 0
	s_andn2_b64 vcc, exec, s[10:11]
	v_mov_b32_e32 v25, 0
	s_cbranch_vccnz .LBB0_528
	s_add_u32 s10, s6, s4
	s_addc_u32 s11, s7, 0
	v_lshl_add_u64 v[26:27], v[18:19], 1, s[10:11]
	v_add_co_u32_e32 v26, vcc, 0x4b39000, v26
	s_nop 1
	v_addc_co_u32_e32 v27, vcc, 0, v27, vcc
	global_load_ushort v25, v[26:27], off offset:1920
.LBB0_528:
	s_add_i32 s5, s9, 17
	s_cmpk_gt_i32 s9, 0xffee
	s_cselect_b64 s[10:11], -1, 0
	s_cmp_lt_u32 s5, s8
	s_cselect_b64 s[18:19], -1, 0
	s_and_b64 s[10:11], s[10:11], s[18:19]
	s_andn2_b64 vcc, exec, s[10:11]
	s_cbranch_vccnz .LBB0_530
	s_add_u32 s10, s6, s4
	s_addc_u32 s11, s7, 0
	v_lshl_add_u64 v[26:27], v[18:19], 1, s[10:11]
	v_add_co_u32_e32 v26, vcc, 0x4b3a000, v26
	s_nop 1
	v_addc_co_u32_e32 v27, vcc, 0, v27, vcc
	global_load_ushort v24, v[26:27], off offset:3008
.LBB0_530:
	s_add_i32 s5, s9, 18
	s_cmpk_gt_i32 s9, 0xffed
	s_cselect_b64 s[10:11], -1, 0
	s_cmp_lt_u32 s5, s8
	s_cselect_b64 s[18:19], -1, 0
	s_and_b64 s[10:11], s[10:11], s[18:19]
	v_mov_b32_e32 v26, 0
	s_andn2_b64 vcc, exec, s[10:11]
	v_mov_b32_e32 v27, 0
	s_cbranch_vccnz .LBB0_532
	s_add_u32 s10, s6, s4
	s_addc_u32 s11, s7, 0
	v_lshl_add_u64 v[28:29], v[18:19], 1, s[10:11]
	v_add_co_u32_e32 v28, vcc, 0x4b3c000, v28
	s_nop 1
	v_addc_co_u32_e32 v29, vcc, 0, v29, vcc
	global_load_ushort v27, v[28:29], off
.LBB0_532:
	s_add_i32 s5, s9, 19
	s_cmpk_gt_i32 s9, 0xffec
	s_cselect_b64 s[10:11], -1, 0
	s_cmp_lt_u32 s5, s8
	s_cselect_b64 s[18:19], -1, 0
	s_and_b64 s[10:11], s[10:11], s[18:19]
	s_andn2_b64 vcc, exec, s[10:11]
	s_cbranch_vccnz .LBB0_534
	s_add_u32 s10, s6, s4
	s_addc_u32 s11, s7, 0
	v_lshl_add_u64 v[28:29], v[18:19], 1, s[10:11]
	v_add_co_u32_e32 v28, vcc, 0x4b3d000, v28
	s_nop 1
	v_addc_co_u32_e32 v29, vcc, 0, v29, vcc
	global_load_ushort v26, v[28:29], off offset:1088
.LBB0_534:
	s_add_i32 s5, s9, 20
	s_cmpk_gt_i32 s9, 0xffeb
	s_cselect_b64 s[10:11], -1, 0
	s_cmp_lt_u32 s5, s8
	s_cselect_b64 s[18:19], -1, 0
	s_and_b64 s[10:11], s[10:11], s[18:19]
	v_mov_b32_e32 v28, 0
	s_andn2_b64 vcc, exec, s[10:11]
	v_mov_b32_e32 v29, 0
	s_cbranch_vccnz .LBB0_536
	s_add_u32 s10, s6, s4
	s_addc_u32 s11, s7, 0
	v_lshl_add_u64 v[30:31], v[18:19], 1, s[10:11]
	v_add_co_u32_e32 v30, vcc, 0x4b3e000, v30
	s_nop 1
	v_addc_co_u32_e32 v31, vcc, 0, v31, vcc
	global_load_ushort v29, v[30:31], off offset:2176
.LBB0_536:
	s_add_i32 s5, s9, 21
	s_cmpk_gt_i32 s9, 0xffea
	s_cselect_b64 s[10:11], -1, 0
	s_cmp_lt_u32 s5, s8
	s_cselect_b64 s[18:19], -1, 0
	s_and_b64 s[10:11], s[10:11], s[18:19]
	s_andn2_b64 vcc, exec, s[10:11]
	s_cbranch_vccnz .LBB0_538
	s_add_u32 s10, s6, s4
	s_addc_u32 s11, s7, 0
	v_lshl_add_u64 v[30:31], v[18:19], 1, s[10:11]
	v_add_co_u32_e32 v30, vcc, 0x4b3f000, v30
	s_nop 1
	v_addc_co_u32_e32 v31, vcc, 0, v31, vcc
	global_load_ushort v28, v[30:31], off offset:3264
.LBB0_538:
	s_add_i32 s5, s9, 22
	s_cmpk_gt_i32 s9, 0xffe9
	s_cselect_b64 s[10:11], -1, 0
	s_cmp_lt_u32 s5, s8
	s_cselect_b64 s[18:19], -1, 0
	s_and_b64 s[10:11], s[10:11], s[18:19]
	v_mov_b32_e32 v30, 0
	s_andn2_b64 vcc, exec, s[10:11]
	v_mov_b32_e32 v31, 0
	s_cbranch_vccnz .LBB0_540
	s_add_u32 s10, s6, s4
	s_addc_u32 s11, s7, 0
	v_lshl_add_u64 v[32:33], v[18:19], 1, s[10:11]
	v_add_co_u32_e32 v32, vcc, 0x4b41000, v32
	s_nop 1
	v_addc_co_u32_e32 v33, vcc, 0, v33, vcc
	global_load_ushort v31, v[32:33], off offset:256
.LBB0_540:
	s_add_i32 s5, s9, 23
	s_cmpk_gt_i32 s9, 0xffe8
	s_cselect_b64 s[10:11], -1, 0
	s_cmp_lt_u32 s5, s8
	s_cselect_b64 s[18:19], -1, 0
	s_and_b64 s[10:11], s[10:11], s[18:19]
	s_andn2_b64 vcc, exec, s[10:11]
	s_cbranch_vccnz .LBB0_542
	s_add_u32 s10, s6, s4
	s_addc_u32 s11, s7, 0
	v_lshl_add_u64 v[32:33], v[18:19], 1, s[10:11]
	v_add_co_u32_e32 v32, vcc, 0x4b42000, v32
	s_nop 1
	v_addc_co_u32_e32 v33, vcc, 0, v33, vcc
	global_load_ushort v30, v[32:33], off offset:1344
.LBB0_542:
	s_add_i32 s5, s9, 24
	s_cmpk_gt_i32 s9, 0xffe7
	s_cselect_b64 s[10:11], -1, 0
	s_cmp_lt_u32 s5, s8
	s_cselect_b64 s[18:19], -1, 0
	s_and_b64 s[10:11], s[10:11], s[18:19]
	v_mov_b32_e32 v32, 0
	s_andn2_b64 vcc, exec, s[10:11]
	v_mov_b32_e32 v33, 0
	s_cbranch_vccnz .LBB0_544
	s_add_u32 s10, s6, s4
	s_addc_u32 s11, s7, 0
	v_lshl_add_u64 v[34:35], v[18:19], 1, s[10:11]
	v_add_co_u32_e32 v34, vcc, 0x4b43000, v34
	s_nop 1
	v_addc_co_u32_e32 v35, vcc, 0, v35, vcc
	global_load_ushort v33, v[34:35], off offset:2432
.LBB0_544:
	s_add_i32 s5, s9, 25
	s_cmpk_gt_i32 s9, 0xffe6
	s_cselect_b64 s[10:11], -1, 0
	s_cmp_lt_u32 s5, s8
	s_cselect_b64 s[18:19], -1, 0
	s_and_b64 s[10:11], s[10:11], s[18:19]
	s_andn2_b64 vcc, exec, s[10:11]
	s_cbranch_vccnz .LBB0_546
	s_add_u32 s10, s6, s4
	s_addc_u32 s11, s7, 0
	v_lshl_add_u64 v[34:35], v[18:19], 1, s[10:11]
	v_add_co_u32_e32 v34, vcc, 0x4b44000, v34
	s_nop 1
	v_addc_co_u32_e32 v35, vcc, 0, v35, vcc
	global_load_ushort v32, v[34:35], off offset:3520
.LBB0_546:
	s_add_i32 s5, s9, 26
	s_cmpk_gt_i32 s9, 0xffe5
	s_cselect_b64 s[10:11], -1, 0
	s_cmp_lt_u32 s5, s8
	s_cselect_b64 s[18:19], -1, 0
	s_and_b64 s[10:11], s[10:11], s[18:19]
	v_mov_b32_e32 v34, 0
	s_andn2_b64 vcc, exec, s[10:11]
	v_mov_b32_e32 v35, 0
	s_cbranch_vccnz .LBB0_548
	s_add_u32 s10, s6, s4
	s_addc_u32 s11, s7, 0
	v_lshl_add_u64 v[36:37], v[18:19], 1, s[10:11]
	v_add_co_u32_e32 v36, vcc, 0x4b46000, v36
	s_nop 1
	v_addc_co_u32_e32 v37, vcc, 0, v37, vcc
	global_load_ushort v35, v[36:37], off offset:512
.LBB0_548:
	s_add_i32 s5, s9, 27
	s_cmpk_gt_i32 s9, 0xffe4
	s_cselect_b64 s[10:11], -1, 0
	s_cmp_lt_u32 s5, s8
	s_cselect_b64 s[18:19], -1, 0
	s_and_b64 s[10:11], s[10:11], s[18:19]
	s_andn2_b64 vcc, exec, s[10:11]
	s_cbranch_vccnz .LBB0_550
	s_add_u32 s10, s6, s4
	s_addc_u32 s11, s7, 0
	v_lshl_add_u64 v[36:37], v[18:19], 1, s[10:11]
	v_add_co_u32_e32 v36, vcc, 0x4b47000, v36
	s_nop 1
	v_addc_co_u32_e32 v37, vcc, 0, v37, vcc
	global_load_ushort v34, v[36:37], off offset:1600
.LBB0_550:
	s_add_i32 s5, s9, 28
	s_cmpk_gt_i32 s9, 0xffe3
	s_cselect_b64 s[10:11], -1, 0
	s_cmp_lt_u32 s5, s8
	s_cselect_b64 s[18:19], -1, 0
	s_and_b64 s[10:11], s[10:11], s[18:19]
	v_mov_b32_e32 v36, 0
	s_andn2_b64 vcc, exec, s[10:11]
	v_mov_b32_e32 v37, 0
	s_cbranch_vccnz .LBB0_552
	s_add_u32 s10, s6, s4
	s_addc_u32 s11, s7, 0
	v_lshl_add_u64 v[38:39], v[18:19], 1, s[10:11]
	v_add_co_u32_e32 v38, vcc, 0x4b48000, v38
	s_nop 1
	v_addc_co_u32_e32 v39, vcc, 0, v39, vcc
	global_load_ushort v37, v[38:39], off offset:2688
.LBB0_552:
	s_add_i32 s5, s9, 29
	s_cmpk_gt_i32 s9, 0xffe2
	s_cselect_b64 s[10:11], -1, 0
	s_cmp_lt_u32 s5, s8
	s_cselect_b64 s[18:19], -1, 0
	s_and_b64 s[10:11], s[10:11], s[18:19]
	s_andn2_b64 vcc, exec, s[10:11]
	s_cbranch_vccnz .LBB0_554
	s_add_u32 s10, s6, s4
	s_addc_u32 s11, s7, 0
	v_lshl_add_u64 v[38:39], v[18:19], 1, s[10:11]
	v_add_co_u32_e32 v38, vcc, 0x4b49000, v38
	s_nop 1
	v_addc_co_u32_e32 v39, vcc, 0, v39, vcc
	global_load_ushort v36, v[38:39], off offset:3776
.LBB0_554:
	s_add_i32 s5, s9, 30
	s_cmpk_gt_i32 s9, 0xffe1
	s_cselect_b64 s[10:11], -1, 0
	s_cmp_lt_u32 s5, s8
	s_cselect_b64 s[18:19], -1, 0
	s_and_b64 s[10:11], s[10:11], s[18:19]
	v_mov_b32_e32 v38, 0
	s_andn2_b64 vcc, exec, s[10:11]
	v_mov_b32_e32 v39, 0
	s_cbranch_vccnz .LBB0_556
	s_add_u32 s10, s6, s4
	s_addc_u32 s11, s7, 0
	v_lshl_add_u64 v[40:41], v[18:19], 1, s[10:11]
	v_add_co_u32_e32 v40, vcc, 0x4b4b000, v40
	s_nop 1
	v_addc_co_u32_e32 v41, vcc, 0, v41, vcc
	global_load_ushort v39, v[40:41], off offset:768
.LBB0_556:
	s_add_i32 s5, s9, 31
	s_cmpk_gt_i32 s9, 0xffe0
	s_cselect_b64 s[10:11], -1, 0
	s_cmp_lt_u32 s5, s8
	s_cselect_b64 s[18:19], -1, 0
	s_and_b64 s[10:11], s[10:11], s[18:19]
	s_andn2_b64 vcc, exec, s[10:11]
	s_cbranch_vccnz .LBB0_558
	s_add_u32 s10, s6, s4
	s_addc_u32 s11, s7, 0
	v_lshl_add_u64 v[40:41], v[18:19], 1, s[10:11]
	v_add_co_u32_e32 v40, vcc, 0x4b4c000, v40
	s_nop 1
	v_addc_co_u32_e32 v41, vcc, 0, v41, vcc
	global_load_ushort v38, v[40:41], off offset:1856
.LBB0_558:
	s_add_i32 s5, s9, 32
	s_cmpk_gt_i32 s9, 0xffdf
	s_cselect_b64 s[10:11], -1, 0
	s_cmp_lt_u32 s5, s8
	s_cselect_b64 s[18:19], -1, 0
	s_and_b64 s[10:11], s[10:11], s[18:19]
	v_mov_b32_e32 v40, 0
	s_andn2_b64 vcc, exec, s[10:11]
	v_mov_b32_e32 v41, 0
	s_cbranch_vccnz .LBB0_560
	s_add_u32 s10, s6, s4
	s_addc_u32 s11, s7, 0
	v_lshl_add_u64 v[42:43], v[18:19], 1, s[10:11]
	v_add_co_u32_e32 v42, vcc, 0x4b4d000, v42
	s_nop 1
	v_addc_co_u32_e32 v43, vcc, 0, v43, vcc
	global_load_ushort v41, v[42:43], off offset:2944
.LBB0_560:
	s_add_i32 s5, s9, 33
	s_cmpk_gt_i32 s9, 0xffde
	s_cselect_b64 s[10:11], -1, 0
	s_cmp_lt_u32 s5, s8
	s_cselect_b64 s[18:19], -1, 0
	s_and_b64 s[10:11], s[10:11], s[18:19]
	s_andn2_b64 vcc, exec, s[10:11]
	s_cbranch_vccnz .LBB0_562
	s_add_u32 s10, s6, s4
	s_addc_u32 s11, s7, 0
	v_lshl_add_u64 v[42:43], v[18:19], 1, s[10:11]
	v_add_co_u32_e32 v42, vcc, 0x4b4e000, v42
	s_nop 1
	v_addc_co_u32_e32 v43, vcc, 0, v43, vcc
	global_load_ushort v40, v[42:43], off offset:4032
.LBB0_562:
	s_add_i32 s5, s9, 34
	s_cmpk_gt_i32 s9, 0xffdd
	s_cselect_b64 s[10:11], -1, 0
	s_cmp_lt_u32 s5, s8
	s_cselect_b64 s[8:9], -1, 0
	s_and_b64 s[8:9], s[10:11], s[8:9]
	s_andn2_b64 vcc, exec, s[8:9]
	v_mov_b32_e32 v42, 0
	s_cbranch_vccnz .LBB0_564
	s_add_u32 s4, s6, s4
	s_addc_u32 s5, s7, 0
	v_lshl_add_u64 v[42:43], v[18:19], 1, s[4:5]
	v_add_co_u32_e32 v42, vcc, 0x4b50000, v42
	s_nop 1
	v_addc_co_u32_e32 v43, vcc, 0, v43, vcc
	global_load_ushort v42, v[42:43], off offset:1024
.LBB0_564:
	s_waitcnt vmcnt(0)
	v_lshlrev_b32_e32 v7, 16, v7
	v_lshlrev_b32_e32 v6, 16, v6
	v_lshlrev_b32_e32 v9, 16, v9
	v_lshlrev_b32_e32 v8, 16, v8
	v_lshlrev_b32_e32 v11, 16, v11
	v_lshlrev_b32_e32 v10, 16, v10
	v_lshlrev_b32_e32 v13, 16, v13
	v_lshlrev_b32_e32 v12, 16, v12
	v_lshlrev_b32_e32 v15, 16, v15
	v_lshlrev_b32_e32 v14, 16, v14
	v_lshlrev_b32_e32 v17, 16, v17
	v_lshlrev_b32_e32 v16, 16, v16
	v_lshlrev_b32_e32 v21, 16, v21
	v_lshlrev_b32_e32 v20, 16, v20
	v_lshlrev_b32_e32 v23, 16, v23
	v_lshlrev_b32_e32 v22, 16, v22
	v_lshlrev_b32_e32 v25, 16, v25
	v_lshlrev_b32_e32 v24, 16, v24
	v_lshlrev_b32_e32 v27, 16, v27
	v_lshlrev_b32_e32 v26, 16, v26
	v_lshlrev_b32_e32 v29, 16, v29
	v_lshlrev_b32_e32 v28, 16, v28
	v_lshlrev_b32_e32 v31, 16, v31
	v_lshlrev_b32_e32 v30, 16, v30
	v_lshlrev_b32_e32 v33, 16, v33
	v_lshlrev_b32_e32 v32, 16, v32
	v_lshlrev_b32_e32 v35, 16, v35
	v_lshlrev_b32_e32 v34, 16, v34
	v_lshlrev_b32_e32 v37, 16, v37
	v_lshlrev_b32_e32 v36, 16, v36
	v_lshlrev_b32_e32 v39, 16, v39
	v_lshlrev_b32_e32 v38, 16, v38
	v_lshlrev_b32_e32 v41, 16, v41
	v_lshlrev_b32_e32 v40, 16, v40
	v_lshlrev_b32_e32 v42, 16, v42
	s_waitcnt vmcnt(3)
	v_mul_f32_e32 v46, v4, v6
	v_fmac_f32_e32 v46, v2, v7
	s_waitcnt vmcnt(2)
	v_fmac_f32_e32 v46, v3, v9
	s_waitcnt vmcnt(1)
	v_fmac_f32_e32 v46, v0, v8
	s_waitcnt vmcnt(0)
	v_add_f32_e32 v7, v5, v46
	v_lshlrev_b32_e32 v46, 1, v18
	v_cvt_pk_bf16_f32 v7, v7, s0
	v_add_u32_e32 v82, 0, v46
	ds_write_b16 v82, v7
	v_mul_f32_e32 v7, v4, v9
	v_fmac_f32_e32 v7, v2, v6
	v_fmac_f32_e32 v7, v3, v8
	v_fmac_f32_e32 v7, v0, v11
	v_add_f32_e32 v6, v5, v7
	v_xor_b32_e32 v7, 8, v18
	v_cvt_pk_bf16_f32 v6, v6, s0
	v_lshl_add_u32 v7, v7, 1, 0
	ds_write_b16 v7, v6 offset:512
	v_mul_f32_e32 v6, v4, v8
	v_fmac_f32_e32 v6, v2, v9
	v_fmac_f32_e32 v6, v3, v11
	v_fmac_f32_e32 v6, v0, v10
	v_add_f32_e32 v6, v5, v6
	v_xor_b32_e32 v9, 16, v18
	v_cvt_pk_bf16_f32 v6, v6, s0
	v_lshl_add_u32 v9, v9, 1, 0
	ds_write_b16 v9, v6 offset:1024
	v_mul_f32_e32 v6, v4, v11
	v_fmac_f32_e32 v6, v2, v8
	v_fmac_f32_e32 v6, v3, v10
	v_fmac_f32_e32 v6, v0, v13
	v_add_f32_e32 v6, v5, v6
	v_xor_b32_e32 v8, 24, v18
	v_cvt_pk_bf16_f32 v6, v6, s0
	v_lshl_add_u32 v8, v8, 1, 0
	ds_write_b16 v8, v6 offset:1536
	v_mul_f32_e32 v6, v4, v10
	v_fmac_f32_e32 v6, v2, v11
	v_fmac_f32_e32 v6, v3, v13
	v_fmac_f32_e32 v6, v0, v12
	v_add_f32_e32 v6, v5, v6
	v_xor_b32_e32 v11, 32, v18
	v_cvt_pk_bf16_f32 v6, v6, s0
	v_lshl_add_u32 v11, v11, 1, 0
	ds_write_b16 v11, v6 offset:2048
	v_mul_f32_e32 v6, v4, v13
	v_fmac_f32_e32 v6, v2, v10
	v_fmac_f32_e32 v6, v3, v12
	v_fmac_f32_e32 v6, v0, v15
	v_add_f32_e32 v6, v5, v6
	v_xor_b32_e32 v10, 40, v18
	v_cvt_pk_bf16_f32 v6, v6, s0
	v_lshl_add_u32 v10, v10, 1, 0
	ds_write_b16 v10, v6 offset:2560
	v_mul_f32_e32 v6, v4, v12
	v_fmac_f32_e32 v6, v2, v13
	v_fmac_f32_e32 v6, v3, v15
	v_fmac_f32_e32 v6, v0, v14
	v_add_f32_e32 v6, v5, v6
	v_xor_b32_e32 v13, 48, v18
	v_cvt_pk_bf16_f32 v6, v6, s0
	v_lshl_add_u32 v13, v13, 1, 0
	ds_write_b16 v13, v6 offset:3072
	v_mul_f32_e32 v6, v4, v15
	v_fmac_f32_e32 v6, v2, v12
	v_fmac_f32_e32 v6, v3, v14
	v_fmac_f32_e32 v6, v0, v17
	v_add_f32_e32 v6, v5, v6
	v_xor_b32_e32 v12, 56, v18
	v_cvt_pk_bf16_f32 v6, v6, s0
	v_lshl_add_u32 v12, v12, 1, 0
	ds_write_b16 v12, v6 offset:3584
	v_mul_f32_e32 v6, v4, v14
	v_fmac_f32_e32 v6, v2, v15
	v_fmac_f32_e32 v6, v3, v17
	v_fmac_f32_e32 v6, v0, v16
	v_add_f32_e32 v6, v5, v6
	v_cvt_pk_bf16_f32 v6, v6, s0
	ds_write_b16 v82, v6 offset:4096
	v_mul_f32_e32 v6, v4, v17
	v_fmac_f32_e32 v6, v2, v14
	v_fmac_f32_e32 v6, v3, v16
	v_fmac_f32_e32 v6, v0, v21
	v_add_f32_e32 v6, v5, v6
	v_cvt_pk_bf16_f32 v6, v6, s0
	ds_write_b16 v7, v6 offset:4608
	v_mul_f32_e32 v6, v4, v16
	v_fmac_f32_e32 v6, v2, v17
	v_fmac_f32_e32 v6, v3, v21
	v_fmac_f32_e32 v6, v0, v20
	v_add_f32_e32 v6, v5, v6
	v_cvt_pk_bf16_f32 v6, v6, s0
	ds_write_b16 v9, v6 offset:5120
	v_mul_f32_e32 v6, v4, v21
	v_fmac_f32_e32 v6, v2, v16
	v_fmac_f32_e32 v6, v3, v20
	v_fmac_f32_e32 v6, v0, v23
	v_add_f32_e32 v6, v5, v6
	v_cvt_pk_bf16_f32 v6, v6, s0
	ds_write_b16 v8, v6 offset:5632
	v_mul_f32_e32 v6, v4, v20
	v_fmac_f32_e32 v6, v2, v21
	v_fmac_f32_e32 v6, v3, v23
	v_fmac_f32_e32 v6, v0, v22
	v_add_f32_e32 v6, v5, v6
	v_cvt_pk_bf16_f32 v6, v6, s0
	ds_write_b16 v11, v6 offset:6144
	v_mul_f32_e32 v6, v4, v23
	v_fmac_f32_e32 v6, v2, v20
	v_fmac_f32_e32 v6, v3, v22
	v_fmac_f32_e32 v6, v0, v25
	v_add_f32_e32 v6, v5, v6
	v_cvt_pk_bf16_f32 v6, v6, s0
	ds_write_b16 v10, v6 offset:6656
	v_mul_f32_e32 v6, v4, v22
	v_fmac_f32_e32 v6, v2, v23
	v_fmac_f32_e32 v6, v3, v25
	v_fmac_f32_e32 v6, v0, v24
	v_add_f32_e32 v6, v5, v6
	v_cvt_pk_bf16_f32 v6, v6, s0
	ds_write_b16 v13, v6 offset:7168
	v_mul_f32_e32 v6, v4, v25
	v_fmac_f32_e32 v6, v2, v22
	v_fmac_f32_e32 v6, v3, v24
	v_fmac_f32_e32 v6, v0, v27
	v_add_f32_e32 v6, v5, v6
	v_cvt_pk_bf16_f32 v6, v6, s0
	ds_write_b16 v12, v6 offset:7680
	v_mul_f32_e32 v6, v4, v24
	v_fmac_f32_e32 v6, v2, v25
	v_fmac_f32_e32 v6, v3, v27
	v_fmac_f32_e32 v6, v0, v26
	v_add_f32_e32 v6, v5, v6
	v_cvt_pk_bf16_f32 v6, v6, s0
	ds_write_b16 v82, v6 offset:8192
	v_mul_f32_e32 v6, v4, v27
	v_fmac_f32_e32 v6, v2, v24
	v_fmac_f32_e32 v6, v3, v26
	v_fmac_f32_e32 v6, v0, v29
	v_add_f32_e32 v6, v5, v6
	v_cvt_pk_bf16_f32 v6, v6, s0
	ds_write_b16 v7, v6 offset:8704
	v_mul_f32_e32 v6, v4, v26
	v_fmac_f32_e32 v6, v2, v27
	v_fmac_f32_e32 v6, v3, v29
	v_fmac_f32_e32 v6, v0, v28
	v_add_f32_e32 v6, v5, v6
	v_cvt_pk_bf16_f32 v6, v6, s0
	ds_write_b16 v9, v6 offset:9216
	v_mul_f32_e32 v6, v4, v29
	v_fmac_f32_e32 v6, v2, v26
	v_fmac_f32_e32 v6, v3, v28
	v_fmac_f32_e32 v6, v0, v31
	v_add_f32_e32 v6, v5, v6
	v_cvt_pk_bf16_f32 v6, v6, s0
	ds_write_b16 v8, v6 offset:9728
	v_mul_f32_e32 v6, v4, v28
	v_fmac_f32_e32 v6, v2, v29
	v_fmac_f32_e32 v6, v3, v31
	v_fmac_f32_e32 v6, v0, v30
	v_add_f32_e32 v6, v5, v6
	v_cvt_pk_bf16_f32 v6, v6, s0
	ds_write_b16 v11, v6 offset:10240
	v_mul_f32_e32 v6, v4, v31
	v_fmac_f32_e32 v6, v2, v28
	v_fmac_f32_e32 v6, v3, v30
	v_fmac_f32_e32 v6, v0, v33
	v_add_f32_e32 v6, v5, v6
	v_cvt_pk_bf16_f32 v6, v6, s0
	ds_write_b16 v10, v6 offset:10752
	v_mul_f32_e32 v6, v4, v30
	v_fmac_f32_e32 v6, v2, v31
	v_fmac_f32_e32 v6, v3, v33
	v_fmac_f32_e32 v6, v0, v32
	v_add_f32_e32 v6, v5, v6
	v_cvt_pk_bf16_f32 v6, v6, s0
	ds_write_b16 v13, v6 offset:11264
	v_mul_f32_e32 v6, v4, v33
	v_fmac_f32_e32 v6, v2, v30
	v_fmac_f32_e32 v6, v3, v32
	v_fmac_f32_e32 v6, v0, v35
	v_add_f32_e32 v6, v5, v6
	v_cvt_pk_bf16_f32 v6, v6, s0
	ds_write_b16 v12, v6 offset:11776
	v_mul_f32_e32 v6, v4, v32
	v_fmac_f32_e32 v6, v2, v33
	v_fmac_f32_e32 v6, v3, v35
	v_fmac_f32_e32 v6, v0, v34
	v_add_f32_e32 v6, v5, v6
	v_cvt_pk_bf16_f32 v6, v6, s0
	ds_write_b16 v82, v6 offset:12288
	v_mul_f32_e32 v6, v4, v35
	v_fmac_f32_e32 v6, v2, v32
	v_fmac_f32_e32 v6, v3, v34
	v_fmac_f32_e32 v6, v0, v37
	v_add_f32_e32 v6, v5, v6
	v_cvt_pk_bf16_f32 v6, v6, s0
	ds_write_b16 v7, v6 offset:12800
	v_mul_f32_e32 v6, v4, v34
	v_fmac_f32_e32 v6, v2, v35
	v_fmac_f32_e32 v6, v3, v37
	v_fmac_f32_e32 v6, v0, v36
	v_add_f32_e32 v6, v5, v6
	v_cvt_pk_bf16_f32 v6, v6, s0
	ds_write_b16 v9, v6 offset:13312
	v_mul_f32_e32 v6, v4, v37
	v_fmac_f32_e32 v6, v2, v34
	v_fmac_f32_e32 v6, v3, v36
	v_fmac_f32_e32 v6, v0, v39
	v_add_f32_e32 v6, v5, v6
	v_cvt_pk_bf16_f32 v6, v6, s0
	ds_write_b16 v8, v6 offset:13824
	v_mul_f32_e32 v6, v4, v36
	v_fmac_f32_e32 v6, v2, v37
	v_fmac_f32_e32 v6, v3, v39
	v_fmac_f32_e32 v6, v0, v38
	v_add_f32_e32 v6, v5, v6
	v_cvt_pk_bf16_f32 v6, v6, s0
	ds_write_b16 v11, v6 offset:14336
	v_mul_f32_e32 v6, v4, v39
	v_fmac_f32_e32 v6, v2, v36
	v_fmac_f32_e32 v6, v3, v38
	v_fmac_f32_e32 v6, v0, v41
	v_add_f32_e32 v6, v5, v6
	v_cvt_pk_bf16_f32 v6, v6, s0
	ds_write_b16 v10, v6 offset:14848
	v_mul_f32_e32 v6, v4, v38
	v_mul_f32_e32 v4, v4, v41
	v_fmac_f32_e32 v6, v2, v39
	v_fmac_f32_e32 v4, v2, v38
	v_fmac_f32_e32 v6, v3, v41
	v_fmac_f32_e32 v4, v3, v40
	v_fmac_f32_e32 v6, v0, v40
	v_fmac_f32_e32 v4, v0, v42
	v_add_f32_e32 v6, v5, v6
	v_add_f32_e32 v0, v5, v4
	v_bfe_u32 v45, v18, 4, 2
	v_cvt_pk_bf16_f32 v6, v6, s0
	v_cvt_pk_bf16_f32 v0, v0, s0
	ds_write_b16 v13, v6 offset:15360
	ds_write_b16 v12, v0 offset:15872
	v_and_b32_e32 v0, 0xffffffc0, v18
	v_lshlrev_b32_e32 v2, 3, v45
	v_lshlrev_b32_e32 v4, 3, v18
	v_and_b32_e32 v43, 15, v18
	v_or_b32_e32 v3, v2, v0
	v_and_b32_e32 v4, 56, v4
	v_lshl_add_u32 v5, v43, 9, 0
	v_bitop3_b32 v0, v2, v4, v0 bitop3:0x36
	v_bitop3_b32 v2, v3, v4, 32 bitop3:0x36
	v_lshl_add_u32 v0, v0, 1, v5
	v_lshl_add_u32 v14, v2, 1, v5
	v_and_b32_e32 v44, 63, v18
	s_waitcnt lgkmcnt(0)
	s_barrier
	ds_read_b128 v[2:5], v0
	ds_read_b128 v[6:9], v0 offset:8192
	ds_read_b128 v[10:13], v14
	ds_read_b128 v[14:17], v14 offset:8192
	v_ashrrev_i32_e32 v0, 4, v18
	v_and_b32_e32 v83, -4, v0
	v_lshlrev_b32_e32 v0, 4, v44
	v_lshl_add_u64 v[20:21], s[6:7], 0, v[0:1]
	s_mov_b64 s[4:5], 0x527800
	v_lshl_add_u64 v[58:59], v[20:21], 0, s[4:5]
	v_lshl_add_u64 v[20:21], v[18:19], 2, s[6:7]
	s_mov_b64 s[6:7], 0x27800
	v_and_b32_e32 v0, 0xffffffcf, v18
	v_lshl_add_u64 v[60:61], v[20:21], 0, s[6:7]
	v_and_b32_e32 v20, 32, v46
	v_lshlrev_b32_e32 v19, 10, v45
	v_lshl_add_u32 v20, v20, 1, 0
	v_lshlrev_b32_e32 v21, 1, v0
	v_lshlrev_b32_e32 v23, 11, v45
	v_lshlrev_b32_e32 v22, 2, v45
	v_add3_u32 v84, v20, v21, v23
	v_add_u32_e32 v20, v19, v0
	v_lshl_add_u32 v85, v20, 1, 0
	v_or_b32_e32 v20, 1, v22
	v_lshlrev_b32_e32 v25, 3, v20
	v_bitop3_b32 v26, v25, v0, 40 bitop3:0x6c
	v_lshlrev_b32_e32 v24, 8, v20
	v_lshlrev_b32_e32 v26, 1, v26
	v_lshlrev_b32_e32 v20, 9, v20
	v_add3_u32 v86, 0, v26, v20
	v_add_u32_e32 v26, v24, v0
	v_lshl_add_u32 v87, v26, 1, 0
	v_or_b32_e32 v26, 2, v22
	v_lshlrev_b32_e32 v28, 3, v26
	v_and_b32_e32 v29, 48, v28
	v_lshlrev_b32_e32 v27, 8, v26
	v_lshlrev_b32_e32 v29, 1, v29
	v_add3_u32 v21, 0, v29, v21
	v_add_u32_e32 v29, v27, v0
	v_lshl_add_u32 v89, v29, 1, 0
	v_or_b32_e32 v29, 3, v22
	v_lshlrev_b32_e32 v31, 3, v29
	v_bitop3_b32 v32, v31, v0, 56 bitop3:0x6c
	v_lshlrev_b32_e32 v30, 8, v29
	v_lshlrev_b32_e32 v32, 1, v32
	v_lshlrev_b32_e32 v29, 9, v29
	v_add3_u32 v90, 0, v32, v29
	v_add_u32_e32 v32, v30, v0
	v_lshl_add_u32 v91, v32, 1, 0
	v_or_b32_e32 v32, 17, v22
	v_lshlrev_b32_e32 v34, 3, v32
	v_bitop3_b32 v35, v34, v0, 40 bitop3:0x6c
	v_lshlrev_b32_e32 v33, 8, v32
	v_lshlrev_b32_e32 v35, 1, v35
	v_lshlrev_b32_e32 v32, 9, v32
	v_add3_u32 v92, 0, v35, v32
	v_add_u32_e32 v35, v33, v0
	v_lshl_add_u32 v93, v35, 1, 0
	v_or_b32_e32 v35, 18, v22
	v_lshlrev_b32_e32 v26, 9, v26
	v_lshlrev_b32_e32 v36, 8, v35
	v_lshlrev_b32_e32 v37, 3, v35
	v_lshlrev_b32_e32 v35, 9, v35
	v_add_u32_e32 v88, v21, v26
	v_add_u32_e32 v94, v21, v35
	v_add_u32_e32 v21, v36, v0
	v_lshl_add_u32 v95, v21, 1, 0
	v_or_b32_e32 v21, 19, v22
	v_lshlrev_b32_e32 v38, 3, v21
	v_bitop3_b32 v39, v38, v0, 56 bitop3:0x6c
	v_lshlrev_b32_e32 v22, 8, v21
	v_lshlrev_b32_e32 v39, 1, v39
	v_lshlrev_b32_e32 v21, 9, v21
	v_add3_u32 v96, 0, v39, v21
	v_add_u32_e32 v39, v22, v0
	v_lshl_add_u32 v97, v39, 1, 0
	v_or_b32_e32 v39, 16, v0
	v_bitop3_b32 v40, v25, v39, 40 bitop3:0x6c
	v_lshlrev_b32_e32 v40, 1, v40
	v_add3_u32 v98, 0, v40, v20
	v_bitop3_b32 v40, v28, v39, 48 bitop3:0x6c
	v_lshlrev_b32_e32 v40, 1, v40
	v_add3_u32 v99, 0, v40, v26
	v_bitop3_b32 v40, v31, v39, 56 bitop3:0x6c
	v_lshlrev_b32_e32 v40, 1, v40
	v_add3_u32 v100, 0, v40, v29
	v_add_u32_e32 v40, v19, v39
	v_lshl_add_u32 v101, v40, 1, 0
	v_bitop3_b32 v40, v34, v39, 40 bitop3:0x6c
	v_lshlrev_b32_e32 v40, 1, v40
	v_add3_u32 v102, 0, v40, v32
	v_bitop3_b32 v40, v37, v39, 48 bitop3:0x6c
	v_lshlrev_b32_e32 v40, 1, v40
	v_bitop3_b32 v39, v38, v39, 56 bitop3:0x6c
	v_add3_u32 v103, 0, v40, v35
	v_lshlrev_b32_e32 v39, 1, v39
	v_bitop3_b32 v40, v46, v0, 32 bitop3:0x4e
	v_add3_u32 v104, 0, v39, v21
	v_or_b32_e32 v39, 32, v0
	v_lshlrev_b32_e32 v40, 1, v40
	v_add3_u32 v105, 0, v40, v23
	v_bitop3_b32 v40, v25, v39, 40 bitop3:0x6c
	v_lshlrev_b32_e32 v40, 1, v40
	v_add3_u32 v106, 0, v40, v20
	v_bitop3_b32 v40, v28, v39, 48 bitop3:0x6c
	v_lshlrev_b32_e32 v40, 1, v40
	v_add3_u32 v107, 0, v40, v26
	v_bitop3_b32 v40, v31, v39, 56 bitop3:0x6c
	v_lshlrev_b32_e32 v40, 1, v40
	v_or_b32_e32 v113, 48, v18
	v_add3_u32 v108, 0, v40, v29
	v_add_u32_e32 v40, v19, v39
	v_add_u32_e32 v19, v19, v113
	v_lshl_add_u32 v115, v19, 1, 0
	v_bitop3_b32 v19, v25, v113, 40 bitop3:0x6c
	v_lshlrev_b32_e32 v19, 1, v19
	v_add3_u32 v116, 0, v19, v20
	v_add_u32_e32 v19, v24, v113
	v_lshl_add_u32 v117, v19, 1, 0
	v_bitop3_b32 v19, v28, v18, 48 bitop3:0x4e
	v_lshlrev_b32_e32 v19, 1, v19
	v_add3_u32 v118, 0, v19, v26
	v_add_u32_e32 v19, v27, v113
	v_lshl_add_u32 v109, v40, 1, 0
	v_bitop3_b32 v40, v34, v39, 40 bitop3:0x6c
	v_lshl_add_u32 v119, v19, 1, 0
	v_bitop3_b32 v19, v31, v113, 56 bitop3:0x6c
	v_bitop3_b32 v18, v37, v18, 48 bitop3:0x4e
	v_lshlrev_b32_e32 v40, 1, v40
	v_lshlrev_b32_e32 v19, 1, v19
	v_lshlrev_b32_e32 v18, 1, v18
	s_load_dwordx2 s[4:5], s[0:1], 0xa8
	s_load_dwordx4 s[8:11], s[0:1], 0xb8
	v_add3_u32 v110, 0, v40, v32
	v_bitop3_b32 v40, v37, v39, 48 bitop3:0x6c
	v_bitop3_b32 v39, v38, v39, 56 bitop3:0x6c
	v_add3_u32 v120, 0, v19, v29
	v_add_u32_e32 v19, v30, v113
	v_add3_u32 v124, 0, v18, v35
	v_add_u32_e32 v18, v36, v113
	v_lshlrev_b32_e32 v39, 1, v39
	v_lshl_add_u32 v121, v19, 1, 0
	v_bitop3_b32 v19, v34, v113, 40 bitop3:0x6c
	v_lshl_add_u32 v125, v18, 1, 0
	v_bitop3_b32 v18, v38, v113, 56 bitop3:0x6c
	v_add3_u32 v112, 0, v39, v21
	v_bitop3_b32 v39, v46, v113, 32 bitop3:0x6c
	v_lshlrev_b32_e32 v19, 1, v19
	v_lshlrev_b32_e32 v18, 1, v18
	v_lshlrev_b32_e32 v40, 1, v40
	v_lshlrev_b32_e32 v39, 1, v39
	v_add3_u32 v122, 0, v19, v32
	v_add_u32_e32 v19, v33, v113
	v_add3_u32 v126, 0, v18, v21
	v_add_u32_e32 v18, v22, v113
	s_lshl_b32 s3, s3, 10
	v_add3_u32 v111, 0, v40, v35
	v_add3_u32 v114, 0, v39, v23
	v_lshl_add_u32 v123, v19, 1, 0
	v_lshl_add_u32 v127, v18, 1, 0
	s_mov_b32 s17, 0
	s_mov_b64 s[18:19], -1

.LBB0_569:
	s_lshl_b32 s4, s16, 4
	s_and_b32 s3, s16, 3
	s_and_b32 s53, s4, 0xffffffc0
	s_cmpk_gt_i32 s53, 0x1fff
	s_movk_i32 s5, 0x100
	s_cselect_b32 s17, 0x1000, s5
	s_movk_i32 s5, 0xff00
	s_cselect_b32 s5, 0xfffff000, s5
	s_waitcnt vmcnt(0)
	v_mov_b32_e32 v47, v133
	s_and_b32 s43, s5, s4
	s_load_dwordx2 s[4:5], s[0:1], 0x130
	s_load_dwordx2 s[6:7], s[0:1], 0xc8
	s_add_i32 s18, s53, -2
	s_sub_i32 s10, s18, s43
	v_and_b32_e32 v46, 63, v47
	s_waitcnt lgkmcnt(0)
	s_add_u32 s8, s4, 0x4b27800
	s_addc_u32 s9, s5, 0
	s_mul_i32 s11, s62, 0x3000
	s_add_u32 s6, s6, s11
	s_mul_hi_i32 s11, s62, 0x3000
	v_lshl_or_b32 v50, s3, 6, v46
	s_addc_u32 s7, s7, s11
	v_lshlrev_b32_e32 v0, 2, v50
	v_lshl_add_u64 v[2:3], s[6:7], 0, v[0:1]
	v_add_co_u32_e32 v4, vcc, s69, v2
	v_ashrrev_i32_e32 v49, 6, v47
	s_nop 0
	v_addc_co_u32_e32 v5, vcc, 0, v3, vcc
	v_add_co_u32_e32 v10, vcc, 0x2000, v2
	v_lshlrev_b32_e32 v48, 4, v49
	s_nop 0
	v_addc_co_u32_e32 v11, vcc, 0, v3, vcc
	global_load_dword v6, v0, s[6:7]
	global_load_dword v7, v0, s[6:7] offset:3072
	global_load_dword v8, v[4:5], off offset:2048
	global_load_dword v9, v[10:11], off offset:1024
	v_add_u32_e32 v4, s10, v48
	v_lshlrev_b32_e32 v0, 1, v50
	v_cmp_lt_i32_e32 vcc, -1, v4
	v_cmp_gt_i32_e64 s[6:7], s17, v4
	v_lshl_add_u64 v[44:45], s[8:9], 0, v[0:1]
	s_and_b64 s[10:11], vcc, s[6:7]
	v_mov_b32_e32 v43, 0
	v_add_u32_e32 v51, s18, v48
	v_mov_b32_e32 v42, 0
	s_and_saveexec_b64 s[6:7], s[10:11]
	s_cbranch_execz .LBB0_571
	v_mad_i64_i32 v[10:11], s[18:19], v51, s33, v[44:45]
	global_load_ushort v42, v[10:11], off offset:2048
.LBB0_571:
	s_or_b64 exec, exec, s[6:7]
	v_or_b32_e32 v0, 1, v4
	v_cmp_gt_i32_e64 s[6:7], s17, v0
	s_and_b64 s[18:19], vcc, s[6:7]
	v_add_u32_e32 v52, s43, v0
	s_and_saveexec_b64 s[6:7], s[18:19]
	s_cbranch_execz .LBB0_573
	v_mad_i64_i32 v[10:11], s[20:21], v52, s33, v[44:45]
	global_load_ushort v43, v[10:11], off offset:2048
.LBB0_573:
	s_or_b64 exec, exec, s[6:7]
	v_add_u32_e32 v0, 2, v4
	v_cmp_lt_i32_e32 vcc, -3, v4
	v_cmp_gt_i32_e64 s[6:7], s17, v0
	s_and_b64 s[20:21], vcc, s[6:7]
	v_mov_b32_e32 v41, 0
	v_add_u32_e32 v53, s43, v0
	v_mov_b32_e32 v40, 0
	s_and_saveexec_b64 s[6:7], s[20:21]
	s_cbranch_execz .LBB0_575
	v_mad_i64_i32 v[10:11], s[22:23], v53, s33, v[44:45]
	global_load_ushort v40, v[10:11], off offset:2048
.LBB0_575:
	s_or_b64 exec, exec, s[6:7]
	v_add_u32_e32 v0, 3, v4
	v_cmp_lt_i32_e32 vcc, -4, v4
	v_cmp_gt_i32_e64 s[6:7], s17, v0
	s_and_b64 s[22:23], vcc, s[6:7]
	v_add_u32_e32 v54, s43, v0
	s_and_saveexec_b64 s[6:7], s[22:23]
	s_cbranch_execz .LBB0_577
	v_mad_i64_i32 v[10:11], s[24:25], v54, s33, v[44:45]
	global_load_ushort v41, v[10:11], off offset:2048
.LBB0_577:
	s_or_b64 exec, exec, s[6:7]
	v_add_u32_e32 v0, 4, v4
	v_cmp_lt_i32_e32 vcc, -5, v4
	v_cmp_gt_i32_e64 s[6:7], s17, v0
	s_and_b64 s[24:25], vcc, s[6:7]
	v_mov_b32_e32 v37, 0
	v_add_u32_e32 v55, s43, v0
	v_mov_b32_e32 v39, 0
	s_and_saveexec_b64 s[6:7], s[24:25]
	s_cbranch_execz .LBB0_579
	v_mad_i64_i32 v[10:11], s[26:27], v55, s33, v[44:45]
	global_load_ushort v39, v[10:11], off offset:2048
.LBB0_579:
	s_or_b64 exec, exec, s[6:7]
	v_add_u32_e32 v0, 5, v4
	v_cmp_lt_i32_e32 vcc, -6, v4
	v_cmp_gt_i32_e64 s[6:7], s17, v0
	s_and_b64 s[26:27], vcc, s[6:7]
	v_add_u32_e32 v56, s43, v0
	s_and_saveexec_b64 s[6:7], s[26:27]
	s_cbranch_execz .LBB0_581
	v_mad_i64_i32 v[10:11], s[28:29], v56, s33, v[44:45]
	global_load_ushort v37, v[10:11], off offset:2048
.LBB0_581:
	s_or_b64 exec, exec, s[6:7]
	v_add_u32_e32 v0, 6, v4
	v_cmp_lt_i32_e32 vcc, -7, v4
	v_cmp_gt_i32_e64 s[6:7], s17, v0
	s_and_b64 s[28:29], vcc, s[6:7]
	v_mov_b32_e32 v33, 0
	v_add_u32_e32 v57, s43, v0
	v_mov_b32_e32 v35, 0
	s_and_saveexec_b64 s[6:7], s[28:29]
	s_cbranch_execz .LBB0_583
	v_mad_i64_i32 v[10:11], s[30:31], v57, s33, v[44:45]
	global_load_ushort v35, v[10:11], off offset:2048
.LBB0_583:
	s_or_b64 exec, exec, s[6:7]
	v_add_u32_e32 v0, 7, v4
	v_cmp_lt_i32_e32 vcc, -8, v4
	v_cmp_gt_i32_e64 s[6:7], s17, v0
	s_and_b64 s[30:31], vcc, s[6:7]
	v_add_u32_e32 v58, s43, v0
	s_and_saveexec_b64 s[6:7], s[30:31]
	s_cbranch_execz .LBB0_585
	v_mad_i64_i32 v[10:11], s[34:35], v58, s33, v[44:45]
	global_load_ushort v33, v[10:11], off offset:2048
.LBB0_585:
	s_or_b64 exec, exec, s[6:7]
	v_add_u32_e32 v0, 8, v4
	v_cmp_lt_i32_e32 vcc, -9, v4
	v_cmp_gt_i32_e64 s[6:7], s17, v0
	s_and_b64 s[34:35], vcc, s[6:7]
	v_mov_b32_e32 v29, 0
	v_add_u32_e32 v59, s43, v0
	v_mov_b32_e32 v31, 0
	s_and_saveexec_b64 s[6:7], s[34:35]
	s_cbranch_execz .LBB0_587
	v_mad_i64_i32 v[10:11], s[36:37], v59, s33, v[44:45]
	global_load_ushort v31, v[10:11], off offset:2048
.LBB0_587:
	s_or_b64 exec, exec, s[6:7]
	v_add_u32_e32 v0, 9, v4
	v_cmp_lt_i32_e32 vcc, -10, v4
	v_cmp_gt_i32_e64 s[6:7], s17, v0
	s_and_b64 s[36:37], vcc, s[6:7]
	v_add_u32_e32 v60, s43, v0
	s_and_saveexec_b64 s[6:7], s[36:37]
	s_cbranch_execz .LBB0_589
	v_mad_i64_i32 v[10:11], s[38:39], v60, s33, v[44:45]
	global_load_ushort v29, v[10:11], off offset:2048
.LBB0_589:
	s_or_b64 exec, exec, s[6:7]
	v_add_u32_e32 v0, 10, v4
	v_cmp_lt_i32_e32 vcc, -11, v4
	v_cmp_gt_i32_e64 s[6:7], s17, v0
	s_and_b64 s[38:39], vcc, s[6:7]
	v_mov_b32_e32 v25, 0
	v_add_u32_e32 v61, s43, v0
	v_mov_b32_e32 v27, 0
	s_and_saveexec_b64 s[6:7], s[38:39]
	s_cbranch_execz .LBB0_591
	v_mad_i64_i32 v[10:11], s[44:45], v61, s33, v[44:45]
	global_load_ushort v27, v[10:11], off offset:2048
.LBB0_591:
	s_or_b64 exec, exec, s[6:7]
	v_add_u32_e32 v0, 11, v4
	v_cmp_lt_i32_e32 vcc, -12, v4
	v_cmp_gt_i32_e64 s[6:7], s17, v0
	s_and_b64 s[44:45], vcc, s[6:7]
	v_add_u32_e32 v62, s43, v0
	s_and_saveexec_b64 s[6:7], s[44:45]
	s_cbranch_execz .LBB0_593
	v_mad_i64_i32 v[10:11], s[48:49], v62, s33, v[44:45]
	global_load_ushort v25, v[10:11], off offset:2048
.LBB0_593:
	s_or_b64 exec, exec, s[6:7]
	v_add_u32_e32 v0, 12, v4
	v_cmp_lt_i32_e32 vcc, -13, v4
	v_cmp_gt_i32_e64 s[6:7], s17, v0
	s_and_b64 s[48:49], vcc, s[6:7]
	v_mov_b32_e32 v21, 0
	v_add_u32_e32 v63, s43, v0
	v_mov_b32_e32 v23, 0
	s_and_saveexec_b64 s[6:7], s[48:49]
	s_cbranch_execz .LBB0_595
	v_mad_i64_i32 v[10:11], s[50:51], v63, s33, v[44:45]
	global_load_ushort v23, v[10:11], off offset:2048
.LBB0_595:
	s_or_b64 exec, exec, s[6:7]
	v_add_u32_e32 v0, 13, v4
	v_cmp_lt_i32_e32 vcc, -14, v4
	v_cmp_gt_i32_e64 s[6:7], s17, v0
	s_and_b64 s[50:51], vcc, s[6:7]
	v_add_u32_e32 v64, s43, v0
	s_and_saveexec_b64 s[6:7], s[50:51]
	s_cbranch_execz .LBB0_597
	v_mad_i64_i32 v[10:11], s[56:57], v64, s33, v[44:45]
	global_load_ushort v21, v[10:11], off offset:2048
.LBB0_597:
	s_or_b64 exec, exec, s[6:7]
	v_add_u32_e32 v0, 14, v4
	v_cmp_lt_i32_e32 vcc, -15, v4
	v_cmp_gt_i32_e64 s[6:7], s17, v0
	s_and_b64 s[56:57], vcc, s[6:7]
	v_mov_b32_e32 v11, 0
	v_add_u32_e32 v65, s43, v0
	v_mov_b32_e32 v13, 0
	s_and_saveexec_b64 s[6:7], s[56:57]
	s_cbranch_execz .LBB0_599
	v_mad_i64_i32 v[12:13], s[58:59], v65, s33, v[44:45]
	global_load_ushort v13, v[12:13], off offset:2048
.LBB0_599:
	s_or_b64 exec, exec, s[6:7]
	v_add_u32_e32 v0, 15, v4
	v_cmp_lt_i32_e32 vcc, -16, v4
	v_cmp_gt_i32_e64 s[6:7], s17, v0
	s_and_b64 s[58:59], vcc, s[6:7]
	v_add_u32_e32 v66, s43, v0
	s_and_saveexec_b64 s[6:7], s[58:59]
	s_cbranch_execz .LBB0_601
	v_mad_i64_i32 v[10:11], s[60:61], v66, s33, v[44:45]
	global_load_ushort v11, v[10:11], off offset:2048
.LBB0_601:
	s_or_b64 exec, exec, s[6:7]
	v_add_u32_e32 v0, 16, v4
	s_movk_i32 s6, 0xffef
	v_cmp_lt_i32_e32 vcc, s6, v4
	v_cmp_gt_i32_e64 s[6:7], s17, v0
	s_and_b64 s[60:61], vcc, s[6:7]
	v_mov_b32_e32 v15, 0
	v_add_u32_e32 v67, s43, v0
	v_mov_b32_e32 v17, 0
	s_and_saveexec_b64 s[6:7], s[60:61]
	s_cbranch_execz .LBB0_603
	v_mad_i64_i32 v[16:17], s[64:65], v67, s33, v[44:45]
	global_load_ushort v17, v[16:17], off offset:2048
.LBB0_603:
	s_or_b64 exec, exec, s[6:7]
	v_add_u32_e32 v0, 17, v4
	s_movk_i32 s6, 0xffee
	v_cmp_lt_i32_e32 vcc, s6, v4
	v_cmp_gt_i32_e64 s[6:7], s17, v0
	s_and_b64 s[70:71], vcc, s[6:7]
	v_add_u32_e32 v68, s43, v0
	s_and_saveexec_b64 s[6:7], s[70:71]
	s_cbranch_execz .LBB0_605
	v_mad_i64_i32 v[14:15], s[64:65], v68, s33, v[44:45]
	global_load_ushort v15, v[14:15], off offset:2048
.LBB0_605:
	s_or_b64 exec, exec, s[6:7]
	v_add_u32_e32 v0, 18, v4
	s_movk_i32 s6, 0xffed
	v_cmp_lt_i32_e32 vcc, s6, v4
	v_cmp_gt_i32_e64 s[6:7], s17, v0
	s_and_b64 s[84:85], vcc, s[6:7]
	v_mov_b32_e32 v4, 0
	v_add_u32_e32 v69, s43, v0
	v_mov_b32_e32 v19, 0
	s_and_saveexec_b64 s[6:7], s[84:85]
	s_cbranch_execz .LBB0_607
	v_mad_i64_i32 v[18:19], s[64:65], v69, s33, v[44:45]
	global_load_ushort v19, v[18:19], off offset:2048
.LBB0_607:
	s_or_b64 exec, exec, s[6:7]
	s_waitcnt vmcnt(0)
	v_lshlrev_b32_e32 v42, 16, v42
	v_lshlrev_b32_e32 v43, 16, v43
	v_lshlrev_b32_e32 v40, 16, v40
	v_lshlrev_b32_e32 v41, 16, v41
	v_lshlrev_b32_e32 v39, 16, v39
	v_lshlrev_b32_e32 v37, 16, v37
	v_lshlrev_b32_e32 v35, 16, v35
	v_lshlrev_b32_e32 v33, 16, v33
	v_lshlrev_b32_e32 v31, 16, v31
	v_lshlrev_b32_e32 v29, 16, v29
	v_lshlrev_b32_e32 v27, 16, v27
	v_lshlrev_b32_e32 v25, 16, v25
	v_lshlrev_b32_e32 v23, 16, v23
	v_lshlrev_b32_e32 v21, 16, v21
	v_lshlrev_b32_e32 v13, 16, v13
	v_lshlrev_b32_e32 v11, 16, v11
	v_lshlrev_b32_e32 v17, 16, v17
	v_lshlrev_b32_e32 v15, 16, v15
	v_lshlrev_b32_e32 v19, 16, v19
	s_waitcnt vmcnt(2)
	v_pk_mul_f32 v[70:71], v[6:7], v[42:43]
	s_waitcnt vmcnt(0)
	v_pk_mul_f32 v[44:45], v[8:9], v[40:41]
	v_add_f32_e32 v0, v70, v71
	v_add_f32_e32 v0, v0, v44
	v_add_f32_e32 v0, v0, v45
	v_mul_f32_e32 v5, 0xbfb8aa3b, v0
	v_exp_f32_e32 v5, v5
	s_ashr_i32 s17, s16, 31
	s_lshl_b64 s[6:7], s[16:17], 13
	s_add_u32 s43, s4, s6
	v_add_f32_e32 v5, 1.0, v5
	v_rcp_f32_e32 v5, v5
	s_addc_u32 s52, s5, s7
	v_mov_b32_e32 v42, v43
	v_mov_b32_e32 v43, v40
	v_mul_f32_e32 v0, v0, v5
	v_mul_f32_e32 v5, v0, v0
	v_mov_b32_e32 v38, v41
	v_pk_mul_f32 v[42:43], v[6:7], v[42:43]
	v_mov_b32_dpp v5, v5 quad_perm:[1,0,3,2] row_mask:0xf bank_mask:0xf bound_ctrl:1
	v_fmac_f32_e32 v5, v0, v0
	v_mov_b32_e32 v36, v39
	v_pk_mul_f32 v[40:41], v[6:7], v[40:41]
	v_add_f32_dpp v5, v5, v5 quad_perm:[2,3,0,1] row_mask:0xf bank_mask:0xf bound_ctrl:1
	v_mov_b32_e32 v34, v37
	v_mov_b32_e32 v32, v35
	v_add_f32_dpp v5, v5, v5 row_half_mirror row_mask:0xf bank_mask:0xf bound_ctrl:1
	v_mov_b32_e32 v30, v33
	v_mov_b32_e32 v28, v31
	v_add_f32_dpp v5, v5, v5 row_mirror row_mask:0xf bank_mask:0xf bound_ctrl:1
	v_mov_b32_e32 v26, v29
	v_readlane_b32 s64, v5, 16
	v_readlane_b32 s65, v5, 48
	v_readlane_b32 s6, v5, 0
	v_readlane_b32 s7, v5, 32
	v_mov_b32_e32 v44, s64
	v_mov_b32_e32 v45, s65
	v_pk_add_f32 v[44:45], s[6:7], v[44:45]
	s_add_u32 s6, s43, 0xbc27800
	v_add_f32_e32 v5, v44, v45
	v_add_f32_e32 v5, 0x358637bd, v5
	v_mul_f32_e32 v10, 0x4b800000, v5
	v_cmp_gt_f32_e32 vcc, s68, v5
	v_pk_mul_f32 v[44:45], v[8:9], v[38:39]
	s_movk_i32 s43, 0x900
	v_cndmask_b32_e32 v5, v5, v10, vcc
	v_rsq_f32_e32 v5, v5
	s_addc_u32 s7, s52, 0
	v_mul_lo_u32 v14, v49, s43
	v_lshl_add_u32 v10, v46, 1, 0
	v_mul_f32_e32 v12, 0x45800000, v5
	v_cndmask_b32_e32 v5, v5, v12, vcc
	v_mul_f32_e32 v5, 0x3e000000, v5
	v_mul_f32_e32 v0, v0, v5
	v_add_f32_e32 v5, v42, v43
	v_add_f32_e32 v5, v5, v44
	v_add_f32_e32 v5, v5, v45
	v_mul_f32_e32 v12, 0xbfb8aa3b, v5
	v_exp_f32_e32 v12, v12
	v_add_u32_e32 v43, v10, v14
	v_lshl_or_b32 v44, v49, 10, v46
	v_ashrrev_i32_e32 v45, 31, v44
	v_add_f32_e32 v12, 1.0, v12
	v_rcp_f32_e32 v12, v12
	v_cvt_pk_bf16_f32 v0, v0, s0
	v_lshl_add_u64 v[44:45], v[44:45], 1, s[6:7]
	global_store_short v[44:45], v0, off
	v_mul_f32_e32 v5, v5, v12
	v_mul_f32_e32 v12, v5, v5
	v_pk_mul_f32 v[44:45], v[8:9], v[36:37]
	ds_write_b16 v43, v0
	v_mov_b32_dpp v12, v12 quad_perm:[1,0,3,2] row_mask:0xf bank_mask:0xf bound_ctrl:1
	v_fmac_f32_e32 v12, v5, v5
	v_or_b32_e32 v0, 1, v48
	v_pk_mul_f32 v[38:39], v[6:7], v[38:39]
	v_add_f32_dpp v12, v12, v12 quad_perm:[2,3,0,1] row_mask:0xf bank_mask:0xf bound_ctrl:1
	v_pk_mul_f32 v[36:37], v[6:7], v[36:37]
	v_mov_b32_e32 v24, v27
	v_add_f32_dpp v12, v12, v12 row_half_mirror row_mask:0xf bank_mask:0xf bound_ctrl:1
	v_mov_b32_e32 v22, v25
	s_nop 0
	v_add_f32_dpp v12, v12, v12 row_mirror row_mask:0xf bank_mask:0xf bound_ctrl:1
	s_nop 0
	v_readlane_b32 s43, v12, 16
	v_readlane_b32 s52, v12, 48
	v_readlane_b32 s64, v12, 0
	v_readlane_b32 s65, v12, 32
	v_mov_b32_e32 v70, s43
	v_mov_b32_e32 v71, s52
	v_pk_add_f32 v[70:71], s[64:65], v[70:71]
	s_movk_i32 s43, 0x90
	v_add_f32_e32 v12, v70, v71
	v_add_f32_e32 v12, 0x358637bd, v12
	v_mul_f32_e32 v14, 0x4b800000, v12
	v_cmp_gt_f32_e32 vcc, s68, v12
	s_nop 1
	v_cndmask_b32_e32 v12, v12, v14, vcc
	v_rsq_f32_e32 v12, v12
	s_nop 0
	v_mul_f32_e32 v14, 0x45800000, v12
	v_cndmask_b32_e32 v12, v12, v14, vcc
	v_add_f32_e32 v14, v40, v41
	v_add_f32_e32 v14, v14, v44
	v_add_f32_e32 v14, v14, v45
	v_mul_f32_e32 v16, 0xbfb8aa3b, v14
	v_exp_f32_e32 v16, v16
	v_mul_f32_e32 v12, 0x3e000000, v12
	v_mul_f32_e32 v5, v5, v12
	v_mul_lo_u32 v12, v0, s43
	v_add_f32_e32 v16, 1.0, v16
	v_rcp_f32_e32 v16, v16
	v_lshl_or_b32 v40, v0, 6, v46
	v_ashrrev_i32_e32 v41, 31, v40
	v_cvt_pk_bf16_f32 v5, v5, s0
	v_mul_f32_e32 v0, v14, v16
	v_mul_f32_e32 v14, v0, v0
	v_add_u32_e32 v42, v10, v12
	v_lshl_add_u64 v[40:41], v[40:41], 1, s[6:7]
	v_mov_b32_dpp v14, v14 quad_perm:[1,0,3,2] row_mask:0xf bank_mask:0xf bound_ctrl:1
	v_fmac_f32_e32 v14, v0, v0
	ds_write_b16 v42, v5
	global_store_short v[40:41], v5, off
	v_add_f32_dpp v14, v14, v14 quad_perm:[2,3,0,1] row_mask:0xf bank_mask:0xf bound_ctrl:1
	v_pk_mul_f32 v[40:41], v[8:9], v[34:35]
	v_pk_mul_f32 v[34:35], v[6:7], v[34:35]
	v_add_f32_dpp v14, v14, v14 row_half_mirror row_mask:0xf bank_mask:0xf bound_ctrl:1
	v_add_u32_e32 v12, 0x2d0, v12
	s_nop 0
	v_add_f32_dpp v14, v14, v14 row_mirror row_mask:0xf bank_mask:0xf bound_ctrl:1
	s_nop 0
	v_readlane_b32 s43, v14, 16
	v_readlane_b32 s52, v14, 48
	v_readlane_b32 s64, v14, 0
	v_readlane_b32 s65, v14, 32
	v_mov_b32_e32 v44, s43
	v_mov_b32_e32 v45, s52
	v_pk_add_f32 v[44:45], s[64:65], v[44:45]
	s_nop 0
	v_add_f32_e32 v14, v44, v45
	v_add_f32_e32 v14, 0x358637bd, v14
	v_mul_f32_e32 v16, 0x4b800000, v14
	v_cmp_gt_f32_e32 vcc, s68, v14
	v_add_u32_e32 v44, v10, v12
	s_nop 0
	v_cndmask_b32_e32 v14, v14, v16, vcc
	v_rsq_f32_e32 v14, v14
	s_nop 0
	v_mul_f32_e32 v5, 0x45800000, v14
	v_cndmask_b32_e32 v5, v14, v5, vcc
	v_add_f32_e32 v14, v38, v39
	v_add_f32_e32 v14, v14, v40
	v_add_f32_e32 v14, v14, v41
	v_mul_f32_e32 v16, 0xbfb8aa3b, v14
	v_exp_f32_e32 v16, v16
	v_mul_f32_e32 v5, 0x3e000000, v5
	v_mul_f32_e32 v0, v0, v5
	v_cvt_pk_bf16_f32 v5, v0, s0
	v_add_f32_e32 v0, 1.0, v16
	v_rcp_f32_e32 v16, v0
	v_lshl_or_b32 v0, v48, 6, v46
	v_or_b32_e32 v38, 0x80, v0
	v_ashrrev_i32_e32 v39, 31, v38
	v_mul_f32_e32 v14, v14, v16
	v_mul_f32_e32 v16, v14, v14
	v_lshl_add_u64 v[38:39], v[38:39], 1, s[6:7]
	global_store_short v[38:39], v5, off
	v_mov_b32_dpp v16, v16 quad_perm:[1,0,3,2] row_mask:0xf bank_mask:0xf bound_ctrl:1
	v_fmac_f32_e32 v16, v14, v14
	v_pk_mul_f32 v[38:39], v[8:9], v[32:33]
	ds_write_b16 v42, v5 offset:144
	v_add_f32_dpp v16, v16, v16 quad_perm:[2,3,0,1] row_mask:0xf bank_mask:0xf bound_ctrl:1
	v_pk_mul_f32 v[32:33], v[6:7], v[32:33]
	s_nop 0
	v_add_f32_dpp v16, v16, v16 row_half_mirror row_mask:0xf bank_mask:0xf bound_ctrl:1
	s_nop 1
	v_add_f32_dpp v16, v16, v16 row_mirror row_mask:0xf bank_mask:0xf bound_ctrl:1
	s_nop 0
	v_readlane_b32 s43, v16, 16
	v_readlane_b32 s52, v16, 48
	v_readlane_b32 s64, v16, 0
	v_readlane_b32 s65, v16, 32
	v_mov_b32_e32 v40, s43
	v_mov_b32_e32 v41, s52
	v_pk_add_f32 v[40:41], s[64:65], v[40:41]
	s_nop 0
	v_add_f32_e32 v16, v40, v41
	v_add_f32_e32 v16, 0x358637bd, v16
	v_mul_f32_e32 v18, 0x4b800000, v16
	v_cmp_gt_f32_e32 vcc, s68, v16
	s_nop 1
	v_cndmask_b32_e32 v16, v16, v18, vcc
	v_add_f32_e32 v18, v36, v37
	v_rsq_f32_e32 v16, v16
	v_add_f32_e32 v18, v18, v38
	v_add_f32_e32 v18, v18, v39
	v_mul_f32_e32 v20, 0xbfb8aa3b, v18
	v_exp_f32_e32 v20, v20
	v_mul_f32_e32 v5, 0x45800000, v16
	v_cndmask_b32_e32 v5, v16, v5, vcc
	v_mul_f32_e32 v5, 0x3e000000, v5
	v_mul_f32_e32 v5, v14, v5
	v_add_f32_e32 v14, 1.0, v20
	v_rcp_f32_e32 v14, v14
	v_or_b32_e32 v36, 0xc0, v0
	v_ashrrev_i32_e32 v37, 31, v36
	v_cvt_pk_bf16_f32 v5, v5, s0
	v_mul_f32_e32 v14, v18, v14
	v_mul_f32_e32 v16, v14, v14
	v_lshl_add_u64 v[36:37], v[36:37], 1, s[6:7]
	global_store_short v[36:37], v5, off
	v_mov_b32_dpp v16, v16 quad_perm:[1,0,3,2] row_mask:0xf bank_mask:0xf bound_ctrl:1
	v_fmac_f32_e32 v16, v14, v14
	v_pk_mul_f32 v[36:37], v[8:9], v[30:31]
	ds_write_b16 v42, v5 offset:288
	v_add_f32_dpp v16, v16, v16 quad_perm:[2,3,0,1] row_mask:0xf bank_mask:0xf bound_ctrl:1
	v_pk_mul_f32 v[30:31], v[6:7], v[30:31]
	s_nop 0
	v_add_f32_dpp v16, v16, v16 row_half_mirror row_mask:0xf bank_mask:0xf bound_ctrl:1
	s_nop 1
	v_add_f32_dpp v16, v16, v16 row_mirror row_mask:0xf bank_mask:0xf bound_ctrl:1
	s_nop 0
	v_readlane_b32 s43, v16, 16
	v_readlane_b32 s52, v16, 48
	v_readlane_b32 s64, v16, 0
	v_readlane_b32 s65, v16, 32
	v_mov_b32_e32 v38, s43
	v_mov_b32_e32 v39, s52
	v_pk_add_f32 v[38:39], s[64:65], v[38:39]
	s_nop 0
	v_add_f32_e32 v16, v38, v39
	v_add_f32_e32 v16, 0x358637bd, v16
	v_mul_f32_e32 v18, 0x4b800000, v16
	v_cmp_gt_f32_e32 vcc, s68, v16
	s_nop 1
	v_cndmask_b32_e32 v16, v16, v18, vcc
	v_add_f32_e32 v18, v34, v35
	v_rsq_f32_e32 v16, v16
	v_add_f32_e32 v18, v18, v36
	v_add_f32_e32 v18, v18, v37
	v_mul_f32_e32 v20, 0xbfb8aa3b, v18
	v_exp_f32_e32 v20, v20
	v_mul_f32_e32 v5, 0x45800000, v16
	v_cndmask_b32_e32 v5, v16, v5, vcc
	v_mul_f32_e32 v5, 0x3e000000, v5
	v_mul_f32_e32 v5, v14, v5
	v_add_f32_e32 v14, 1.0, v20
	v_rcp_f32_e32 v14, v14
	v_or_b32_e32 v34, 0x100, v0
	v_ashrrev_i32_e32 v35, 31, v34
	v_cvt_pk_bf16_f32 v5, v5, s0
	v_mul_f32_e32 v14, v18, v14
	v_mul_f32_e32 v16, v14, v14
	v_lshl_add_u64 v[34:35], v[34:35], 1, s[6:7]
	global_store_short v[34:35], v5, off
	v_mov_b32_dpp v16, v16 quad_perm:[1,0,3,2] row_mask:0xf bank_mask:0xf bound_ctrl:1
	v_fmac_f32_e32 v16, v14, v14
	v_pk_mul_f32 v[34:35], v[8:9], v[28:29]
	ds_write_b16 v42, v5 offset:432
	v_add_f32_dpp v16, v16, v16 quad_perm:[2,3,0,1] row_mask:0xf bank_mask:0xf bound_ctrl:1
	v_pk_mul_f32 v[28:29], v[6:7], v[28:29]
	s_nop 0
	v_add_f32_dpp v16, v16, v16 row_half_mirror row_mask:0xf bank_mask:0xf bound_ctrl:1
	s_nop 1
	v_add_f32_dpp v16, v16, v16 row_mirror row_mask:0xf bank_mask:0xf bound_ctrl:1
	s_nop 0
	v_readlane_b32 s43, v16, 16
	v_readlane_b32 s52, v16, 48
	v_readlane_b32 s64, v16, 0
	v_readlane_b32 s65, v16, 32
	v_mov_b32_e32 v36, s43
	v_mov_b32_e32 v37, s52
	v_pk_add_f32 v[36:37], s[64:65], v[36:37]
	s_nop 0
	v_add_f32_e32 v16, v36, v37
	v_add_f32_e32 v16, 0x358637bd, v16
	v_mul_f32_e32 v18, 0x4b800000, v16
	v_cmp_gt_f32_e32 vcc, s68, v16
	s_nop 1
	v_cndmask_b32_e32 v16, v16, v18, vcc
	v_add_f32_e32 v18, v32, v33
	v_rsq_f32_e32 v16, v16
	v_add_f32_e32 v18, v18, v34
	v_add_f32_e32 v18, v18, v35
	v_mul_f32_e32 v20, 0xbfb8aa3b, v18
	v_exp_f32_e32 v20, v20
	v_mul_f32_e32 v5, 0x45800000, v16
	v_cndmask_b32_e32 v5, v16, v5, vcc
	v_mul_f32_e32 v5, 0x3e000000, v5
	v_mul_f32_e32 v5, v14, v5
	v_add_f32_e32 v14, 1.0, v20
	v_rcp_f32_e32 v14, v14
	v_or_b32_e32 v32, 0x140, v0
	v_ashrrev_i32_e32 v33, 31, v32
	v_cvt_pk_bf16_f32 v5, v5, s0
	v_mul_f32_e32 v14, v18, v14
	v_mul_f32_e32 v16, v14, v14
	v_lshl_add_u64 v[32:33], v[32:33], 1, s[6:7]
	ds_write_b16 v42, v5 offset:576
	v_mov_b32_dpp v16, v16 quad_perm:[1,0,3,2] row_mask:0xf bank_mask:0xf bound_ctrl:1
	v_fmac_f32_e32 v16, v14, v14
	global_store_short v[32:33], v5, off
	v_pk_mul_f32 v[32:33], v[8:9], v[26:27]
	v_add_f32_dpp v16, v16, v16 quad_perm:[2,3,0,1] row_mask:0xf bank_mask:0xf bound_ctrl:1
	v_pk_mul_f32 v[26:27], v[6:7], v[26:27]
	v_mov_b32_e32 v20, v23
	v_add_f32_dpp v16, v16, v16 row_half_mirror row_mask:0xf bank_mask:0xf bound_ctrl:1
	s_nop 1
	v_add_f32_dpp v16, v16, v16 row_mirror row_mask:0xf bank_mask:0xf bound_ctrl:1
	s_nop 0
	v_readlane_b32 s43, v16, 16
	v_readlane_b32 s52, v16, 48
	v_readlane_b32 s64, v16, 0
	v_readlane_b32 s65, v16, 32
	v_mov_b32_e32 v34, s43
	v_mov_b32_e32 v35, s52
	v_pk_add_f32 v[34:35], s[64:65], v[34:35]
	s_nop 0
	v_add_f32_e32 v16, v34, v35
	v_add_f32_e32 v16, 0x358637bd, v16
	v_mul_f32_e32 v18, 0x4b800000, v16
	v_cmp_gt_f32_e32 vcc, s68, v16
	s_nop 1
	v_cndmask_b32_e32 v16, v16, v18, vcc
	v_rsq_f32_e32 v16, v16
	s_nop 0
	v_mul_f32_e32 v5, 0x45800000, v16
	v_cndmask_b32_e32 v5, v16, v5, vcc
	v_add_f32_e32 v16, v30, v31
	v_add_f32_e32 v16, v16, v32
	v_add_f32_e32 v16, v16, v33
	v_mul_f32_e32 v18, 0xbfb8aa3b, v16
	v_exp_f32_e32 v18, v18
	v_mul_f32_e32 v5, 0x3e000000, v5
	v_mul_f32_e32 v5, v14, v5
	v_or_b32_e32 v30, 0x180, v0
	v_add_f32_e32 v14, 1.0, v18
	v_rcp_f32_e32 v14, v14
	v_ashrrev_i32_e32 v31, 31, v30
	v_cvt_pk_bf16_f32 v5, v5, s0
	v_lshl_add_u64 v[30:31], v[30:31], 1, s[6:7]
	v_mul_f32_e32 v10, v16, v14
	v_mul_f32_e32 v12, v10, v10
	global_store_short v[30:31], v5, off
	v_pk_mul_f32 v[30:31], v[8:9], v[24:25]
	v_mov_b32_dpp v12, v12 quad_perm:[1,0,3,2] row_mask:0xf bank_mask:0xf bound_ctrl:1
	v_fmac_f32_e32 v12, v10, v10
	ds_write_b16 v44, v5
	v_pk_mul_f32 v[24:25], v[6:7], v[24:25]
	v_add_f32_dpp v12, v12, v12 quad_perm:[2,3,0,1] row_mask:0xf bank_mask:0xf bound_ctrl:1
	s_nop 1
	v_add_f32_dpp v12, v12, v12 row_half_mirror row_mask:0xf bank_mask:0xf bound_ctrl:1
	s_nop 1
	v_add_f32_dpp v12, v12, v12 row_mirror row_mask:0xf bank_mask:0xf bound_ctrl:1
	s_nop 0
	v_readlane_b32 s43, v12, 16
	v_readlane_b32 s52, v12, 48
	v_readlane_b32 s64, v12, 0
	v_readlane_b32 s65, v12, 32
	v_mov_b32_e32 v32, s43
	v_mov_b32_e32 v33, s52
	v_pk_add_f32 v[32:33], s[64:65], v[32:33]
	s_nop 0
	v_add_f32_e32 v12, v32, v33
	v_add_f32_e32 v12, 0x358637bd, v12
	v_mul_f32_e32 v14, 0x4b800000, v12
	v_cmp_gt_f32_e32 vcc, s68, v12
	s_nop 1
	v_cndmask_b32_e32 v12, v12, v14, vcc
	v_add_f32_e32 v14, v28, v29
	v_rsq_f32_e32 v12, v12
	v_add_f32_e32 v14, v14, v30
	v_add_f32_e32 v14, v14, v31
	v_mul_f32_e32 v16, 0xbfb8aa3b, v14
	v_exp_f32_e32 v16, v16
	v_mul_f32_e32 v5, 0x45800000, v12
	v_cndmask_b32_e32 v5, v12, v5, vcc
	v_mul_f32_e32 v5, 0x3e000000, v5
	v_mul_f32_e32 v5, v10, v5
	v_add_f32_e32 v10, 1.0, v16
	v_rcp_f32_e32 v10, v10
	v_or_b32_e32 v28, 0x1c0, v0
	v_ashrrev_i32_e32 v29, 31, v28
	v_cvt_pk_bf16_f32 v5, v5, s0
	v_mul_f32_e32 v10, v14, v10
	v_mul_f32_e32 v12, v10, v10
	v_lshl_add_u64 v[28:29], v[28:29], 1, s[6:7]
	global_store_short v[28:29], v5, off
	v_mov_b32_dpp v12, v12 quad_perm:[1,0,3,2] row_mask:0xf bank_mask:0xf bound_ctrl:1
	v_fmac_f32_e32 v12, v10, v10
	v_pk_mul_f32 v[28:29], v[8:9], v[22:23]
	ds_write_b16 v44, v5 offset:144
	v_add_f32_dpp v12, v12, v12 quad_perm:[2,3,0,1] row_mask:0xf bank_mask:0xf bound_ctrl:1
	v_pk_mul_f32 v[22:23], v[6:7], v[22:23]
	s_nop 0
	v_add_f32_dpp v12, v12, v12 row_half_mirror row_mask:0xf bank_mask:0xf bound_ctrl:1
	s_nop 1
	v_add_f32_dpp v12, v12, v12 row_mirror row_mask:0xf bank_mask:0xf bound_ctrl:1
	s_nop 0
	v_readlane_b32 s43, v12, 16
	v_readlane_b32 s52, v12, 48
	v_readlane_b32 s64, v12, 0
	v_readlane_b32 s65, v12, 32
	v_mov_b32_e32 v30, s43
	v_mov_b32_e32 v31, s52
	v_pk_add_f32 v[30:31], s[64:65], v[30:31]
	s_nop 0
	v_add_f32_e32 v12, v30, v31
	v_add_f32_e32 v12, 0x358637bd, v12
	v_mul_f32_e32 v14, 0x4b800000, v12
	v_cmp_gt_f32_e32 vcc, s68, v12
	s_nop 1
	v_cndmask_b32_e32 v12, v12, v14, vcc
	v_add_f32_e32 v14, v26, v27
	v_rsq_f32_e32 v12, v12
	v_add_f32_e32 v14, v14, v28
	v_add_f32_e32 v14, v14, v29
	v_mul_f32_e32 v16, 0xbfb8aa3b, v14
	v_exp_f32_e32 v16, v16
	v_mul_f32_e32 v5, 0x45800000, v12
	v_cndmask_b32_e32 v5, v12, v5, vcc
	v_mul_f32_e32 v5, 0x3e000000, v5
	v_mul_f32_e32 v5, v10, v5
	v_add_f32_e32 v10, 1.0, v16
	v_rcp_f32_e32 v10, v10
	v_or_b32_e32 v26, 0x200, v0
	v_ashrrev_i32_e32 v27, 31, v26
	v_cvt_pk_bf16_f32 v5, v5, s0
	v_mul_f32_e32 v10, v14, v10
	v_mul_f32_e32 v12, v10, v10
	v_lshl_add_u64 v[26:27], v[26:27], 1, s[6:7]
	global_store_short v[26:27], v5, off
	v_mov_b32_dpp v12, v12 quad_perm:[1,0,3,2] row_mask:0xf bank_mask:0xf bound_ctrl:1
	v_fmac_f32_e32 v12, v10, v10
	v_pk_mul_f32 v[26:27], v[8:9], v[20:21]
	ds_write_b16 v44, v5 offset:288
	v_add_f32_dpp v12, v12, v12 quad_perm:[2,3,0,1] row_mask:0xf bank_mask:0xf bound_ctrl:1
	s_nop 1
	v_add_f32_dpp v12, v12, v12 row_half_mirror row_mask:0xf bank_mask:0xf bound_ctrl:1
	s_nop 1
	v_add_f32_dpp v12, v12, v12 row_mirror row_mask:0xf bank_mask:0xf bound_ctrl:1
	s_nop 0
	v_readlane_b32 s43, v12, 16
	v_readlane_b32 s52, v12, 48
	v_readlane_b32 s64, v12, 0
	v_readlane_b32 s65, v12, 32
	v_mov_b32_e32 v28, s43
	v_mov_b32_e32 v29, s52
	v_pk_add_f32 v[28:29], s[64:65], v[28:29]
	s_nop 0
	v_add_f32_e32 v12, v28, v29
	v_add_f32_e32 v12, 0x358637bd, v12
	v_mul_f32_e32 v14, 0x4b800000, v12
	v_cmp_gt_f32_e32 vcc, s68, v12
	s_nop 1
	v_cndmask_b32_e32 v12, v12, v14, vcc
	v_add_f32_e32 v14, v24, v25
	v_rsq_f32_e32 v12, v12
	v_add_f32_e32 v14, v14, v26
	v_add_f32_e32 v14, v14, v27
	v_mul_f32_e32 v16, 0xbfb8aa3b, v14
	v_exp_f32_e32 v16, v16
	v_mul_f32_e32 v5, 0x45800000, v12
	v_cndmask_b32_e32 v5, v12, v5, vcc
	v_mul_f32_e32 v5, 0x3e000000, v5
	v_mul_f32_e32 v5, v10, v5
	v_add_f32_e32 v10, 1.0, v16
	v_rcp_f32_e32 v10, v10
	v_or_b32_e32 v24, 0x240, v0
	v_ashrrev_i32_e32 v25, 31, v24
	v_cvt_pk_bf16_f32 v5, v5, s0
	v_mul_f32_e32 v10, v14, v10
	v_mul_f32_e32 v12, v10, v10
	v_lshl_add_u64 v[24:25], v[24:25], 1, s[6:7]
	global_store_short v[24:25], v5, off
	v_mov_b32_dpp v12, v12 quad_perm:[1,0,3,2] row_mask:0xf bank_mask:0xf bound_ctrl:1
	v_fmac_f32_e32 v12, v10, v10
	v_add_f32_e32 v16, v22, v23
	ds_write_b16 v44, v5 offset:432
	v_add_f32_dpp v12, v12, v12 quad_perm:[2,3,0,1] row_mask:0xf bank_mask:0xf bound_ctrl:1
	v_or_b32_e32 v22, 0x280, v0
	v_ashrrev_i32_e32 v23, 31, v22
	v_add_f32_dpp v12, v12, v12 row_half_mirror row_mask:0xf bank_mask:0xf bound_ctrl:1
	v_lshl_add_u64 v[22:23], v[22:23], 1, s[6:7]
	s_nop 0
	v_add_f32_dpp v12, v12, v12 row_mirror row_mask:0xf bank_mask:0xf bound_ctrl:1
	s_nop 0
	v_readlane_b32 s43, v12, 16
	v_readlane_b32 s52, v12, 48
	v_readlane_b32 s64, v12, 0
	v_readlane_b32 s65, v12, 32
	v_mov_b32_e32 v26, s43
	v_mov_b32_e32 v27, s52
	v_pk_add_f32 v[26:27], s[64:65], v[26:27]
	s_nop 0
	v_add_f32_e32 v12, v26, v27
	v_add_f32_e32 v12, 0x358637bd, v12
	v_mul_f32_e32 v14, 0x4b800000, v12
	v_cmp_gt_f32_e32 vcc, s68, v12
	s_nop 1
	v_cndmask_b32_e32 v12, v12, v14, vcc
	v_rsq_f32_e32 v14, v12
	v_mov_b32_e32 v12, v21
	v_pk_mul_f32 v[24:25], v[8:9], v[12:13]
	v_pk_mul_f32 v[20:21], v[6:7], v[20:21]
	v_add_f32_e32 v16, v16, v24
	v_add_f32_e32 v16, v16, v25
	v_mul_f32_e32 v18, 0xbfb8aa3b, v16
	v_exp_f32_e32 v18, v18
	v_mul_f32_e32 v5, 0x45800000, v14
	v_cndmask_b32_e32 v5, v14, v5, vcc
	v_mul_f32_e32 v5, 0x3e000000, v5
	v_mul_f32_e32 v5, v10, v5
	v_add_f32_e32 v10, 1.0, v18
	v_rcp_f32_e32 v10, v10
	v_cvt_pk_bf16_f32 v5, v5, s0
	global_store_short v[22:23], v5, off
	v_add_f32_e32 v18, v20, v21
	v_mul_f32_e32 v14, v16, v10
	v_mul_f32_e32 v10, v14, v14
	ds_write_b16 v44, v5 offset:576
	s_nop 0
	v_mov_b32_dpp v10, v10 quad_perm:[1,0,3,2] row_mask:0xf bank_mask:0xf bound_ctrl:1
	v_fmac_f32_e32 v10, v14, v14
	s_nop 1
	v_add_f32_dpp v10, v10, v10 quad_perm:[2,3,0,1] row_mask:0xf bank_mask:0xf bound_ctrl:1
	s_nop 1
	v_add_f32_dpp v10, v10, v10 row_half_mirror row_mask:0xf bank_mask:0xf bound_ctrl:1
	s_nop 1
	v_add_f32_dpp v10, v10, v10 row_mirror row_mask:0xf bank_mask:0xf bound_ctrl:1
	s_nop 0
	v_readlane_b32 s43, v10, 16
	v_readlane_b32 s52, v10, 48
	v_readlane_b32 s64, v10, 0
	v_readlane_b32 s65, v10, 32
	v_mov_b32_e32 v24, s43
	v_mov_b32_e32 v25, s52
	v_pk_add_f32 v[24:25], s[64:65], v[24:25]
	s_nop 0
	v_add_f32_e32 v10, v24, v25
	v_add_f32_e32 v10, 0x358637bd, v10
	v_mul_f32_e32 v16, 0x4b800000, v10
	v_cmp_gt_f32_e32 vcc, s68, v10
	s_nop 1
	v_cndmask_b32_e32 v10, v10, v16, vcc
	v_rsq_f32_e32 v16, v10
	v_mov_b32_e32 v10, v13
	v_pk_mul_f32 v[22:23], v[8:9], v[10:11]
	v_pk_mul_f32 v[12:13], v[6:7], v[12:13]
	v_add_f32_e32 v18, v18, v22
	v_add_f32_e32 v18, v18, v23
	v_mul_f32_e32 v20, 0xbfb8aa3b, v18
	v_exp_f32_e32 v20, v20
	v_mul_f32_e32 v5, 0x45800000, v16
	v_cndmask_b32_e32 v5, v16, v5, vcc
	v_mul_f32_e32 v5, 0x3e000000, v5
	v_mul_f32_e32 v5, v14, v5
	v_add_f32_e32 v14, 1.0, v20
	v_rcp_f32_e32 v14, v14
	v_or_b32_e32 v20, 0x2c0, v0
	v_ashrrev_i32_e32 v21, 31, v20
	v_cvt_pk_bf16_f32 v5, v5, s0
	v_mul_f32_e32 v14, v18, v14
	v_mul_f32_e32 v16, v14, v14
	v_lshl_add_u64 v[20:21], v[20:21], 1, s[6:7]
	global_store_short v[20:21], v5, off
	v_mov_b32_dpp v16, v16 quad_perm:[1,0,3,2] row_mask:0xf bank_mask:0xf bound_ctrl:1
	v_fmac_f32_e32 v16, v14, v14
	v_add_f32_e32 v12, v12, v13
	ds_write_b16 v44, v5 offset:720
	v_add_f32_dpp v16, v16, v16 quad_perm:[2,3,0,1] row_mask:0xf bank_mask:0xf bound_ctrl:1
	s_nop 1
	v_add_f32_dpp v16, v16, v16 row_half_mirror row_mask:0xf bank_mask:0xf bound_ctrl:1
	s_nop 1
	v_add_f32_dpp v16, v16, v16 row_mirror row_mask:0xf bank_mask:0xf bound_ctrl:1
	s_nop 0
	v_readlane_b32 s43, v16, 16
	v_readlane_b32 s52, v16, 48
	v_readlane_b32 s64, v16, 0
	v_readlane_b32 s65, v16, 32
	v_mov_b32_e32 v22, s43
	v_mov_b32_e32 v23, s52
	v_pk_add_f32 v[22:23], s[64:65], v[22:23]
	s_nop 0
	v_add_f32_e32 v16, v22, v23
	v_add_f32_e32 v16, 0x358637bd, v16
	v_mul_f32_e32 v18, 0x4b800000, v16
	v_cmp_gt_f32_e32 vcc, s68, v16
	s_nop 1
	v_cndmask_b32_e32 v16, v16, v18, vcc
	v_rsq_f32_e32 v18, v16
	v_mov_b32_e32 v16, v11
	v_pk_mul_f32 v[20:21], v[8:9], v[16:17]
	v_pk_mul_f32 v[10:11], v[6:7], v[10:11]
	v_add_f32_e32 v12, v12, v20
	v_add_f32_e32 v13, v12, v21
	v_mul_f32_e32 v12, 0xbfb8aa3b, v13
	v_exp_f32_e32 v12, v12
	v_mul_f32_e32 v5, 0x45800000, v18
	v_cndmask_b32_e32 v5, v18, v5, vcc
	v_mul_f32_e32 v5, 0x3e000000, v5
	v_add_f32_e32 v12, 1.0, v12
	v_mul_f32_e32 v5, v14, v5
	v_rcp_f32_e32 v14, v12
	v_or_b32_e32 v12, 0x300, v0
	v_cvt_pk_bf16_f32 v5, v5, s0
	v_add_f32_e32 v10, v10, v11
	v_mul_f32_e32 v18, v13, v14
	v_mul_f32_e32 v13, v18, v18
	ds_write_b16 v44, v5 offset:864
	v_pk_mul_f32 v[6:7], v[6:7], v[16:17]
	v_mov_b32_dpp v13, v13 quad_perm:[1,0,3,2] row_mask:0xf bank_mask:0xf bound_ctrl:1
	v_fmac_f32_e32 v13, v18, v18
	v_add_f32_e32 v6, v6, v7
	s_nop 0
	v_add_f32_dpp v13, v13, v13 quad_perm:[2,3,0,1] row_mask:0xf bank_mask:0xf bound_ctrl:1
	s_nop 1
	v_add_f32_dpp v13, v13, v13 row_half_mirror row_mask:0xf bank_mask:0xf bound_ctrl:1
	s_nop 1
	v_add_f32_dpp v13, v13, v13 row_mirror row_mask:0xf bank_mask:0xf bound_ctrl:1
	s_nop 0
	v_readlane_b32 s43, v13, 16
	v_readlane_b32 s52, v13, 48
	v_readlane_b32 s64, v13, 0
	v_readlane_b32 s65, v13, 32
	v_mov_b32_e32 v20, s43
	v_mov_b32_e32 v21, s52
	v_pk_add_f32 v[20:21], s[64:65], v[20:21]
	s_mov_b64 s[64:65], 0x400
	v_add_f32_e32 v13, v20, v21
	v_add_f32_e32 v13, 0x358637bd, v13
	v_mul_f32_e32 v14, 0x4b800000, v13
	v_cmp_gt_f32_e32 vcc, s68, v13
	s_nop 1
	v_cndmask_b32_e32 v13, v13, v14, vcc
	v_rsq_f32_e32 v20, v13
	v_ashrrev_i32_e32 v13, 31, v12
	v_lshl_add_u64 v[12:13], v[12:13], 1, s[6:7]
	v_mov_b32_e32 v14, v17
	global_store_short v[12:13], v5, off
	v_pk_mul_f32 v[12:13], v[8:9], v[14:15]
	v_mul_f32_e32 v5, 0x45800000, v20
	v_add_f32_e32 v10, v10, v12
	v_add_f32_e32 v14, v10, v13
	v_mul_f32_e32 v10, 0xbfb8aa3b, v14
	v_exp_f32_e32 v10, v10
	v_cndmask_b32_e32 v5, v20, v5, vcc
	v_add_co_u32_e32 v20, vcc, 0x1000, v2
	v_mul_f32_e32 v5, 0x3e000000, v5
	s_nop 0
	v_addc_co_u32_e32 v21, vcc, 0, v3, vcc
	v_lshl_add_u64 v[12:13], v[2:3], 0, s[64:65]
	v_add_co_u32_e32 v22, vcc, 0x2000, v2
	v_mul_f32_e32 v5, v18, v5
	v_add_f32_e32 v18, 1.0, v10
	v_addc_co_u32_e32 v23, vcc, 0, v3, vcc
	global_load_dword v10, v[2:3], off offset:1024
	global_load_dword v11, v[12:13], off offset:3072
	s_nop 0
	global_load_dword v12, v[20:21], off offset:3072
	global_load_dword v13, v[22:23], off offset:2048
	v_rcp_f32_e32 v18, v18
	v_or_b32_e32 v20, 0x340, v0
	v_cvt_pk_bf16_f32 v5, v5, s0
	ds_write_b16 v44, v5 offset:1008
	v_mul_f32_e32 v14, v14, v18
	v_mul_f32_e32 v18, v14, v14
	s_nop 1
	v_mov_b32_dpp v18, v18 quad_perm:[1,0,3,2] row_mask:0xf bank_mask:0xf bound_ctrl:1
	v_fmac_f32_e32 v18, v14, v14
	s_nop 1
	v_add_f32_dpp v18, v18, v18 quad_perm:[2,3,0,1] row_mask:0xf bank_mask:0xf bound_ctrl:1
	s_nop 1
	v_add_f32_dpp v18, v18, v18 row_half_mirror row_mask:0xf bank_mask:0xf bound_ctrl:1
	s_nop 1
	v_add_f32_dpp v18, v18, v18 row_mirror row_mask:0xf bank_mask:0xf bound_ctrl:1
	s_nop 0
	v_readlane_b32 s43, v18, 16
	v_readlane_b32 s52, v18, 48
	v_readlane_b32 s64, v18, 0
	v_readlane_b32 s65, v18, 32
	v_mov_b32_e32 v22, s43
	v_mov_b32_e32 v23, s52
	v_pk_add_f32 v[22:23], s[64:65], v[22:23]
	s_nop 0
	v_add_f32_e32 v18, v22, v23
	v_add_f32_e32 v18, 0x358637bd, v18
	v_mul_f32_e32 v21, 0x4b800000, v18
	v_cmp_gt_f32_e32 vcc, s68, v18
	s_nop 1
	v_cndmask_b32_e32 v18, v18, v21, vcc
	v_rsq_f32_e32 v22, v18
	v_mov_b32_e32 v18, v15
	v_pk_mul_f32 v[8:9], v[8:9], v[18:19]
	v_ashrrev_i32_e32 v21, 31, v20
	v_add_f32_e32 v6, v6, v8
	v_add_f32_e32 v7, v6, v9
	v_mul_f32_e32 v6, 0xbfb8aa3b, v7
	v_exp_f32_e32 v6, v6
	v_lshl_add_u64 v[20:21], v[20:21], 1, s[6:7]
	global_store_short v[20:21], v5, off
	v_mul_f32_e32 v5, 0x45800000, v22
	v_add_f32_e32 v6, 1.0, v6
	v_rcp_f32_e32 v8, v6
	v_cndmask_b32_e32 v5, v22, v5, vcc
	v_mul_f32_e32 v5, 0x3e000000, v5
	v_mul_f32_e32 v5, v14, v5
	v_mul_f32_e32 v14, v7, v8
	v_mul_f32_e32 v7, v14, v14
	v_or_b32_e32 v6, 0x380, v0
	v_cvt_pk_bf16_f32 v5, v5, s0
	v_mov_b32_dpp v7, v7 quad_perm:[1,0,3,2] row_mask:0xf bank_mask:0xf bound_ctrl:1
	v_fmac_f32_e32 v7, v14, v14
	ds_write_b16 v44, v5 offset:1152
	s_nop 0
	v_add_f32_dpp v7, v7, v7 quad_perm:[2,3,0,1] row_mask:0xf bank_mask:0xf bound_ctrl:1
	s_nop 1
	v_add_f32_dpp v7, v7, v7 row_half_mirror row_mask:0xf bank_mask:0xf bound_ctrl:1
	s_nop 1
	v_add_f32_dpp v7, v7, v7 row_mirror row_mask:0xf bank_mask:0xf bound_ctrl:1
	s_nop 0
	v_readlane_b32 s43, v7, 16
	v_readlane_b32 s52, v7, 48
	v_readlane_b32 s64, v7, 0
	v_readlane_b32 s65, v7, 32
	v_mov_b32_e32 v8, s43
	v_mov_b32_e32 v9, s52
	v_pk_add_f32 v[8:9], s[64:65], v[8:9]
	s_nop 0
	v_add_f32_e32 v7, v8, v9
	v_add_f32_e32 v7, 0x358637bd, v7
	v_mul_f32_e32 v8, 0x4b800000, v7
	v_cmp_gt_f32_e32 vcc, s68, v7
	s_nop 1
	v_cndmask_b32_e32 v7, v7, v8, vcc
	v_rsq_f32_e32 v8, v7
	v_ashrrev_i32_e32 v7, 31, v6
	v_lshl_add_u64 v[6:7], v[6:7], 1, s[6:7]
	global_store_short v[6:7], v5, off
	v_mul_f32_e32 v5, 0x45800000, v8
	v_cndmask_b32_e32 v5, v8, v5, vcc
	v_mul_f32_e32 v5, 0x3e000000, v5
	v_or_b32_e32 v6, 0x3c0, v0
	v_mul_f32_e32 v5, v14, v5
	v_ashrrev_i32_e32 v7, 31, v6
	v_or_b32_e32 v0, 0x100, v50
	v_cvt_pk_bf16_f32 v5, v5, s0
	v_lshl_add_u64 v[6:7], v[6:7], 1, s[6:7]
	v_lshlrev_b32_e32 v0, 1, v0
	ds_write_b16 v44, v5 offset:1296
	global_store_short v[6:7], v5, off
	s_and_saveexec_b64 s[6:7], s[10:11]
	s_cbranch_execz .LBB0_609
	v_mov_b64_e32 v[4:5], s[8:9]
	v_mad_i64_i32 v[4:5], s[64:65], v51, s33, v[4:5]
	v_lshl_add_u64 v[4:5], v[4:5], 0, v[0:1]
	global_load_ushort v4, v[4:5], off offset:2048

.LBB0_611:
	s_or_b64 exec, exec, s[6:7]
	s_and_saveexec_b64 s[6:7], s[20:21]
	s_cbranch_execz .LBB0_613
	v_mov_b64_e32 v[6:7], s[8:9]
	v_mad_i64_i32 v[6:7], s[64:65], v53, s33, v[6:7]
	v_lshl_add_u64 v[6:7], v[6:7], 0, v[0:1]
	global_load_ushort v40, v[6:7], off offset:2048
.LBB0_613:
	s_or_b64 exec, exec, s[6:7]
	v_mov_b32_e32 v39, 0
	v_mov_b32_e32 v41, 0
	s_and_saveexec_b64 s[6:7], s[22:23]
	s_cbranch_execz .LBB0_615
	v_mov_b64_e32 v[6:7], s[8:9]
	v_mad_i64_i32 v[6:7], s[64:65], v54, s33, v[6:7]
	v_lshl_add_u64 v[6:7], v[6:7], 0, v[0:1]
	global_load_ushort v41, v[6:7], off offset:2048
.LBB0_615:
	s_or_b64 exec, exec, s[6:7]
	s_and_saveexec_b64 s[6:7], s[24:25]
	s_cbranch_execz .LBB0_617
	v_mov_b64_e32 v[6:7], s[8:9]
	v_mad_i64_i32 v[6:7], s[64:65], v55, s33, v[6:7]
	v_lshl_add_u64 v[6:7], v[6:7], 0, v[0:1]
	global_load_ushort v39, v[6:7], off offset:2048
.LBB0_617:
	s_or_b64 exec, exec, s[6:7]
	v_mov_b32_e32 v35, 0
	v_mov_b32_e32 v37, 0
	s_and_saveexec_b64 s[6:7], s[26:27]
	s_cbranch_execz .LBB0_619
	v_mov_b64_e32 v[6:7], s[8:9]
	v_mad_i64_i32 v[6:7], s[64:65], v56, s33, v[6:7]
	v_lshl_add_u64 v[6:7], v[6:7], 0, v[0:1]
	global_load_ushort v37, v[6:7], off offset:2048
.LBB0_619:
	s_or_b64 exec, exec, s[6:7]
	s_and_saveexec_b64 s[6:7], s[28:29]
	s_cbranch_execz .LBB0_621
	v_mov_b64_e32 v[6:7], s[8:9]
	v_mad_i64_i32 v[6:7], s[64:65], v57, s33, v[6:7]
	v_lshl_add_u64 v[6:7], v[6:7], 0, v[0:1]
	global_load_ushort v35, v[6:7], off offset:2048
.LBB0_621:
	s_or_b64 exec, exec, s[6:7]
	v_mov_b32_e32 v31, 0
	v_mov_b32_e32 v33, 0
	s_and_saveexec_b64 s[6:7], s[30:31]
	s_cbranch_execz .LBB0_623
	v_mov_b64_e32 v[6:7], s[8:9]
	v_mad_i64_i32 v[6:7], s[64:65], v58, s33, v[6:7]
	v_lshl_add_u64 v[6:7], v[6:7], 0, v[0:1]
	global_load_ushort v33, v[6:7], off offset:2048
.LBB0_623:
	s_or_b64 exec, exec, s[6:7]
	s_and_saveexec_b64 s[6:7], s[34:35]
	s_cbranch_execz .LBB0_625
	v_mov_b64_e32 v[6:7], s[8:9]
	v_mad_i64_i32 v[6:7], s[64:65], v59, s33, v[6:7]
	v_lshl_add_u64 v[6:7], v[6:7], 0, v[0:1]
	global_load_ushort v31, v[6:7], off offset:2048
.LBB0_625:
	s_or_b64 exec, exec, s[6:7]
	v_mov_b32_e32 v27, 0
	v_mov_b32_e32 v29, 0
	s_and_saveexec_b64 s[6:7], s[36:37]
	s_cbranch_execz .LBB0_627
	v_mov_b64_e32 v[6:7], s[8:9]
	v_mad_i64_i32 v[6:7], s[64:65], v60, s33, v[6:7]
	v_lshl_add_u64 v[6:7], v[6:7], 0, v[0:1]
	global_load_ushort v29, v[6:7], off offset:2048
.LBB0_627:
	s_or_b64 exec, exec, s[6:7]
	s_and_saveexec_b64 s[6:7], s[38:39]
	s_cbranch_execz .LBB0_629
	v_mov_b64_e32 v[6:7], s[8:9]
	v_mad_i64_i32 v[6:7], s[64:65], v61, s33, v[6:7]
	v_lshl_add_u64 v[6:7], v[6:7], 0, v[0:1]
	global_load_ushort v27, v[6:7], off offset:2048
.LBB0_629:
	s_or_b64 exec, exec, s[6:7]
	v_mov_b32_e32 v23, 0
	v_mov_b32_e32 v25, 0
	s_and_saveexec_b64 s[6:7], s[44:45]
	s_cbranch_execz .LBB0_631
	v_mov_b64_e32 v[6:7], s[8:9]
	v_mad_i64_i32 v[6:7], s[64:65], v62, s33, v[6:7]
	v_lshl_add_u64 v[6:7], v[6:7], 0, v[0:1]
	global_load_ushort v25, v[6:7], off offset:2048
.LBB0_631:
	s_or_b64 exec, exec, s[6:7]
	s_and_saveexec_b64 s[6:7], s[48:49]
	s_cbranch_execz .LBB0_633
	v_mov_b64_e32 v[6:7], s[8:9]
	v_mad_i64_i32 v[6:7], s[64:65], v63, s33, v[6:7]
	v_lshl_add_u64 v[6:7], v[6:7], 0, v[0:1]
	global_load_ushort v23, v[6:7], off offset:2048
.LBB0_633:
	s_or_b64 exec, exec, s[6:7]
	v_mov_b32_e32 v19, 0
	v_mov_b32_e32 v21, 0
	s_and_saveexec_b64 s[6:7], s[50:51]
	s_cbranch_execz .LBB0_635
	v_mov_b64_e32 v[6:7], s[8:9]
	v_mad_i64_i32 v[6:7], s[64:65], v64, s33, v[6:7]
	v_lshl_add_u64 v[6:7], v[6:7], 0, v[0:1]
	global_load_ushort v21, v[6:7], off offset:2048
.LBB0_635:
	s_or_b64 exec, exec, s[6:7]
	s_and_saveexec_b64 s[6:7], s[56:57]
	s_cbranch_execz .LBB0_637
	v_mov_b64_e32 v[6:7], s[8:9]
	v_mad_i64_i32 v[6:7], s[64:65], v65, s33, v[6:7]
	v_lshl_add_u64 v[6:7], v[6:7], 0, v[0:1]
	global_load_ushort v19, v[6:7], off offset:2048
.LBB0_637:
	s_or_b64 exec, exec, s[6:7]
	v_mov_b32_e32 v7, 0
	v_mov_b32_e32 v9, 0
	s_and_saveexec_b64 s[6:7], s[58:59]
	s_cbranch_execz .LBB0_639
	v_mov_b64_e32 v[8:9], s[8:9]
	v_mad_i64_i32 v[8:9], s[64:65], v66, s33, v[8:9]
	v_lshl_add_u64 v[8:9], v[8:9], 0, v[0:1]
	global_load_ushort v9, v[8:9], off offset:2048
.LBB0_639:
	s_or_b64 exec, exec, s[6:7]
	s_and_saveexec_b64 s[6:7], s[60:61]
	s_cbranch_execz .LBB0_641
	v_mov_b64_e32 v[6:7], s[8:9]
	v_mad_i64_i32 v[6:7], s[64:65], v67, s33, v[6:7]
	v_lshl_add_u64 v[6:7], v[6:7], 0, v[0:1]
	global_load_ushort v7, v[6:7], off offset:2048
.LBB0_641:
	s_or_b64 exec, exec, s[6:7]
	v_mov_b32_e32 v15, 0
	v_mov_b32_e32 v17, 0
	s_and_saveexec_b64 s[6:7], s[70:71]
	s_cbranch_execz .LBB0_643
	v_mov_b64_e32 v[16:17], s[8:9]
	v_mad_i64_i32 v[16:17], s[64:65], v68, s33, v[16:17]
	v_lshl_add_u64 v[16:17], v[16:17], 0, v[0:1]
	global_load_ushort v17, v[16:17], off offset:2048
.LBB0_643:
	s_or_b64 exec, exec, s[6:7]
	s_and_saveexec_b64 s[6:7], s[84:85]
	s_cbranch_execz .LBB0_645
	v_mov_b64_e32 v[14:15], s[8:9]
	v_mad_i64_i32 v[14:15], s[64:65], v69, s33, v[14:15]
	v_lshl_add_u64 v[14:15], v[14:15], 0, v[0:1]
	global_load_ushort v15, v[14:15], off offset:2048
.LBB0_645:
	s_or_b64 exec, exec, s[6:7]
	s_waitcnt vmcnt(0)
	v_lshlrev_b32_e32 v4, 16, v4
	v_lshlrev_b32_e32 v5, 16, v5
	v_lshlrev_b32_e32 v40, 16, v40
	v_lshlrev_b32_e32 v41, 16, v41
	v_lshlrev_b32_e32 v39, 16, v39
	v_lshlrev_b32_e32 v37, 16, v37
	v_lshlrev_b32_e32 v35, 16, v35
	v_lshlrev_b32_e32 v33, 16, v33
	v_lshlrev_b32_e32 v31, 16, v31
	v_lshlrev_b32_e32 v29, 16, v29
	v_lshlrev_b32_e32 v27, 16, v27
	v_lshlrev_b32_e32 v25, 16, v25
	v_lshlrev_b32_e32 v23, 16, v23
	v_lshlrev_b32_e32 v21, 16, v21
	v_lshlrev_b32_e32 v19, 16, v19
	v_lshlrev_b32_e32 v9, 16, v9
	v_lshlrev_b32_e32 v7, 16, v7
	v_lshlrev_b32_e32 v17, 16, v17
	v_lshlrev_b32_e32 v15, 16, v15
	s_waitcnt vmcnt(5)
	v_pk_mul_f32 v[72:73], v[10:11], v[4:5]
	s_waitcnt vmcnt(3)
	v_pk_mul_f32 v[70:71], v[12:13], v[40:41]
	v_add_f32_e32 v0, v72, v73
	v_add_f32_e32 v0, v0, v70
	v_add_f32_e32 v0, v0, v71
	v_mul_f32_e32 v4, 0xbfb8aa3b, v0
	v_exp_f32_e32 v4, v4
	v_mov_b32_e32 v38, v41
	v_mov_b32_e32 v36, v39
	v_mov_b32_e32 v34, v37
	v_add_f32_e32 v4, 1.0, v4
	v_rcp_f32_e32 v4, v4
	v_mov_b32_e32 v32, v35
	v_mov_b32_e32 v30, v33
	v_mov_b32_e32 v28, v31
	v_mul_f32_e32 v0, v0, v4
	v_mul_f32_e32 v4, v0, v0
	v_mov_b32_e32 v26, v29
	v_mov_b32_e32 v24, v27
	v_mov_b32_dpp v4, v4 quad_perm:[1,0,3,2] row_mask:0xf bank_mask:0xf bound_ctrl:1
	v_fmac_f32_e32 v4, v0, v0
	v_mov_b32_e32 v22, v25
	v_mov_b32_e32 v20, v23
	v_add_f32_dpp v4, v4, v4 quad_perm:[2,3,0,1] row_mask:0xf bank_mask:0xf bound_ctrl:1
	v_mov_b32_e32 v18, v21
	s_mov_b64 s[64:65], 0x800
	v_add_f32_dpp v4, v4, v4 row_half_mirror row_mask:0xf bank_mask:0xf bound_ctrl:1
	s_nop 1
	v_add_f32_dpp v4, v4, v4 row_mirror row_mask:0xf bank_mask:0xf bound_ctrl:1
	s_nop 0
	v_readlane_b32 s43, v4, 16
	v_readlane_b32 s52, v4, 48
	v_readlane_b32 s6, v4, 0
	v_readlane_b32 s7, v4, 32
	v_mov_b32_e32 v70, s43
	v_mov_b32_e32 v71, s52
	v_pk_add_f32 v[70:71], s[6:7], v[70:71]
	s_nop 0
	v_add_f32_e32 v4, v70, v71
	v_add_f32_e32 v6, 0x358637bd, v4
	v_mov_b32_e32 v4, v5
	v_mov_b32_e32 v5, v40
	v_pk_mul_f32 v[4:5], v[10:11], v[4:5]
	v_pk_mul_f32 v[70:71], v[12:13], v[38:39]
	v_add_f32_e32 v4, v4, v5
	v_add_f32_e32 v4, v4, v70
	v_add_f32_e32 v4, v4, v71
	v_mul_f32_e32 v5, 0xbfb8aa3b, v4
	v_exp_f32_e32 v5, v5
	v_mul_f32_e32 v8, 0x4b800000, v6
	v_cmp_gt_f32_e32 vcc, s68, v6
	v_pk_mul_f32 v[40:41], v[10:11], v[40:41]
	v_add_f32_e32 v5, 1.0, v5
	v_cndmask_b32_e32 v6, v6, v8, vcc
	v_rsq_f32_e32 v6, v6
	v_rcp_f32_e32 v5, v5
	v_add_f32_e32 v14, v40, v41
	v_pk_mul_f32 v[38:39], v[10:11], v[38:39]
	v_mul_f32_e32 v8, 0x45800000, v6
	v_cndmask_b32_e32 v6, v6, v8, vcc
	v_mul_f32_e32 v0, v0, v6
	v_mul_f32_e32 v6, v4, v5
	v_mul_f32_e32 v4, v6, v6
	v_cvt_pk_bf16_f32 v0, v0, s0
	ds_write_b16 v43, v0 offset:9216
	v_mov_b32_dpp v4, v4 quad_perm:[1,0,3,2] row_mask:0xf bank_mask:0xf bound_ctrl:1
	v_fmac_f32_e32 v4, v6, v6
	v_add_f32_e32 v16, v38, v39
	s_nop 0
	v_add_f32_dpp v4, v4, v4 quad_perm:[2,3,0,1] row_mask:0xf bank_mask:0xf bound_ctrl:1
	s_nop 1
	v_add_f32_dpp v4, v4, v4 row_half_mirror row_mask:0xf bank_mask:0xf bound_ctrl:1
	s_nop 1
	v_add_f32_dpp v4, v4, v4 row_mirror row_mask:0xf bank_mask:0xf bound_ctrl:1
	s_nop 0
	v_readlane_b32 s43, v4, 16
	v_readlane_b32 s52, v4, 48
	v_readlane_b32 s6, v4, 0
	v_readlane_b32 s7, v4, 32
	v_mov_b32_e32 v4, s43
	v_mov_b32_e32 v5, s52
	v_pk_add_f32 v[4:5], s[6:7], v[4:5]
	s_nop 0
	v_add_f32_e32 v4, v4, v5
	v_add_f32_e32 v4, 0x358637bd, v4
	v_mul_f32_e32 v5, 0x4b800000, v4
	v_cmp_gt_f32_e32 vcc, s68, v4
	s_nop 1
	v_cndmask_b32_e32 v4, v4, v5, vcc
	v_rsq_f32_e32 v8, v4
	v_pk_mul_f32 v[4:5], v[12:13], v[36:37]
	v_pk_mul_f32 v[36:37], v[10:11], v[36:37]
	v_add_f32_e32 v4, v14, v4
	v_add_f32_e32 v4, v4, v5
	v_mul_f32_e32 v5, 0xbfb8aa3b, v4
	v_exp_f32_e32 v5, v5
	v_mul_f32_e32 v0, 0x45800000, v8
	v_cndmask_b32_e32 v0, v8, v0, vcc
	v_mul_f32_e32 v0, v6, v0
	v_add_f32_e32 v5, 1.0, v5
	v_rcp_f32_e32 v5, v5
	v_cvt_pk_bf16_f32 v0, v0, s0
	ds_write_b16 v42, v0 offset:9216
	v_mul_f32_e32 v6, v4, v5
	v_mul_f32_e32 v4, v6, v6
	s_nop 1
	v_mov_b32_dpp v4, v4 quad_perm:[1,0,3,2] row_mask:0xf bank_mask:0xf bound_ctrl:1
	v_fmac_f32_e32 v4, v6, v6
	s_nop 1
	v_add_f32_dpp v4, v4, v4 quad_perm:[2,3,0,1] row_mask:0xf bank_mask:0xf bound_ctrl:1
	s_nop 1
	v_add_f32_dpp v4, v4, v4 row_half_mirror row_mask:0xf bank_mask:0xf bound_ctrl:1
	s_nop 1
	v_add_f32_dpp v4, v4, v4 row_mirror row_mask:0xf bank_mask:0xf bound_ctrl:1
	s_nop 0
	v_readlane_b32 s43, v4, 16
	v_readlane_b32 s52, v4, 48
	v_readlane_b32 s6, v4, 0
	v_readlane_b32 s7, v4, 32
	v_mov_b32_e32 v4, s43
	v_mov_b32_e32 v5, s52
	v_pk_add_f32 v[4:5], s[6:7], v[4:5]
	s_nop 0
	v_add_f32_e32 v4, v4, v5
	v_add_f32_e32 v8, 0x358637bd, v4
	v_pk_mul_f32 v[4:5], v[12:13], v[34:35]
	v_mul_f32_e32 v14, 0x4b800000, v8
	v_add_f32_e32 v4, v16, v4
	v_add_f32_e32 v4, v4, v5
	v_mul_f32_e32 v5, 0xbfb8aa3b, v4
	v_exp_f32_e32 v5, v5
	v_cmp_gt_f32_e32 vcc, s68, v8
	v_pk_mul_f32 v[34:35], v[10:11], v[34:35]
	v_add_f32_e32 v0, 1.0, v5
	v_rcp_f32_e32 v0, v0
	v_cndmask_b32_e32 v8, v8, v14, vcc
	v_rsq_f32_e32 v8, v8
	v_add_f32_e32 v14, v36, v37
	v_mul_f32_e32 v0, v4, v0
	v_mul_f32_e32 v4, v0, v0
	v_mul_f32_e32 v5, 0x45800000, v8
	v_cndmask_b32_e32 v5, v8, v5, vcc
	v_mov_b32_dpp v4, v4 quad_perm:[1,0,3,2] row_mask:0xf bank_mask:0xf bound_ctrl:1
	v_fmac_f32_e32 v4, v0, v0
	v_mul_f32_e32 v6, v6, v5
	v_cvt_pk_bf16_f32 v6, v6, s0
	v_add_f32_dpp v4, v4, v4 quad_perm:[2,3,0,1] row_mask:0xf bank_mask:0xf bound_ctrl:1
	ds_write_b16 v42, v6 offset:9360
	v_add_f32_e32 v16, v34, v35
	v_add_f32_dpp v4, v4, v4 row_half_mirror row_mask:0xf bank_mask:0xf bound_ctrl:1
	s_nop 1
	v_add_f32_dpp v4, v4, v4 row_mirror row_mask:0xf bank_mask:0xf bound_ctrl:1
	s_nop 0
	v_readlane_b32 s43, v4, 16
	v_readlane_b32 s52, v4, 48
	v_readlane_b32 s6, v4, 0
	v_readlane_b32 s7, v4, 32
	v_mov_b32_e32 v4, s43
	v_mov_b32_e32 v5, s52
	v_pk_add_f32 v[4:5], s[6:7], v[4:5]
	s_nop 0
	v_add_f32_e32 v4, v4, v5
	v_add_f32_e32 v4, 0x358637bd, v4
	v_mul_f32_e32 v5, 0x4b800000, v4
	v_cmp_gt_f32_e32 vcc, s68, v4
	s_nop 1
	v_cndmask_b32_e32 v4, v4, v5, vcc
	v_rsq_f32_e32 v8, v4
	v_pk_mul_f32 v[4:5], v[12:13], v[32:33]
	v_pk_mul_f32 v[32:33], v[10:11], v[32:33]
	v_add_f32_e32 v4, v14, v4
	v_add_f32_e32 v4, v4, v5
	v_mul_f32_e32 v5, 0xbfb8aa3b, v4
	v_exp_f32_e32 v5, v5
	v_mul_f32_e32 v6, 0x45800000, v8
	v_cndmask_b32_e32 v6, v8, v6, vcc
	v_mul_f32_e32 v0, v0, v6
	v_add_f32_e32 v5, 1.0, v5
	v_rcp_f32_e32 v5, v5
	v_cvt_pk_bf16_f32 v0, v0, s0
	ds_write_b16 v42, v0 offset:9504
	v_mul_f32_e32 v6, v4, v5
	v_mul_f32_e32 v4, v6, v6
	s_nop 1
	v_mov_b32_dpp v4, v4 quad_perm:[1,0,3,2] row_mask:0xf bank_mask:0xf bound_ctrl:1
	v_fmac_f32_e32 v4, v6, v6
	s_nop 1
	v_add_f32_dpp v4, v4, v4 quad_perm:[2,3,0,1] row_mask:0xf bank_mask:0xf bound_ctrl:1
	s_nop 1
	v_add_f32_dpp v4, v4, v4 row_half_mirror row_mask:0xf bank_mask:0xf bound_ctrl:1
	s_nop 1
	v_add_f32_dpp v4, v4, v4 row_mirror row_mask:0xf bank_mask:0xf bound_ctrl:1
	s_nop 0
	v_readlane_b32 s43, v4, 16
	v_readlane_b32 s52, v4, 48
	v_readlane_b32 s6, v4, 0
	v_readlane_b32 s7, v4, 32
	v_mov_b32_e32 v4, s43
	v_mov_b32_e32 v5, s52
	v_pk_add_f32 v[4:5], s[6:7], v[4:5]
	s_nop 0
	v_add_f32_e32 v4, v4, v5
	v_add_f32_e32 v8, 0x358637bd, v4
	v_pk_mul_f32 v[4:5], v[12:13], v[30:31]
	v_mul_f32_e32 v14, 0x4b800000, v8
	v_add_f32_e32 v4, v16, v4
	v_add_f32_e32 v4, v4, v5
	v_mul_f32_e32 v5, 0xbfb8aa3b, v4
	v_exp_f32_e32 v5, v5
	v_cmp_gt_f32_e32 vcc, s68, v8
	v_pk_mul_f32 v[30:31], v[10:11], v[30:31]
	v_add_f32_e32 v0, 1.0, v5
	v_rcp_f32_e32 v0, v0
	v_cndmask_b32_e32 v8, v8, v14, vcc
	v_rsq_f32_e32 v8, v8
	v_add_f32_e32 v14, v32, v33
	v_mul_f32_e32 v0, v4, v0
	v_mul_f32_e32 v4, v0, v0
	v_mul_f32_e32 v5, 0x45800000, v8
	v_cndmask_b32_e32 v5, v8, v5, vcc
	v_mov_b32_dpp v4, v4 quad_perm:[1,0,3,2] row_mask:0xf bank_mask:0xf bound_ctrl:1
	v_fmac_f32_e32 v4, v0, v0
	v_mul_f32_e32 v6, v6, v5
	v_cvt_pk_bf16_f32 v6, v6, s0
	v_add_f32_dpp v4, v4, v4 quad_perm:[2,3,0,1] row_mask:0xf bank_mask:0xf bound_ctrl:1
	ds_write_b16 v42, v6 offset:9648
	v_add_f32_e32 v16, v30, v31
	v_add_f32_dpp v4, v4, v4 row_half_mirror row_mask:0xf bank_mask:0xf bound_ctrl:1
	s_nop 1
	v_add_f32_dpp v4, v4, v4 row_mirror row_mask:0xf bank_mask:0xf bound_ctrl:1
	s_nop 0
	v_readlane_b32 s43, v4, 16
	v_readlane_b32 s52, v4, 48
	v_readlane_b32 s6, v4, 0
	v_readlane_b32 s7, v4, 32
	v_mov_b32_e32 v4, s43
	v_mov_b32_e32 v5, s52
	v_pk_add_f32 v[4:5], s[6:7], v[4:5]
	s_nop 0
	v_add_f32_e32 v4, v4, v5
	v_add_f32_e32 v4, 0x358637bd, v4
	v_mul_f32_e32 v5, 0x4b800000, v4
	v_cmp_gt_f32_e32 vcc, s68, v4
	s_nop 1
	v_cndmask_b32_e32 v4, v4, v5, vcc
	v_rsq_f32_e32 v8, v4
	v_pk_mul_f32 v[4:5], v[12:13], v[28:29]
	v_pk_mul_f32 v[28:29], v[10:11], v[28:29]
	v_add_f32_e32 v4, v14, v4
	v_add_f32_e32 v4, v4, v5
	v_mul_f32_e32 v5, 0xbfb8aa3b, v4
	v_exp_f32_e32 v5, v5
	v_mul_f32_e32 v6, 0x45800000, v8
	v_cndmask_b32_e32 v6, v8, v6, vcc
	v_mul_f32_e32 v0, v0, v6
	v_add_f32_e32 v5, 1.0, v5
	v_rcp_f32_e32 v5, v5
	v_cvt_pk_bf16_f32 v0, v0, s0
	ds_write_b16 v42, v0 offset:9792
	v_mul_f32_e32 v6, v4, v5
	v_mul_f32_e32 v4, v6, v6
	s_nop 1
	v_mov_b32_dpp v4, v4 quad_perm:[1,0,3,2] row_mask:0xf bank_mask:0xf bound_ctrl:1
	v_fmac_f32_e32 v4, v6, v6
	s_nop 1
	v_add_f32_dpp v4, v4, v4 quad_perm:[2,3,0,1] row_mask:0xf bank_mask:0xf bound_ctrl:1
	s_nop 1
	v_add_f32_dpp v4, v4, v4 row_half_mirror row_mask:0xf bank_mask:0xf bound_ctrl:1
	s_nop 1
	v_add_f32_dpp v4, v4, v4 row_mirror row_mask:0xf bank_mask:0xf bound_ctrl:1
	s_nop 0
	v_readlane_b32 s43, v4, 16
	v_readlane_b32 s52, v4, 48
	v_readlane_b32 s6, v4, 0
	v_readlane_b32 s7, v4, 32
	v_mov_b32_e32 v4, s43
	v_mov_b32_e32 v5, s52
	v_pk_add_f32 v[4:5], s[6:7], v[4:5]
	s_nop 0
	v_add_f32_e32 v4, v4, v5
	v_add_f32_e32 v8, 0x358637bd, v4
	v_pk_mul_f32 v[4:5], v[12:13], v[26:27]
	v_mul_f32_e32 v14, 0x4b800000, v8
	v_add_f32_e32 v4, v16, v4
	v_add_f32_e32 v4, v4, v5
	v_mul_f32_e32 v5, 0xbfb8aa3b, v4
	v_exp_f32_e32 v5, v5
	v_cmp_gt_f32_e32 vcc, s68, v8
	v_pk_mul_f32 v[26:27], v[10:11], v[26:27]
	v_add_f32_e32 v0, 1.0, v5
	v_rcp_f32_e32 v0, v0
	v_cndmask_b32_e32 v8, v8, v14, vcc
	v_rsq_f32_e32 v8, v8
	v_add_f32_e32 v14, v28, v29
	v_mul_f32_e32 v0, v4, v0
	v_mul_f32_e32 v4, v0, v0
	v_mul_f32_e32 v5, 0x45800000, v8
	v_cndmask_b32_e32 v5, v8, v5, vcc
	v_mov_b32_dpp v4, v4 quad_perm:[1,0,3,2] row_mask:0xf bank_mask:0xf bound_ctrl:1
	v_fmac_f32_e32 v4, v0, v0
	v_mul_f32_e32 v6, v6, v5
	v_cvt_pk_bf16_f32 v6, v6, s0
	v_add_f32_dpp v4, v4, v4 quad_perm:[2,3,0,1] row_mask:0xf bank_mask:0xf bound_ctrl:1
	ds_write_b16 v44, v6 offset:9216
	v_add_f32_e32 v16, v26, v27
	v_add_f32_dpp v4, v4, v4 row_half_mirror row_mask:0xf bank_mask:0xf bound_ctrl:1
	s_nop 1
	v_add_f32_dpp v4, v4, v4 row_mirror row_mask:0xf bank_mask:0xf bound_ctrl:1
	s_nop 0
	v_readlane_b32 s43, v4, 16
	v_readlane_b32 s52, v4, 48
	v_readlane_b32 s6, v4, 0
	v_readlane_b32 s7, v4, 32
	v_mov_b32_e32 v4, s43
	v_mov_b32_e32 v5, s52
	v_pk_add_f32 v[4:5], s[6:7], v[4:5]
	s_nop 0
	v_add_f32_e32 v4, v4, v5
	v_add_f32_e32 v4, 0x358637bd, v4
	v_mul_f32_e32 v5, 0x4b800000, v4
	v_cmp_gt_f32_e32 vcc, s68, v4
	s_nop 1
	v_cndmask_b32_e32 v4, v4, v5, vcc
	v_rsq_f32_e32 v8, v4
	v_pk_mul_f32 v[4:5], v[12:13], v[24:25]
	v_pk_mul_f32 v[24:25], v[10:11], v[24:25]
	v_add_f32_e32 v4, v14, v4
	v_add_f32_e32 v4, v4, v5
	v_mul_f32_e32 v5, 0xbfb8aa3b, v4
	v_exp_f32_e32 v5, v5
	v_mul_f32_e32 v6, 0x45800000, v8
	v_cndmask_b32_e32 v6, v8, v6, vcc
	v_mul_f32_e32 v0, v0, v6
	v_add_f32_e32 v5, 1.0, v5
	v_rcp_f32_e32 v5, v5
	v_cvt_pk_bf16_f32 v0, v0, s0
	ds_write_b16 v44, v0 offset:9360
	v_mul_f32_e32 v6, v4, v5
	v_mul_f32_e32 v4, v6, v6
	s_nop 1
	v_mov_b32_dpp v4, v4 quad_perm:[1,0,3,2] row_mask:0xf bank_mask:0xf bound_ctrl:1
	v_fmac_f32_e32 v4, v6, v6
	s_nop 1
	v_add_f32_dpp v4, v4, v4 quad_perm:[2,3,0,1] row_mask:0xf bank_mask:0xf bound_ctrl:1
	s_nop 1
	v_add_f32_dpp v4, v4, v4 row_half_mirror row_mask:0xf bank_mask:0xf bound_ctrl:1
	s_nop 1
	v_add_f32_dpp v4, v4, v4 row_mirror row_mask:0xf bank_mask:0xf bound_ctrl:1
	s_nop 0
	v_readlane_b32 s43, v4, 16
	v_readlane_b32 s52, v4, 48
	v_readlane_b32 s6, v4, 0
	v_readlane_b32 s7, v4, 32
	v_mov_b32_e32 v4, s43
	v_mov_b32_e32 v5, s52
	v_pk_add_f32 v[4:5], s[6:7], v[4:5]
	s_nop 0
	v_add_f32_e32 v4, v4, v5
	v_add_f32_e32 v8, 0x358637bd, v4
	v_pk_mul_f32 v[4:5], v[12:13], v[22:23]
	v_mul_f32_e32 v14, 0x4b800000, v8
	v_add_f32_e32 v4, v16, v4
	v_add_f32_e32 v4, v4, v5
	v_mul_f32_e32 v5, 0xbfb8aa3b, v4
	v_exp_f32_e32 v5, v5
	v_cmp_gt_f32_e32 vcc, s68, v8
	v_pk_mul_f32 v[22:23], v[10:11], v[22:23]
	v_add_f32_e32 v0, 1.0, v5
	v_rcp_f32_e32 v0, v0
	v_cndmask_b32_e32 v8, v8, v14, vcc
	v_rsq_f32_e32 v8, v8
	v_add_f32_e32 v14, v24, v25
	v_mul_f32_e32 v0, v4, v0
	v_mul_f32_e32 v4, v0, v0
	v_mul_f32_e32 v5, 0x45800000, v8
	v_cndmask_b32_e32 v5, v8, v5, vcc
	v_mov_b32_dpp v4, v4 quad_perm:[1,0,3,2] row_mask:0xf bank_mask:0xf bound_ctrl:1
	v_fmac_f32_e32 v4, v0, v0
	v_mul_f32_e32 v6, v6, v5
	v_cvt_pk_bf16_f32 v6, v6, s0
	v_add_f32_dpp v4, v4, v4 quad_perm:[2,3,0,1] row_mask:0xf bank_mask:0xf bound_ctrl:1
	ds_write_b16 v44, v6 offset:9504
	v_add_f32_e32 v16, v22, v23
	v_add_f32_dpp v4, v4, v4 row_half_mirror row_mask:0xf bank_mask:0xf bound_ctrl:1
	s_nop 1
	v_add_f32_dpp v4, v4, v4 row_mirror row_mask:0xf bank_mask:0xf bound_ctrl:1
	s_nop 0
	v_readlane_b32 s43, v4, 16
	v_readlane_b32 s52, v4, 48
	v_readlane_b32 s6, v4, 0
	v_readlane_b32 s7, v4, 32
	v_mov_b32_e32 v4, s43
	v_mov_b32_e32 v5, s52
	v_pk_add_f32 v[4:5], s[6:7], v[4:5]
	s_nop 0
	v_add_f32_e32 v4, v4, v5
	v_add_f32_e32 v4, 0x358637bd, v4
	v_mul_f32_e32 v5, 0x4b800000, v4
	v_cmp_gt_f32_e32 vcc, s68, v4
	s_nop 1
	v_cndmask_b32_e32 v4, v4, v5, vcc
	v_rsq_f32_e32 v8, v4
	v_pk_mul_f32 v[4:5], v[12:13], v[20:21]
	v_pk_mul_f32 v[20:21], v[10:11], v[20:21]
	v_add_f32_e32 v4, v14, v4
	v_add_f32_e32 v4, v4, v5
	v_mul_f32_e32 v5, 0xbfb8aa3b, v4
	v_exp_f32_e32 v5, v5
	v_mul_f32_e32 v6, 0x45800000, v8
	v_cndmask_b32_e32 v6, v8, v6, vcc
	v_mul_f32_e32 v0, v0, v6
	v_add_f32_e32 v5, 1.0, v5
	v_rcp_f32_e32 v5, v5
	v_cvt_pk_bf16_f32 v0, v0, s0
	ds_write_b16 v44, v0 offset:9648
	v_mul_f32_e32 v6, v4, v5
	v_mul_f32_e32 v4, v6, v6
	s_nop 1
	v_mov_b32_dpp v4, v4 quad_perm:[1,0,3,2] row_mask:0xf bank_mask:0xf bound_ctrl:1
	v_fmac_f32_e32 v4, v6, v6
	s_nop 1
	v_add_f32_dpp v4, v4, v4 quad_perm:[2,3,0,1] row_mask:0xf bank_mask:0xf bound_ctrl:1
	s_nop 1
	v_add_f32_dpp v4, v4, v4 row_half_mirror row_mask:0xf bank_mask:0xf bound_ctrl:1
	s_nop 1
	v_add_f32_dpp v4, v4, v4 row_mirror row_mask:0xf bank_mask:0xf bound_ctrl:1
	s_nop 0
	v_readlane_b32 s43, v4, 16
	v_readlane_b32 s52, v4, 48
	v_readlane_b32 s6, v4, 0
	v_readlane_b32 s7, v4, 32
	v_mov_b32_e32 v4, s43
	v_mov_b32_e32 v5, s52
	v_pk_add_f32 v[4:5], s[6:7], v[4:5]
	s_nop 0
	v_add_f32_e32 v4, v4, v5
	v_add_f32_e32 v8, 0x358637bd, v4
	v_pk_mul_f32 v[4:5], v[12:13], v[18:19]
	v_mul_f32_e32 v14, 0x4b800000, v8
	v_add_f32_e32 v4, v16, v4
	v_add_f32_e32 v4, v4, v5
	v_mul_f32_e32 v5, 0xbfb8aa3b, v4
	v_exp_f32_e32 v5, v5
	v_cmp_gt_f32_e32 vcc, s68, v8
	v_add_f32_e32 v16, v20, v21
	v_add_f32_e32 v0, 1.0, v5
	v_rcp_f32_e32 v0, v0
	v_cndmask_b32_e32 v8, v8, v14, vcc
	v_rsq_f32_e32 v8, v8
	v_mul_f32_e32 v0, v4, v0
	v_mul_f32_e32 v4, v0, v0
	v_mul_f32_e32 v5, 0x45800000, v8
	v_cndmask_b32_e32 v5, v8, v5, vcc
	v_mov_b32_dpp v4, v4 quad_perm:[1,0,3,2] row_mask:0xf bank_mask:0xf bound_ctrl:1
	v_fmac_f32_e32 v4, v0, v0
	v_mul_f32_e32 v6, v6, v5
	v_mov_b32_e32 v8, v19
	v_add_f32_dpp v4, v4, v4 quad_perm:[2,3,0,1] row_mask:0xf bank_mask:0xf bound_ctrl:1
	v_cvt_pk_bf16_f32 v6, v6, s0
	ds_write_b16 v44, v6 offset:9792
	v_add_f32_dpp v4, v4, v4 row_half_mirror row_mask:0xf bank_mask:0xf bound_ctrl:1
	v_pk_mul_f32 v[18:19], v[10:11], v[18:19]
	s_nop 0
	v_add_f32_dpp v4, v4, v4 row_mirror row_mask:0xf bank_mask:0xf bound_ctrl:1
	v_add_f32_e32 v18, v18, v19
	v_readlane_b32 s43, v4, 16
	v_readlane_b32 s52, v4, 48
	v_readlane_b32 s6, v4, 0
	v_readlane_b32 s7, v4, 32
	v_mov_b32_e32 v4, s43
	v_mov_b32_e32 v5, s52
	v_pk_add_f32 v[4:5], s[6:7], v[4:5]
	s_nop 0
	v_add_f32_e32 v4, v4, v5
	v_add_f32_e32 v4, 0x358637bd, v4
	v_mul_f32_e32 v5, 0x4b800000, v4
	v_cmp_gt_f32_e32 vcc, s68, v4
	s_nop 1
	v_cndmask_b32_e32 v4, v4, v5, vcc
	v_rsq_f32_e32 v14, v4
	v_pk_mul_f32 v[4:5], v[12:13], v[8:9]
	v_mul_f32_e32 v6, 0x45800000, v14
	v_add_f32_e32 v4, v16, v4
	v_add_f32_e32 v4, v4, v5
	v_mul_f32_e32 v5, 0xbfb8aa3b, v4
	v_exp_f32_e32 v5, v5
	v_cndmask_b32_e32 v6, v14, v6, vcc
	v_mul_f32_e32 v0, v0, v6
	v_mov_b32_e32 v6, v9
	v_add_f32_e32 v5, 1.0, v5
	v_rcp_f32_e32 v5, v5
	v_cvt_pk_bf16_f32 v0, v0, s0
	ds_write_b16 v44, v0 offset:9936
	v_pk_mul_f32 v[8:9], v[10:11], v[8:9]
	v_mul_f32_e32 v14, v4, v5
	v_mul_f32_e32 v4, v14, v14
	v_add_f32_e32 v8, v8, v9
	s_nop 0
	v_mov_b32_dpp v4, v4 quad_perm:[1,0,3,2] row_mask:0xf bank_mask:0xf bound_ctrl:1
	v_fmac_f32_e32 v4, v14, v14
	s_nop 1
	v_add_f32_dpp v4, v4, v4 quad_perm:[2,3,0,1] row_mask:0xf bank_mask:0xf bound_ctrl:1
	s_nop 1
	v_add_f32_dpp v4, v4, v4 row_half_mirror row_mask:0xf bank_mask:0xf bound_ctrl:1
	s_nop 1
	v_add_f32_dpp v4, v4, v4 row_mirror row_mask:0xf bank_mask:0xf bound_ctrl:1
	s_nop 0
	v_readlane_b32 s43, v4, 16
	v_readlane_b32 s52, v4, 48
	v_readlane_b32 s6, v4, 0
	v_readlane_b32 s7, v4, 32
	v_mov_b32_e32 v4, s43
	v_mov_b32_e32 v5, s52
	v_pk_add_f32 v[4:5], s[6:7], v[4:5]
	s_nop 0
	v_add_f32_e32 v4, v4, v5
	v_add_f32_e32 v16, 0x358637bd, v4
	v_pk_mul_f32 v[4:5], v[12:13], v[6:7]
	v_mul_f32_e32 v20, 0x4b800000, v16
	v_add_f32_e32 v4, v18, v4
	v_add_f32_e32 v4, v4, v5
	v_mul_f32_e32 v5, 0xbfb8aa3b, v4
	v_exp_f32_e32 v5, v5
	v_cmp_gt_f32_e32 vcc, s68, v16
	v_add_f32_e32 v0, 1.0, v5
	v_rcp_f32_e32 v0, v0
	v_cndmask_b32_e32 v16, v16, v20, vcc
	v_rsq_f32_e32 v16, v16
	v_mul_f32_e32 v0, v4, v0
	v_mul_f32_e32 v4, v0, v0
	v_mul_f32_e32 v5, 0x45800000, v16
	v_cndmask_b32_e32 v5, v16, v5, vcc
	v_mov_b32_dpp v4, v4 quad_perm:[1,0,3,2] row_mask:0xf bank_mask:0xf bound_ctrl:1
	v_fmac_f32_e32 v4, v0, v0
	v_mul_f32_e32 v14, v14, v5
	v_add_co_u32_e32 v20, vcc, 0x2000, v2
	v_add_f32_dpp v4, v4, v4 quad_perm:[2,3,0,1] row_mask:0xf bank_mask:0xf bound_ctrl:1
	s_nop 0
	v_addc_co_u32_e32 v21, vcc, 0, v3, vcc
	v_add_f32_dpp v4, v4, v4 row_half_mirror row_mask:0xf bank_mask:0xf bound_ctrl:1
	v_mov_b32_e32 v16, v7
	v_pk_mul_f32 v[18:19], v[12:13], v[16:17]
	v_add_f32_dpp v4, v4, v4 row_mirror row_mask:0xf bank_mask:0xf bound_ctrl:1
	v_add_f32_e32 v8, v8, v18
	v_readlane_b32 s43, v4, 16
	v_readlane_b32 s52, v4, 48
	v_readlane_b32 s6, v4, 0
	v_readlane_b32 s7, v4, 32
	v_mov_b32_e32 v4, s43
	v_mov_b32_e32 v5, s52
	v_pk_add_f32 v[4:5], s[6:7], v[4:5]
	v_add_f32_e32 v8, v8, v19
	v_add_f32_e32 v4, v4, v5
	v_add_f32_e32 v4, 0x358637bd, v4
	v_mul_f32_e32 v5, 0x4b800000, v4
	v_cmp_gt_f32_e64 s[6:7], s68, v4
	v_mul_f32_e32 v9, 0xbfb8aa3b, v8
	v_exp_f32_e32 v9, v9
	v_cndmask_b32_e64 v4, v4, v5, s[6:7]
	v_rsq_f32_e32 v22, v4
	v_lshl_add_u64 v[4:5], v[2:3], 0, s[64:65]
	global_load_dword v2, v[2:3], off offset:2048
	s_nop 0
	global_load_dword v5, v[4:5], off offset:3072
	s_nop 0
	global_load_dword v4, v[20:21], off
	global_load_dword v3, v[20:21], off offset:3072
	v_add_f32_e32 v9, 1.0, v9
	v_rcp_f32_e32 v9, v9
	v_cvt_pk_bf16_f32 v14, v14, s0
	ds_write_b16 v44, v14 offset:10080
	v_mul_f32_e32 v14, 0x45800000, v22
	v_mul_f32_e32 v16, v8, v9
	v_mul_f32_e32 v8, v16, v16
	v_cndmask_b32_e64 v14, v22, v14, s[6:7]
	v_mul_f32_e32 v0, v0, v14
	v_mov_b32_dpp v8, v8 quad_perm:[1,0,3,2] row_mask:0xf bank_mask:0xf bound_ctrl:1
	v_fmac_f32_e32 v8, v16, v16
	v_mov_b32_e32 v14, v17
	v_pk_mul_f32 v[6:7], v[10:11], v[6:7]
	v_add_f32_dpp v8, v8, v8 quad_perm:[2,3,0,1] row_mask:0xf bank_mask:0xf bound_ctrl:1
	v_add_f32_e32 v6, v6, v7
	v_cvt_pk_bf16_f32 v0, v0, s0
	v_add_f32_dpp v8, v8, v8 row_half_mirror row_mask:0xf bank_mask:0xf bound_ctrl:1
	ds_write_b16 v44, v0 offset:10224
	v_mov_b32_e32 v11, 0
	v_add_f32_dpp v8, v8, v8 row_mirror row_mask:0xf bank_mask:0xf bound_ctrl:1
	s_nop 0
	v_readlane_b32 s43, v8, 16
	v_readlane_b32 s52, v8, 48
	v_readlane_b32 s6, v8, 0
	v_readlane_b32 s7, v8, 32
	v_mov_b32_e32 v8, s43
	v_mov_b32_e32 v9, s52
	v_pk_add_f32 v[8:9], s[6:7], v[8:9]
	s_nop 0
	v_add_f32_e32 v8, v8, v9
	v_add_f32_e32 v18, 0x358637bd, v8
	v_pk_mul_f32 v[8:9], v[12:13], v[14:15]
	v_mul_f32_e32 v19, 0x4b800000, v18
	v_add_f32_e32 v6, v6, v8
	v_add_f32_e32 v6, v6, v9
	v_mul_f32_e32 v7, 0xbfb8aa3b, v6
	v_exp_f32_e32 v7, v7
	v_cmp_gt_f32_e32 vcc, s68, v18
	v_add_f32_e32 v7, 1.0, v7
	s_nop 0
	v_cndmask_b32_e32 v8, v18, v19, vcc
	v_rsq_f32_e32 v8, v8
	v_rcp_f32_e32 v7, v7
	v_mul_f32_e32 v0, 0x45800000, v8
	v_cndmask_b32_e32 v0, v8, v0, vcc
	v_mul_f32_e32 v8, v6, v7
	v_mul_f32_e32 v6, v8, v8
	v_mul_f32_e32 v0, v16, v0
	v_cvt_pk_bf16_f32 v0, v0, s0
	v_mov_b32_dpp v6, v6 quad_perm:[1,0,3,2] row_mask:0xf bank_mask:0xf bound_ctrl:1
	v_fmac_f32_e32 v6, v8, v8
	ds_write_b16 v44, v0 offset:10368
	s_nop 0
	v_add_f32_dpp v6, v6, v6 quad_perm:[2,3,0,1] row_mask:0xf bank_mask:0xf bound_ctrl:1
	s_nop 1
	v_add_f32_dpp v6, v6, v6 row_half_mirror row_mask:0xf bank_mask:0xf bound_ctrl:1
	s_nop 1
	v_add_f32_dpp v6, v6, v6 row_mirror row_mask:0xf bank_mask:0xf bound_ctrl:1
	s_nop 0
	v_readlane_b32 s43, v6, 16
	v_readlane_b32 s52, v6, 48
	v_readlane_b32 s6, v6, 0
	v_readlane_b32 s7, v6, 32
	v_mov_b32_e32 v6, s43
	v_mov_b32_e32 v7, s52
	v_pk_add_f32 v[6:7], s[6:7], v[6:7]
	s_nop 0
	v_add_f32_e32 v6, v6, v7
	v_add_f32_e32 v6, 0x358637bd, v6
	v_mul_f32_e32 v7, 0x4b800000, v6
	v_cmp_gt_f32_e32 vcc, s68, v6
	s_nop 1
	v_cndmask_b32_e32 v6, v6, v7, vcc
	v_rsq_f32_e32 v6, v6
	s_nop 0
	v_mul_f32_e32 v0, 0x45800000, v6
	v_cndmask_b32_e32 v0, v6, v0, vcc
	v_mul_f32_e32 v0, v8, v0
	v_cvt_pk_bf16_f32 v0, v0, s0
	ds_write_b16 v44, v0 offset:10512
	v_or_b32_e32 v0, 0x200, v50
	v_mov_b32_e32 v6, 0
	v_lshlrev_b32_e32 v0, 1, v0
	s_and_saveexec_b64 s[6:7], s[10:11]
	s_cbranch_execz .LBB0_647
	v_mov_b64_e32 v[8:9], s[8:9]
	v_mad_i64_i32 v[8:9], s[10:11], v51, s33, v[8:9]
	v_lshl_add_u64 v[8:9], v[8:9], 0, v[0:1]
	global_load_ushort v11, v[8:9], off offset:2048

.LBB0_649:
	s_or_b64 exec, exec, s[6:7]
	v_mov_b32_e32 v7, 0
	v_mov_b32_e32 v13, 0
	s_and_saveexec_b64 s[6:7], s[20:21]
	s_cbranch_execz .LBB0_651
	v_mov_b64_e32 v[8:9], s[8:9]
	v_mad_i64_i32 v[8:9], s[10:11], v53, s33, v[8:9]
	v_lshl_add_u64 v[8:9], v[8:9], 0, v[0:1]
	global_load_ushort v13, v[8:9], off offset:2048

.LBB0_653:
	s_or_b64 exec, exec, s[6:7]
	v_mov_b32_e32 v8, 0
	v_mov_b32_e32 v15, 0
	s_and_saveexec_b64 s[6:7], s[24:25]
	s_cbranch_execz .LBB0_655
	v_mov_b64_e32 v[14:15], s[8:9]
	v_mad_i64_i32 v[14:15], s[10:11], v55, s33, v[14:15]
	v_lshl_add_u64 v[14:15], v[14:15], 0, v[0:1]
	global_load_ushort v15, v[14:15], off offset:2048

.LBB0_657:
	s_or_b64 exec, exec, s[6:7]
	v_mov_b32_e32 v9, 0
	v_mov_b32_e32 v17, 0
	s_and_saveexec_b64 s[6:7], s[28:29]
	s_cbranch_execz .LBB0_659
	v_mov_b64_e32 v[16:17], s[8:9]
	v_mad_i64_i32 v[16:17], s[10:11], v57, s33, v[16:17]
	v_lshl_add_u64 v[16:17], v[16:17], 0, v[0:1]
	global_load_ushort v17, v[16:17], off offset:2048

.LBB0_661:
	s_or_b64 exec, exec, s[6:7]
	v_mov_b32_e32 v10, 0
	v_mov_b32_e32 v18, 0
	s_and_saveexec_b64 s[6:7], s[34:35]
	s_cbranch_execz .LBB0_663
	v_mov_b64_e32 v[18:19], s[8:9]
	v_mad_i64_i32 v[18:19], s[10:11], v59, s33, v[18:19]
	v_lshl_add_u64 v[18:19], v[18:19], 0, v[0:1]
	global_load_ushort v18, v[18:19], off offset:2048

.LBB0_665:
	s_or_b64 exec, exec, s[6:7]
	v_mov_b32_e32 v12, 0
	v_mov_b32_e32 v19, 0
	s_and_saveexec_b64 s[6:7], s[38:39]
	s_cbranch_execz .LBB0_667
	v_mov_b64_e32 v[20:21], s[8:9]
	v_mad_i64_i32 v[20:21], s[10:11], v61, s33, v[20:21]
	v_lshl_add_u64 v[20:21], v[20:21], 0, v[0:1]
	global_load_ushort v19, v[20:21], off offset:2048

.LBB0_669:
	s_or_b64 exec, exec, s[6:7]
	v_mov_b32_e32 v14, 0
	v_mov_b32_e32 v20, 0
	s_and_saveexec_b64 s[6:7], s[48:49]
	s_cbranch_execz .LBB0_671
	v_mov_b64_e32 v[20:21], s[8:9]
	v_mad_i64_i32 v[20:21], s[10:11], v63, s33, v[20:21]
	v_lshl_add_u64 v[20:21], v[20:21], 0, v[0:1]
	global_load_ushort v20, v[20:21], off offset:2048
.LBB0_671:
	s_or_b64 exec, exec, s[6:7]
	s_and_saveexec_b64 s[6:7], s[50:51]
	s_cbranch_execz .LBB0_673
	v_mov_b64_e32 v[22:23], s[8:9]
	v_mad_i64_i32 v[22:23], s[10:11], v64, s33, v[22:23]
	v_lshl_add_u64 v[22:23], v[22:23], 0, v[0:1]
	global_load_ushort v14, v[22:23], off offset:2048
.LBB0_673:
	s_or_b64 exec, exec, s[6:7]
	v_mov_b32_e32 v16, 0
	v_mov_b32_e32 v21, 0
	s_and_saveexec_b64 s[6:7], s[56:57]
	s_cbranch_execz .LBB0_675
	v_mov_b64_e32 v[22:23], s[8:9]
	v_mad_i64_i32 v[22:23], s[10:11], v65, s33, v[22:23]
	v_lshl_add_u64 v[22:23], v[22:23], 0, v[0:1]
	global_load_ushort v21, v[22:23], off offset:2048
.LBB0_675:
	s_or_b64 exec, exec, s[6:7]
	s_and_saveexec_b64 s[6:7], s[58:59]
	s_cbranch_execz .LBB0_677
	v_mov_b64_e32 v[22:23], s[8:9]
	v_mad_i64_i32 v[22:23], s[10:11], v66, s33, v[22:23]
	v_lshl_add_u64 v[22:23], v[22:23], 0, v[0:1]
	global_load_ushort v16, v[22:23], off offset:2048
.LBB0_677:
	s_or_b64 exec, exec, s[6:7]
	v_mov_b32_e32 v22, 0
	v_mov_b32_e32 v23, 0
	s_and_saveexec_b64 s[6:7], s[60:61]
	s_cbranch_execnz .LBB0_759
	s_or_b64 exec, exec, s[6:7]
	s_and_saveexec_b64 s[6:7], s[70:71]
	s_cbranch_execnz .LBB0_760

.LBB0_680:
	v_mov_b64_e32 v[24:25], s[8:9]
	v_mad_i64_i32 v[24:25], s[10:11], v69, s33, v[24:25]
	v_lshl_add_u64 v[24:25], v[24:25], 0, v[0:1]
	global_load_ushort v24, v[24:25], off offset:2048
.LBB0_681:
	s_or_b64 exec, exec, s[6:7]
	s_waitcnt vmcnt(0)
	v_lshlrev_b32_e32 v11, 16, v11
	v_lshlrev_b32_e32 v6, 16, v6
	v_lshlrev_b32_e32 v13, 16, v13
	v_lshlrev_b32_e32 v7, 16, v7
	v_lshlrev_b32_e32 v15, 16, v15
	v_lshlrev_b32_e32 v8, 16, v8
	v_lshlrev_b32_e32 v17, 16, v17
	v_lshlrev_b32_e32 v9, 16, v9
	v_lshlrev_b32_e32 v18, 16, v18
	v_lshlrev_b32_e32 v10, 16, v10
	v_lshlrev_b32_e32 v19, 16, v19
	v_lshlrev_b32_e32 v12, 16, v12
	v_lshlrev_b32_e32 v20, 16, v20
	v_lshlrev_b32_e32 v14, 16, v14
	v_lshlrev_b32_e32 v21, 16, v21
	v_lshlrev_b32_e32 v16, 16, v16
	v_lshlrev_b32_e32 v24, 16, v24
	v_lshlrev_b32_e32 v23, 16, v23
	v_lshlrev_b32_e32 v22, 16, v22
	s_waitcnt vmcnt(2)
	v_mul_f32_e32 v0, v5, v6
	v_fmac_f32_e32 v0, v2, v11
	s_waitcnt vmcnt(1)
	v_fmac_f32_e32 v0, v4, v13
	v_mul_f32_e32 v25, v5, v13
	s_waitcnt vmcnt(0)
	v_fmac_f32_e32 v0, v3, v7
	v_fmac_f32_e32 v25, v2, v6
	v_mul_f32_e32 v11, 0xbfb8aa3b, v0
	v_fmac_f32_e32 v25, v4, v7
	v_exp_f32_e32 v11, v11
	v_fmac_f32_e32 v25, v3, v15
	v_mul_f32_e32 v6, 0xbfb8aa3b, v25
	v_exp_f32_e32 v6, v6
	v_add_f32_e32 v11, 1.0, v11
	v_rcp_f32_e32 v11, v11
	s_movk_i32 s6, 0x7f
	v_add_f32_e32 v6, 1.0, v6
	v_rcp_f32_e32 v6, v6
	v_mul_f32_e32 v0, v0, v11
	v_cvt_pk_bf16_f32 v0, v0, s0
	ds_write_b16 v43, v0 offset:18432
	v_mul_f32_e32 v0, v25, v6
	v_mul_f32_e32 v6, v5, v7
	v_fmac_f32_e32 v6, v2, v13
	v_fmac_f32_e32 v6, v4, v15
	v_fmac_f32_e32 v6, v3, v8
	v_mul_f32_e32 v11, 0xbfb8aa3b, v6
	v_exp_f32_e32 v11, v11
	v_mul_f32_e32 v13, v5, v15
	v_fmac_f32_e32 v13, v2, v7
	v_fmac_f32_e32 v13, v4, v8
	v_add_f32_e32 v11, 1.0, v11
	v_rcp_f32_e32 v11, v11
	v_fmac_f32_e32 v13, v3, v17
	v_mul_f32_e32 v7, 0xbfb8aa3b, v13
	v_exp_f32_e32 v7, v7
	v_mul_f32_e32 v6, v6, v11
	v_cvt_pk_bf16_f32 v6, v6, s0
	ds_write_b16 v42, v6 offset:18576
	v_mul_f32_e32 v6, v5, v8
	v_fmac_f32_e32 v6, v2, v15
	v_fmac_f32_e32 v6, v4, v17
	v_cvt_pk_bf16_f32 v0, v0, s0
	v_fmac_f32_e32 v6, v3, v9
	ds_write_b16 v42, v0 offset:18432
	v_add_f32_e32 v0, 1.0, v7
	v_mul_f32_e32 v7, 0xbfb8aa3b, v6
	v_exp_f32_e32 v7, v7
	v_mul_f32_e32 v11, v5, v17
	v_fmac_f32_e32 v11, v2, v8
	v_fmac_f32_e32 v11, v4, v9
	v_add_f32_e32 v7, 1.0, v7
	v_rcp_f32_e32 v7, v7
	v_rcp_f32_e32 v0, v0
	v_fmac_f32_e32 v11, v3, v18
	v_mul_f32_e32 v8, 0xbfb8aa3b, v11
	v_mul_f32_e32 v6, v6, v7
	v_cvt_pk_bf16_f32 v6, v6, s0
	ds_write_b16 v42, v6 offset:18864
	v_mul_f32_e32 v6, v5, v9
	v_fmac_f32_e32 v6, v2, v17
	v_fmac_f32_e32 v6, v4, v18
	v_fmac_f32_e32 v6, v3, v10
	v_mul_f32_e32 v7, 0xbfb8aa3b, v6
	v_exp_f32_e32 v8, v8
	v_exp_f32_e32 v7, v7
	v_mul_f32_e32 v0, v13, v0
	v_cvt_pk_bf16_f32 v0, v0, s0
	ds_write_b16 v42, v0 offset:18720
	v_add_f32_e32 v0, 1.0, v8
	v_add_f32_e32 v7, 1.0, v7
	v_rcp_f32_e32 v0, v0
	v_rcp_f32_e32 v7, v7
	v_mul_f32_e32 v8, v5, v18
	v_fmac_f32_e32 v8, v2, v9
	v_mul_f32_e32 v0, v11, v0
	v_mul_f32_e32 v6, v6, v7
	v_cvt_pk_bf16_f32 v0, v0, s0
	v_cvt_pk_bf16_f32 v6, v6, s0
	ds_write_b16 v42, v0 offset:19008
	ds_write_b16 v44, v6 offset:18432
	v_mul_f32_e32 v6, v5, v10
	v_fmac_f32_e32 v8, v4, v10
	v_fmac_f32_e32 v6, v2, v18
	v_fmac_f32_e32 v8, v3, v19
	v_fmac_f32_e32 v6, v4, v19
	v_mul_f32_e32 v9, 0xbfb8aa3b, v8
	v_fmac_f32_e32 v6, v3, v12
	v_exp_f32_e32 v9, v9
	v_mul_f32_e32 v7, 0xbfb8aa3b, v6
	v_exp_f32_e32 v7, v7
	s_lshl_b32 s18, s16, 1
	v_add_f32_e32 v0, 1.0, v9
	v_rcp_f32_e32 v0, v0
	v_add_f32_e32 v7, 1.0, v7
	v_rcp_f32_e32 v7, v7
	v_cmp_lt_i32_e64 s[6:7], s6, v47
	v_mul_f32_e32 v0, v8, v0
	v_mul_f32_e32 v8, v5, v19
	v_fmac_f32_e32 v8, v2, v10
	v_mul_f32_e32 v6, v6, v7
	v_fmac_f32_e32 v8, v4, v12
	v_cvt_pk_bf16_f32 v6, v6, s0
	v_fmac_f32_e32 v8, v3, v20
	ds_write_b16 v44, v6 offset:18720
	v_mul_f32_e32 v6, v5, v12
	v_mul_f32_e32 v9, 0xbfb8aa3b, v8
	v_fmac_f32_e32 v6, v2, v19
	v_exp_f32_e32 v9, v9
	v_fmac_f32_e32 v6, v4, v20
	v_fmac_f32_e32 v6, v3, v14
	v_mul_f32_e32 v7, 0xbfb8aa3b, v6
	v_cvt_pk_bf16_f32 v0, v0, s0
	v_exp_f32_e32 v7, v7
	ds_write_b16 v44, v0 offset:18576
	v_add_f32_e32 v0, 1.0, v9
	v_rcp_f32_e32 v0, v0
	v_add_f32_e32 v7, 1.0, v7
	v_rcp_f32_e32 v7, v7
	v_cmp_gt_i32_e32 vcc, s67, v47
	v_mul_f32_e32 v0, v8, v0
	v_mul_f32_e32 v8, v5, v20
	v_fmac_f32_e32 v8, v2, v12
	v_fmac_f32_e32 v8, v4, v14
	v_fmac_f32_e32 v8, v3, v21
	v_mul_f32_e32 v6, v6, v7
	v_mul_f32_e32 v9, 0xbfb8aa3b, v8
	v_cvt_pk_bf16_f32 v6, v6, s0
	v_exp_f32_e32 v9, v9
	ds_write_b16 v44, v6 offset:19008
	v_mul_f32_e32 v6, v5, v14
	v_fmac_f32_e32 v6, v2, v20
	v_fmac_f32_e32 v6, v4, v21
	v_cvt_pk_bf16_f32 v0, v0, s0
	v_fmac_f32_e32 v6, v3, v16
	ds_write_b16 v44, v0 offset:18864
	v_add_f32_e32 v0, 1.0, v9
	v_mul_f32_e32 v7, 0xbfb8aa3b, v6
	v_rcp_f32_e32 v0, v0
	v_exp_f32_e32 v7, v7
	v_mul_f32_e32 v0, v8, v0
	v_mul_f32_e32 v8, v5, v21
	v_add_f32_e32 v7, 1.0, v7
	v_fmac_f32_e32 v8, v2, v14
	v_rcp_f32_e32 v7, v7
	v_fmac_f32_e32 v8, v4, v16
	v_fmac_f32_e32 v8, v3, v23
	v_mul_f32_e32 v9, 0xbfb8aa3b, v8
	v_exp_f32_e32 v9, v9
	v_mul_f32_e32 v6, v6, v7
	v_cvt_pk_bf16_f32 v6, v6, s0
	ds_write_b16 v44, v6 offset:19296
	v_mul_f32_e32 v6, v5, v16
	v_mul_f32_e32 v5, v5, v23
	v_cvt_pk_bf16_f32 v0, v0, s0
	v_fmac_f32_e32 v6, v2, v21
	v_fmac_f32_e32 v5, v2, v16
	ds_write_b16 v44, v0 offset:19152
	v_add_f32_e32 v0, 1.0, v9
	v_fmac_f32_e32 v6, v4, v23
	v_fmac_f32_e32 v5, v4, v22
	v_rcp_f32_e32 v0, v0
	v_fmac_f32_e32 v6, v3, v22
	v_fmac_f32_e32 v5, v3, v24
	v_mul_f32_e32 v7, 0xbfb8aa3b, v6
	v_mul_f32_e32 v2, 0xbfb8aa3b, v5
	v_exp_f32_e32 v7, v7
	v_exp_f32_e32 v2, v2
	v_mul_f32_e32 v0, v8, v0
	v_cvt_pk_bf16_f32 v0, v0, s0
	v_add_f32_e32 v3, 1.0, v7
	ds_write_b16 v44, v0 offset:19440
	v_add_f32_e32 v0, 1.0, v2
	v_rcp_f32_e32 v3, v3
	v_rcp_f32_e32 v0, v0
	v_mul_f32_e32 v2, v6, v3
	v_mul_f32_e32 v0, v5, v0
	v_cvt_pk_bf16_f32 v2, v2, s0
	v_cvt_pk_bf16_f32 v0, v0, s0
	ds_write_b16 v44, v2 offset:19584
	ds_write_b16 v44, v0 offset:19728
	s_and_saveexec_b64 s[10:11], vcc
	s_cbranch_execz .LBB0_684
	v_xor_b32_e32 v0, 63, v46
	v_cmp_gt_u32_e32 vcc, 64, v47
	v_mov_b64_e32 v[2:3], s[8:9]
	s_load_dwordx4 s[20:23], s[0:1], 0xd0
	v_cndmask_b32_e32 v0, v0, v46, vcc
	v_or_b32_e32 v0, s53, v0
	v_mad_i64_i32 v[2:3], s[8:9], v0, s33, v[2:3]
	v_lshlrev_b32_e32 v0, 2, v49
	v_or_b32_e32 v8, s3, v0
	v_add_u32_e32 v4, 0xa00, v8
	v_ashrrev_i32_e32 v5, 31, v4
	s_or_b32 s19, s63, s3
	v_lshl_add_u64 v[4:5], v[4:5], 1, v[2:3]
	global_load_ushort v9, v[4:5], off
	v_add_u32_e32 v4, s19, v0
	v_ashrrev_i32_e32 v5, 31, v4
	v_lshlrev_b64 v[4:5], 2, v[4:5]
	s_waitcnt lgkmcnt(0)
	v_lshl_add_u64 v[6:7], s[22:23], 0, v[4:5]
	global_load_dword v0, v[6:7], off
	v_lshl_add_u64 v[4:5], s[20:21], 0, v[4:5]
	global_load_dword v6, v[4:5], off
	v_add_u32_e32 v4, 0xa08, v8
	v_ashrrev_i32_e32 v5, 31, v4
	v_lshl_add_u64 v[2:3], v[4:5], 1, v[2:3]
	global_load_ushort v3, v[2:3], off
	v_and_b32_e32 v4, 64, v190
	v_add_u32_e32 v2, -1, v190
	v_cmp_lt_i32_e32 vcc, v2, v4
	s_mov_b32 s3, 0x41a00000
	v_add_u32_e32 v5, -2, v190
	v_cndmask_b32_e32 v2, v2, v190, vcc
	v_lshlrev_b32_e32 v2, 2, v2
	v_add_u32_e32 v7, -4, v190
	v_cmp_lt_i32_e64 s[8:9], v7, v4
	v_add_u32_e32 v8, -8, v190
	v_add_u32_e32 v10, -16, v190
	v_subrev_u32_e32 v11, 32, v190
	s_mov_b64 s[20:21], 0x327800
	s_waitcnt vmcnt(3)
	v_lshlrev_b32_e32 v9, 16, v9
	s_waitcnt vmcnt(2)
	v_add_f32_e32 v0, v0, v9
	v_mul_f32_e32 v9, 0x3fb8aa3b, v0
	v_exp_f32_e32 v9, v9
	s_waitcnt vmcnt(1)
	v_mul_f32_e32 v6, 0x3fb8aa3b, v6
	v_exp_f32_e32 v6, v6
	v_add_f32_e32 v9, 1.0, v9
	v_cmp_gt_f32_e32 vcc, s68, v9
	s_waitcnt vmcnt(0)
	v_lshlrev_b32_e32 v3, 16, v3
	v_mul_f32_e32 v3, 0xbfb8aa3b, v3
	v_cndmask_b32_e64 v12, 0, 32, vcc
	v_ldexp_f32 v9, v9, v12
	v_log_f32_e32 v9, v9
	v_cndmask_b32_e32 v12, 0, v187, vcc
	v_mul_f32_e32 v13, 0x3f317217, v9
	v_fma_f32 v13, v9, s55, -v13
	v_fmac_f32_e32 v13, 0x3377d1cf, v9
	v_fmac_f32_e32 v13, 0x3f317217, v9
	v_cmp_lt_f32_e64 vcc, |v9|, s78
	s_nop 1
	v_cndmask_b32_e32 v9, v9, v13, vcc
	v_sub_f32_e32 v9, v9, v12
	v_cmp_lt_f32_e32 vcc, s3, v0
	v_lshl_add_u32 v12, v47, 2, 0
	s_nop 0
	v_cndmask_b32_e32 v0, v9, v0, vcc
	v_mul_f32_e64 v9, v0, -v6
	ds_bpermute_b32 v2, v2, v9
	v_cmp_lt_i32_e32 vcc, v5, v4
	s_waitcnt lgkmcnt(0)
	v_fma_f32 v0, v0, -v6, v2
	v_cndmask_b32_e32 v5, v5, v190, vcc
	v_cmp_eq_u32_e32 vcc, 0, v46
	v_lshlrev_b32_e32 v5, 2, v5
	v_cndmask_b32_e64 v6, v7, v190, s[8:9]
	v_cndmask_b32_e32 v0, v0, v9, vcc
	ds_bpermute_b32 v5, v5, v0
	v_cmp_gt_u32_e64 s[8:9], 2, v46
	v_lshlrev_b32_e32 v6, 2, v6
	v_add_u32_e32 v2, s18, v49
	s_waitcnt lgkmcnt(0)
	v_add_f32_e32 v5, v0, v5
	v_cndmask_b32_e64 v0, v5, v0, s[8:9]
	ds_bpermute_b32 v5, v6, v0
	v_cmp_lt_i32_e64 s[8:9], v8, v4
	s_waitcnt lgkmcnt(0)
	v_add_f32_e32 v5, v0, v5
	v_cndmask_b32_e64 v6, v8, v190, s[8:9]
	v_cmp_gt_u32_e64 s[8:9], 4, v46
	v_lshlrev_b32_e32 v6, 2, v6
	s_nop 0
	v_cndmask_b32_e64 v0, v5, v0, s[8:9]
	ds_bpermute_b32 v5, v6, v0
	v_cmp_lt_i32_e64 s[8:9], v10, v4
	s_waitcnt lgkmcnt(0)
	v_add_f32_e32 v5, v0, v5
	v_cndmask_b32_e64 v6, v10, v190, s[8:9]
	v_cmp_lt_i32_e64 s[8:9], v11, v4
	v_lshlrev_b32_e32 v6, 2, v6
	s_nop 0
	v_cndmask_b32_e64 v4, v11, v190, s[8:9]
	v_cmp_gt_u32_e64 s[8:9], 8, v46
	v_lshlrev_b32_e32 v4, 2, v4
	s_nop 0
	v_cndmask_b32_e64 v0, v5, v0, s[8:9]
	ds_bpermute_b32 v5, v6, v0
	v_exp_f32_e32 v6, v3
	v_cmp_gt_u32_e64 s[8:9], 16, v46
	s_waitcnt lgkmcnt(0)
	v_add_f32_e32 v3, v0, v5
	v_cndmask_b32_e64 v0, v3, v0, s[8:9]
	ds_bpermute_b32 v4, v4, v0
	v_cmp_gt_u32_e64 s[8:9], 32, v46
	v_add_f32_e32 v5, 1.0, v6
	v_rcp_f32_e32 v5, v5
	v_ashrrev_i32_e32 v3, 31, v2
	s_waitcnt lgkmcnt(0)
	v_add_f32_e32 v4, v0, v4
	v_cndmask_b32_e64 v0, v4, v0, s[8:9]
	ds_bpermute_b32 v4, v191, v0
	v_mul_f32_e32 v6, 0x3fb8aa3b, v0
	v_exp_f32_e32 v8, v6
	ds_write2st64_b32 v12, v0, v5 offset0:236 offset1:238
	ds_write_b32 v12, v8 offset:61440
	s_waitcnt lgkmcnt(2)
	v_sub_f32_e32 v0, v4, v0
	v_lshlrev_b64 v[2:3], 10, v[2:3]
	v_mul_f32_e32 v0, 0x3fb8aa3b, v0
	v_lshl_add_u64 v[2:3], s[4:5], 0, v[2:3]
	v_exp_f32_e32 v5, v0
	v_lshl_add_u64 v[2:3], v[2:3], 0, s[20:21]
	v_lshlrev_b32_e32 v0, 2, v46
	v_lshl_add_u64 v[6:7], v[2:3], 0, v[0:1]
	global_store_dword v[6:7], v8, off
	global_store_dword v[6:7], v5, off offset:256
	s_and_b64 exec, exec, vcc
	s_cbranch_execz .LBB0_684
	v_mul_f32_e32 v0, 0x3fb8aa3b, v4
	v_exp_f32_e32 v0, v0
	global_store_dword v[2:3], v0, off offset:512

.LBB0_759:
	v_mov_b64_e32 v[24:25], s[8:9]
	v_mad_i64_i32 v[24:25], s[10:11], v67, s33, v[24:25]
	v_lshl_add_u64 v[24:25], v[24:25], 0, v[0:1]
	global_load_ushort v23, v[24:25], off offset:2048
	s_or_b64 exec, exec, s[6:7]
	s_and_saveexec_b64 s[6:7], s[70:71]
	s_cbranch_execz .LBB0_679
.LBB0_760:
	v_mov_b64_e32 v[24:25], s[8:9]
	v_mad_i64_i32 v[24:25], s[10:11], v68, s33, v[24:25]
	v_lshl_add_u64 v[24:25], v[24:25], 0, v[0:1]
	global_load_ushort v22, v[24:25], off offset:2048
	s_or_b64 exec, exec, s[6:7]
	v_mov_b32_e32 v24, 0
	s_and_saveexec_b64 s[6:7], s[84:85]
	s_cbranch_execnz .LBB0_680
	s_branch .LBB0_681
